# sample-group attention items (sdil, smem layer0) hand-rewritten: 32 K/V row loads in flight as constant-vmcnt stream, DPP reductions; plus rmsnorm phases
# speedup vs baseline: 1.0436x; 1.0187x over previous
.LBB0_682:
	s_add_i32 s2, s33, 0x500
	s_and_b32 s4, s2, 0x7ff
	s_and_b64 s[2:3], s[86:87], exec
	s_cselect_b32 s56, s4, s33
	s_cmpk_gt_i32 s56, 0x2ff
	s_mov_b64 s[2:3], -1
	s_cbranch_scc0 .LBB0_734
	s_cmpk_gt_u32 s56, 0x4ff
	s_cbranch_scc0 .LBB0_731
	s_cmpk_gt_u32 s56, 0x57f
	s_cbranch_scc0 .LBB0_726
	s_cmpk_gt_u32 s56, 0x67f
	s_cbranch_scc0 .LBB0_709
	s_cmpk_lt_u32 s56, 0x780
	s_cbranch_scc1 .LBB0_696
	v_and_b32_e32 v18, 63, v208
	v_lshrrev_b32_e32 v19, 6, v208
	v_and_b32_e32 v20, 3, v19
	v_lshrrev_b32_e32 v21, 2, v19
	v_and_b32_e32 v22, 15, v18
	v_lshrrev_b32_e32 v23, 4, v18
	v_lshlrev_b32_e32 v176, 2, v18
	v_xor_b32_e32 v238, 64, v176
	v_xor_b32_e32 v239, 0x80, v176
	s_and_b32 s2, s56, 0x7c
	s_and_b32 s94, s56, 3
	v_readfirstlane_b32 s6, v21
	v_add_u32_e32 v230, s2, v20
	v_or_b32_e32 v230, 0x2000, v230
	v_mul_u32_u24_e32 v231, 0x5800, v230
	s_lshl_b32 s3, s94, 8
	v_lshl_add_u32 v232, v22, 4, v231
	v_add_u32_e32 v232, s3, v232
	v_add_u32_e32 v232, 0x5000, v232
	global_load_dwordx4 v[160:163], v232, s[0:1]
	v_add_u32_e32 v232, 0x400, v232
	v_mov_b32_e32 v233, 0
	v_lshl_add_u64 v[244:245], s[0:1], 0, v[232:233]
	v_mul_u32_u24_e32 v231, 0x1c00, v230
	v_lshl_add_u32 v232, v22, 4, v231
	v_add_u32_e32 v232, s3, v232
	v_add_u32_e32 v232, 0x1d301800, v232
	v_lshl_add_u64 v[246:247], s[96:97], 0, v[232:233]
	s_lshl_b32 s7, s2, 17
	s_lshl_b32 s8, s94, 9
	s_lshl_b32 s6, s6, 18
	s_add_u32 s7, s7, s8
	s_add_u32 s7, s7, s6
	s_add_u32 s2, s70, s7
	s_addc_u32 s3, s71, 0
	s_add_u32 s4, s72, s7
	s_addc_u32 s5, s73, 0
	v_lshlrev_b32_e32 v24, 15, v23
	v_lshl_add_u32 v24, v22, 5, v24
	v_add_u32_e32 v25, 0x1000, v24
	v_add_u32_e32 v26, 0x2000, v24
	v_add_u32_e32 v27, 0x3000, v24
	v_add_u32_e32 v28, 0x4000, v24
	v_add_u32_e32 v29, 0x5000, v24
	v_add_u32_e32 v30, 0x6000, v24
	v_add_u32_e32 v31, 0x7000, v24
	v_mov_b32_e32 v16, v206
	v_mov_b32_e32 v17, 0
	v_mov_b32_e32 v8, 0
	v_mov_b32_e32 v9, 0
	v_mov_b32_e32 v10, 0
	v_mov_b32_e32 v11, 0
	v_mov_b32_e32 v12, 0
	v_mov_b32_e32 v13, 0
	v_mov_b32_e32 v14, 0
	v_mov_b32_e32 v15, 0
	global_load_dwordx4 v[32:35], v24, s[2:3]
	global_load_dwordx4 v[36:39], v24, s[2:3] offset:16
	global_load_dwordx4 v[40:43], v24, s[2:3] offset:2048
	global_load_dwordx4 v[44:47], v24, s[2:3] offset:2064
	global_load_dwordx4 v[48:51], v25, s[2:3]
	global_load_dwordx4 v[52:55], v25, s[2:3] offset:16
	global_load_dwordx4 v[56:59], v25, s[2:3] offset:2048
	global_load_dwordx4 v[60:63], v25, s[2:3] offset:2064
	global_load_dwordx4 v[64:67], v26, s[2:3]
	global_load_dwordx4 v[68:71], v26, s[2:3] offset:16
	global_load_dwordx4 v[72:75], v26, s[2:3] offset:2048
	global_load_dwordx4 v[76:79], v26, s[2:3] offset:2064
	global_load_dwordx4 v[80:83], v27, s[2:3]
	global_load_dwordx4 v[84:87], v27, s[2:3] offset:16
	global_load_dwordx4 v[88:91], v27, s[2:3] offset:2048
	global_load_dwordx4 v[92:95], v27, s[2:3] offset:2064
	global_load_dwordx4 v[96:99], v28, s[2:3]
	global_load_dwordx4 v[100:103], v28, s[2:3] offset:16
	global_load_dwordx4 v[104:107], v28, s[2:3] offset:2048
	global_load_dwordx4 v[108:111], v28, s[2:3] offset:2064
	global_load_dwordx4 v[112:115], v29, s[2:3]
	global_load_dwordx4 v[116:119], v29, s[2:3] offset:16
	global_load_dwordx4 v[120:123], v29, s[2:3] offset:2048
	global_load_dwordx4 v[124:127], v29, s[2:3] offset:2064
	global_load_dwordx4 v[128:131], v30, s[2:3]
	global_load_dwordx4 v[132:135], v30, s[2:3] offset:16
	global_load_dwordx4 v[136:139], v30, s[2:3] offset:2048
	global_load_dwordx4 v[140:143], v30, s[2:3] offset:2064
	global_load_dwordx4 v[144:147], v31, s[2:3]
	global_load_dwordx4 v[148:151], v31, s[2:3] offset:16
	global_load_dwordx4 v[152:155], v31, s[2:3] offset:2048
	global_load_dwordx4 v[156:159], v31, s[2:3] offset:2064
	s_waitcnt vmcnt(32)
	v_lshlrev_b32_e32 v0, 16, v160
	v_and_b32_e32 v1, 0xffff0000, v160
	v_lshlrev_b32_e32 v2, 16, v161
	v_and_b32_e32 v3, 0xffff0000, v161
	v_lshlrev_b32_e32 v4, 16, v162
	v_and_b32_e32 v5, 0xffff0000, v162
	v_lshlrev_b32_e32 v6, 16, v163
	v_and_b32_e32 v7, 0xffff0000, v163
	s_waitcnt vmcnt(30)
	v_mul_f32_e32 v160, v32, v0
	v_fmac_f32_e32 v160, v33, v1
	v_fmac_f32_e32 v160, v34, v2
	v_fmac_f32_e32 v160, v35, v3
	v_fmac_f32_e32 v160, v36, v4
	v_fmac_f32_e32 v160, v37, v5
	v_fmac_f32_e32 v160, v38, v6
	v_fmac_f32_e32 v160, v39, v7
	global_load_dwordx4 v[32:35], v24, s[4:5]
	global_load_dwordx4 v[36:39], v24, s[4:5] offset:16
	s_waitcnt vmcnt(30)
	v_mul_f32_e32 v161, v40, v0
	v_fmac_f32_e32 v161, v41, v1
	v_fmac_f32_e32 v161, v42, v2
	v_fmac_f32_e32 v161, v43, v3
	v_fmac_f32_e32 v161, v44, v4
	v_fmac_f32_e32 v161, v45, v5
	v_fmac_f32_e32 v161, v46, v6
	v_fmac_f32_e32 v161, v47, v7
	global_load_dwordx4 v[40:43], v24, s[4:5] offset:2048
	global_load_dwordx4 v[44:47], v24, s[4:5] offset:2064
	s_waitcnt vmcnt(30)
	v_mul_f32_e32 v162, v48, v0
	v_fmac_f32_e32 v162, v49, v1
	v_fmac_f32_e32 v162, v50, v2
	v_fmac_f32_e32 v162, v51, v3
	v_fmac_f32_e32 v162, v52, v4
	v_fmac_f32_e32 v162, v53, v5
	v_fmac_f32_e32 v162, v54, v6
	v_fmac_f32_e32 v162, v55, v7
	global_load_dwordx4 v[48:51], v25, s[4:5]
	global_load_dwordx4 v[52:55], v25, s[4:5] offset:16
	s_waitcnt vmcnt(30)
	v_mul_f32_e32 v163, v56, v0
	v_fmac_f32_e32 v163, v57, v1
	v_fmac_f32_e32 v163, v58, v2
	v_fmac_f32_e32 v163, v59, v3
	v_fmac_f32_e32 v163, v60, v4
	v_fmac_f32_e32 v163, v61, v5
	v_fmac_f32_e32 v163, v62, v6
	v_fmac_f32_e32 v163, v63, v7
	global_load_dwordx4 v[56:59], v25, s[4:5] offset:2048
	global_load_dwordx4 v[60:63], v25, s[4:5] offset:2064
	s_waitcnt vmcnt(30)
	v_mul_f32_e32 v164, v64, v0
	v_fmac_f32_e32 v164, v65, v1
	v_fmac_f32_e32 v164, v66, v2
	v_fmac_f32_e32 v164, v67, v3
	v_fmac_f32_e32 v164, v68, v4
	v_fmac_f32_e32 v164, v69, v5
	v_fmac_f32_e32 v164, v70, v6
	v_fmac_f32_e32 v164, v71, v7
	global_load_dwordx4 v[64:67], v26, s[4:5]
	global_load_dwordx4 v[68:71], v26, s[4:5] offset:16
	s_waitcnt vmcnt(30)
	v_mul_f32_e32 v165, v72, v0
	v_fmac_f32_e32 v165, v73, v1
	v_fmac_f32_e32 v165, v74, v2
	v_fmac_f32_e32 v165, v75, v3
	v_fmac_f32_e32 v165, v76, v4
	v_fmac_f32_e32 v165, v77, v5
	v_fmac_f32_e32 v165, v78, v6
	v_fmac_f32_e32 v165, v79, v7
	global_load_dwordx4 v[72:75], v26, s[4:5] offset:2048
	global_load_dwordx4 v[76:79], v26, s[4:5] offset:2064
	s_waitcnt vmcnt(30)
	v_mul_f32_e32 v166, v80, v0
	v_fmac_f32_e32 v166, v81, v1
	v_fmac_f32_e32 v166, v82, v2
	v_fmac_f32_e32 v166, v83, v3
	v_fmac_f32_e32 v166, v84, v4
	v_fmac_f32_e32 v166, v85, v5
	v_fmac_f32_e32 v166, v86, v6
	v_fmac_f32_e32 v166, v87, v7
	global_load_dwordx4 v[80:83], v27, s[4:5]
	global_load_dwordx4 v[84:87], v27, s[4:5] offset:16
	s_waitcnt vmcnt(30)
	v_mul_f32_e32 v167, v88, v0
	v_fmac_f32_e32 v167, v89, v1
	v_fmac_f32_e32 v167, v90, v2
	v_fmac_f32_e32 v167, v91, v3
	v_fmac_f32_e32 v167, v92, v4
	v_fmac_f32_e32 v167, v93, v5
	v_fmac_f32_e32 v167, v94, v6
	v_fmac_f32_e32 v167, v95, v7
	global_load_dwordx4 v[88:91], v27, s[4:5] offset:2048
	global_load_dwordx4 v[92:95], v27, s[4:5] offset:2064
	s_waitcnt vmcnt(30)
	v_mul_f32_e32 v168, v96, v0
	v_fmac_f32_e32 v168, v97, v1
	v_fmac_f32_e32 v168, v98, v2
	v_fmac_f32_e32 v168, v99, v3
	v_fmac_f32_e32 v168, v100, v4
	v_fmac_f32_e32 v168, v101, v5
	v_fmac_f32_e32 v168, v102, v6
	v_fmac_f32_e32 v168, v103, v7
	global_load_dwordx4 v[96:99], v28, s[4:5]
	global_load_dwordx4 v[100:103], v28, s[4:5] offset:16
	s_waitcnt vmcnt(30)
	v_mul_f32_e32 v169, v104, v0
	v_fmac_f32_e32 v169, v105, v1
	v_fmac_f32_e32 v169, v106, v2
	v_fmac_f32_e32 v169, v107, v3
	v_fmac_f32_e32 v169, v108, v4
	v_fmac_f32_e32 v169, v109, v5
	v_fmac_f32_e32 v169, v110, v6
	v_fmac_f32_e32 v169, v111, v7
	global_load_dwordx4 v[104:107], v28, s[4:5] offset:2048
	global_load_dwordx4 v[108:111], v28, s[4:5] offset:2064
	s_waitcnt vmcnt(30)
	v_mul_f32_e32 v170, v112, v0
	v_fmac_f32_e32 v170, v113, v1
	v_fmac_f32_e32 v170, v114, v2
	v_fmac_f32_e32 v170, v115, v3
	v_fmac_f32_e32 v170, v116, v4
	v_fmac_f32_e32 v170, v117, v5
	v_fmac_f32_e32 v170, v118, v6
	v_fmac_f32_e32 v170, v119, v7
	global_load_dwordx4 v[112:115], v29, s[4:5]
	global_load_dwordx4 v[116:119], v29, s[4:5] offset:16
	s_waitcnt vmcnt(30)
	v_mul_f32_e32 v171, v120, v0
	v_fmac_f32_e32 v171, v121, v1
	v_fmac_f32_e32 v171, v122, v2
	v_fmac_f32_e32 v171, v123, v3
	v_fmac_f32_e32 v171, v124, v4
	v_fmac_f32_e32 v171, v125, v5
	v_fmac_f32_e32 v171, v126, v6
	v_fmac_f32_e32 v171, v127, v7
	global_load_dwordx4 v[120:123], v29, s[4:5] offset:2048
	global_load_dwordx4 v[124:127], v29, s[4:5] offset:2064
	s_waitcnt vmcnt(30)
	v_mul_f32_e32 v172, v128, v0
	v_fmac_f32_e32 v172, v129, v1
	v_fmac_f32_e32 v172, v130, v2
	v_fmac_f32_e32 v172, v131, v3
	v_fmac_f32_e32 v172, v132, v4
	v_fmac_f32_e32 v172, v133, v5
	v_fmac_f32_e32 v172, v134, v6
	v_fmac_f32_e32 v172, v135, v7
	global_load_dwordx4 v[128:131], v30, s[4:5]
	global_load_dwordx4 v[132:135], v30, s[4:5] offset:16
	s_waitcnt vmcnt(30)
	v_mul_f32_e32 v173, v136, v0
	v_fmac_f32_e32 v173, v137, v1
	v_fmac_f32_e32 v173, v138, v2
	v_fmac_f32_e32 v173, v139, v3
	v_fmac_f32_e32 v173, v140, v4
	v_fmac_f32_e32 v173, v141, v5
	v_fmac_f32_e32 v173, v142, v6
	v_fmac_f32_e32 v173, v143, v7
	global_load_dwordx4 v[136:139], v30, s[4:5] offset:2048
	global_load_dwordx4 v[140:143], v30, s[4:5] offset:2064
	s_waitcnt vmcnt(30)
	v_mul_f32_e32 v174, v144, v0
	v_fmac_f32_e32 v174, v145, v1
	v_fmac_f32_e32 v174, v146, v2
	v_fmac_f32_e32 v174, v147, v3
	v_fmac_f32_e32 v174, v148, v4
	v_fmac_f32_e32 v174, v149, v5
	v_fmac_f32_e32 v174, v150, v6
	v_fmac_f32_e32 v174, v151, v7
	global_load_dwordx4 v[144:147], v31, s[4:5]
	global_load_dwordx4 v[148:151], v31, s[4:5] offset:16
	s_waitcnt vmcnt(30)
	v_mul_f32_e32 v175, v152, v0
	v_fmac_f32_e32 v175, v153, v1
	v_fmac_f32_e32 v175, v154, v2
	v_fmac_f32_e32 v175, v155, v3
	v_fmac_f32_e32 v175, v156, v4
	v_fmac_f32_e32 v175, v157, v5
	v_fmac_f32_e32 v175, v158, v6
	v_fmac_f32_e32 v175, v159, v7
	global_load_dwordx4 v[152:155], v31, s[4:5] offset:2048
	global_load_dwordx4 v[156:159], v31, s[4:5] offset:2064
	v_add_f32_dpp v160, v160, v160 row_ror:8 row_mask:0xf bank_mask:0x3
	v_add_f32_dpp v160, v168, v168 row_ror:8 row_mask:0xf bank_mask:0xc
	v_add_f32_dpp v161, v161, v161 row_ror:8 row_mask:0xf bank_mask:0x3
	v_add_f32_dpp v161, v169, v169 row_ror:8 row_mask:0xf bank_mask:0xc
	v_add_f32_dpp v162, v162, v162 row_ror:8 row_mask:0xf bank_mask:0x3
	v_add_f32_dpp v162, v170, v170 row_ror:8 row_mask:0xf bank_mask:0xc
	v_add_f32_dpp v163, v163, v163 row_ror:8 row_mask:0xf bank_mask:0x3
	v_add_f32_dpp v163, v171, v171 row_ror:8 row_mask:0xf bank_mask:0xc
	v_add_f32_dpp v164, v164, v164 row_ror:8 row_mask:0xf bank_mask:0x3
	v_add_f32_dpp v164, v172, v172 row_ror:8 row_mask:0xf bank_mask:0xc
	v_add_f32_dpp v165, v165, v165 row_ror:8 row_mask:0xf bank_mask:0x3
	v_add_f32_dpp v165, v173, v173 row_ror:8 row_mask:0xf bank_mask:0xc
	v_add_f32_dpp v166, v166, v166 row_ror:8 row_mask:0xf bank_mask:0x3
	v_add_f32_dpp v166, v174, v174 row_ror:8 row_mask:0xf bank_mask:0xc
	v_add_f32_dpp v167, v167, v167 row_ror:8 row_mask:0xf bank_mask:0x3
	v_add_f32_dpp v167, v175, v175 row_ror:8 row_mask:0xf bank_mask:0xc
	v_add_f32_dpp v160, v160, v160 row_shl:4 row_mask:0xf bank_mask:0x5
	v_add_f32_dpp v160, v164, v164 row_shr:4 row_mask:0xf bank_mask:0xa
	v_add_f32_dpp v161, v161, v161 row_shl:4 row_mask:0xf bank_mask:0x5
	v_add_f32_dpp v161, v165, v165 row_shr:4 row_mask:0xf bank_mask:0xa
	v_add_f32_dpp v162, v162, v162 row_shl:4 row_mask:0xf bank_mask:0x5
	v_add_f32_dpp v162, v166, v166 row_shr:4 row_mask:0xf bank_mask:0xa
	v_add_f32_dpp v163, v163, v163 row_shl:4 row_mask:0xf bank_mask:0x5
	v_add_f32_dpp v163, v167, v167 row_shr:4 row_mask:0xf bank_mask:0xa
	v_and_b32_e32 v176, 2, v18
	v_cmp_ne_u32_e32 vcc, 0, v176
	v_add_f32_dpp v230, v160, v160 quad_perm:[2,3,0,1] row_mask:0xf bank_mask:0xf
	v_add_f32_dpp v231, v162, v162 quad_perm:[2,3,0,1] row_mask:0xf bank_mask:0xf
	v_add_f32_dpp v232, v161, v161 quad_perm:[2,3,0,1] row_mask:0xf bank_mask:0xf
	v_add_f32_dpp v233, v163, v163 quad_perm:[2,3,0,1] row_mask:0xf bank_mask:0xf
	v_cndmask_b32_e32 v230, v230, v231, vcc
	v_cndmask_b32_e32 v232, v232, v233, vcc
	v_and_b32_e32 v176, 1, v18
	v_cmp_ne_u32_e32 vcc, 0, v176
	v_add_f32_dpp v231, v230, v230 quad_perm:[1,0,3,2] row_mask:0xf bank_mask:0xf
	v_add_f32_dpp v233, v232, v232 quad_perm:[1,0,3,2] row_mask:0xf bank_mask:0xf
	s_nop 1
	v_cndmask_b32_e32 v241, v231, v233, vcc
	s_nop 1
	v_max_f32_dpp v242, v241, v241 row_ror:8 row_mask:0xf bank_mask:0xf
	s_nop 1
	v_max_f32_dpp v242, v242, v242 row_ror:4 row_mask:0xf bank_mask:0xf
	s_nop 1
	v_max_f32_dpp v242, v242, v242 row_ror:2 row_mask:0xf bank_mask:0xf
	s_nop 1
	v_max_f32_dpp v242, v242, v242 row_ror:1 row_mask:0xf bank_mask:0xf
	ds_bpermute_b32 v234, v238, v242
	s_waitcnt lgkmcnt(0)
	v_max_f32_e32 v242, v242, v234
	ds_bpermute_b32 v234, v239, v242
	s_waitcnt lgkmcnt(0)
	v_max_f32_e32 v242, v242, v234
	v_max_f32_e32 v242, v16, v242
	v_sub_f32_e32 v243, v16, v242
	v_sub_f32_e32 v240, v241, v242
	v_mul_f32_e32 v243, 0x3fb8aa3b, v243
	v_mul_f32_e32 v240, 0x3fb8aa3b, v240
	v_exp_f32_e32 v243, v243
	v_exp_f32_e32 v240, v240
	v_mov_b32_e32 v16, v242
	s_nop 0
	s_nop 1
	v_add_f32_dpp v235, v240, v240 row_ror:8 row_mask:0xf bank_mask:0xf
	s_nop 1
	v_add_f32_dpp v235, v235, v235 row_ror:4 row_mask:0xf bank_mask:0xf
	s_nop 1
	v_add_f32_dpp v235, v235, v235 row_ror:2 row_mask:0xf bank_mask:0xf
	s_nop 1
	v_add_f32_dpp v235, v235, v235 row_ror:1 row_mask:0xf bank_mask:0xf
	ds_bpermute_b32 v234, v238, v235
	s_waitcnt lgkmcnt(0)
	v_add_f32_e32 v235, v235, v234
	ds_bpermute_b32 v234, v239, v235
	s_waitcnt lgkmcnt(0)
	v_add_f32_e32 v235, v235, v234
	v_fma_f32 v17, v17, v243, v235
	v_mul_f32_e32 v8, v8, v243
	v_mul_f32_e32 v9, v9, v243
	v_mul_f32_e32 v10, v10, v243
	v_mul_f32_e32 v11, v11, v243
	v_mul_f32_e32 v12, v12, v243
	v_mul_f32_e32 v13, v13, v243
	v_mul_f32_e32 v14, v14, v243
	v_mul_f32_e32 v15, v15, v243
	s_add_u32 s2, s2, 0x20000
	s_addc_u32 s3, s3, 0
	s_add_u32 s4, s4, 0x20000
	s_addc_u32 s5, s5, 0
	s_waitcnt vmcnt(30)
	v_fmac_f32_dpp v8, v240, v32 row_newbcast:0 row_mask:0xf bank_mask:0xf
	v_fmac_f32_dpp v9, v240, v33 row_newbcast:0 row_mask:0xf bank_mask:0xf
	v_fmac_f32_dpp v10, v240, v34 row_newbcast:0 row_mask:0xf bank_mask:0xf
	v_fmac_f32_dpp v11, v240, v35 row_newbcast:0 row_mask:0xf bank_mask:0xf
	v_fmac_f32_dpp v12, v240, v36 row_newbcast:0 row_mask:0xf bank_mask:0xf
	v_fmac_f32_dpp v13, v240, v37 row_newbcast:0 row_mask:0xf bank_mask:0xf
	v_fmac_f32_dpp v14, v240, v38 row_newbcast:0 row_mask:0xf bank_mask:0xf
	v_fmac_f32_dpp v15, v240, v39 row_newbcast:0 row_mask:0xf bank_mask:0xf
	global_load_dwordx4 v[32:35], v24, s[2:3]
	global_load_dwordx4 v[36:39], v24, s[2:3] offset:16
	s_waitcnt vmcnt(30)
	v_fmac_f32_dpp v8, v240, v40 row_newbcast:1 row_mask:0xf bank_mask:0xf
	v_fmac_f32_dpp v9, v240, v41 row_newbcast:1 row_mask:0xf bank_mask:0xf
	v_fmac_f32_dpp v10, v240, v42 row_newbcast:1 row_mask:0xf bank_mask:0xf
	v_fmac_f32_dpp v11, v240, v43 row_newbcast:1 row_mask:0xf bank_mask:0xf
	v_fmac_f32_dpp v12, v240, v44 row_newbcast:1 row_mask:0xf bank_mask:0xf
	v_fmac_f32_dpp v13, v240, v45 row_newbcast:1 row_mask:0xf bank_mask:0xf
	v_fmac_f32_dpp v14, v240, v46 row_newbcast:1 row_mask:0xf bank_mask:0xf
	v_fmac_f32_dpp v15, v240, v47 row_newbcast:1 row_mask:0xf bank_mask:0xf
	global_load_dwordx4 v[40:43], v24, s[2:3] offset:2048
	global_load_dwordx4 v[44:47], v24, s[2:3] offset:2064
	s_waitcnt vmcnt(30)
	v_fmac_f32_dpp v8, v240, v48 row_newbcast:2 row_mask:0xf bank_mask:0xf
	v_fmac_f32_dpp v9, v240, v49 row_newbcast:2 row_mask:0xf bank_mask:0xf
	v_fmac_f32_dpp v10, v240, v50 row_newbcast:2 row_mask:0xf bank_mask:0xf
	v_fmac_f32_dpp v11, v240, v51 row_newbcast:2 row_mask:0xf bank_mask:0xf
	v_fmac_f32_dpp v12, v240, v52 row_newbcast:2 row_mask:0xf bank_mask:0xf
	v_fmac_f32_dpp v13, v240, v53 row_newbcast:2 row_mask:0xf bank_mask:0xf
	v_fmac_f32_dpp v14, v240, v54 row_newbcast:2 row_mask:0xf bank_mask:0xf
	v_fmac_f32_dpp v15, v240, v55 row_newbcast:2 row_mask:0xf bank_mask:0xf
	global_load_dwordx4 v[48:51], v25, s[2:3]
	global_load_dwordx4 v[52:55], v25, s[2:3] offset:16
	s_waitcnt vmcnt(30)
	v_fmac_f32_dpp v8, v240, v56 row_newbcast:3 row_mask:0xf bank_mask:0xf
	v_fmac_f32_dpp v9, v240, v57 row_newbcast:3 row_mask:0xf bank_mask:0xf
	v_fmac_f32_dpp v10, v240, v58 row_newbcast:3 row_mask:0xf bank_mask:0xf
	v_fmac_f32_dpp v11, v240, v59 row_newbcast:3 row_mask:0xf bank_mask:0xf
	v_fmac_f32_dpp v12, v240, v60 row_newbcast:3 row_mask:0xf bank_mask:0xf
	v_fmac_f32_dpp v13, v240, v61 row_newbcast:3 row_mask:0xf bank_mask:0xf
	v_fmac_f32_dpp v14, v240, v62 row_newbcast:3 row_mask:0xf bank_mask:0xf
	v_fmac_f32_dpp v15, v240, v63 row_newbcast:3 row_mask:0xf bank_mask:0xf
	global_load_dwordx4 v[56:59], v25, s[2:3] offset:2048
	global_load_dwordx4 v[60:63], v25, s[2:3] offset:2064
	s_waitcnt vmcnt(30)
	v_fmac_f32_dpp v8, v240, v64 row_newbcast:4 row_mask:0xf bank_mask:0xf
	v_fmac_f32_dpp v9, v240, v65 row_newbcast:4 row_mask:0xf bank_mask:0xf
	v_fmac_f32_dpp v10, v240, v66 row_newbcast:4 row_mask:0xf bank_mask:0xf
	v_fmac_f32_dpp v11, v240, v67 row_newbcast:4 row_mask:0xf bank_mask:0xf
	v_fmac_f32_dpp v12, v240, v68 row_newbcast:4 row_mask:0xf bank_mask:0xf
	v_fmac_f32_dpp v13, v240, v69 row_newbcast:4 row_mask:0xf bank_mask:0xf
	v_fmac_f32_dpp v14, v240, v70 row_newbcast:4 row_mask:0xf bank_mask:0xf
	v_fmac_f32_dpp v15, v240, v71 row_newbcast:4 row_mask:0xf bank_mask:0xf
	global_load_dwordx4 v[64:67], v26, s[2:3]
	global_load_dwordx4 v[68:71], v26, s[2:3] offset:16
	s_waitcnt vmcnt(30)
	v_fmac_f32_dpp v8, v240, v72 row_newbcast:5 row_mask:0xf bank_mask:0xf
	v_fmac_f32_dpp v9, v240, v73 row_newbcast:5 row_mask:0xf bank_mask:0xf
	v_fmac_f32_dpp v10, v240, v74 row_newbcast:5 row_mask:0xf bank_mask:0xf
	v_fmac_f32_dpp v11, v240, v75 row_newbcast:5 row_mask:0xf bank_mask:0xf
	v_fmac_f32_dpp v12, v240, v76 row_newbcast:5 row_mask:0xf bank_mask:0xf
	v_fmac_f32_dpp v13, v240, v77 row_newbcast:5 row_mask:0xf bank_mask:0xf
	v_fmac_f32_dpp v14, v240, v78 row_newbcast:5 row_mask:0xf bank_mask:0xf
	v_fmac_f32_dpp v15, v240, v79 row_newbcast:5 row_mask:0xf bank_mask:0xf
	global_load_dwordx4 v[72:75], v26, s[2:3] offset:2048
	global_load_dwordx4 v[76:79], v26, s[2:3] offset:2064
	s_waitcnt vmcnt(30)
	v_fmac_f32_dpp v8, v240, v80 row_newbcast:6 row_mask:0xf bank_mask:0xf
	v_fmac_f32_dpp v9, v240, v81 row_newbcast:6 row_mask:0xf bank_mask:0xf
	v_fmac_f32_dpp v10, v240, v82 row_newbcast:6 row_mask:0xf bank_mask:0xf
	v_fmac_f32_dpp v11, v240, v83 row_newbcast:6 row_mask:0xf bank_mask:0xf
	v_fmac_f32_dpp v12, v240, v84 row_newbcast:6 row_mask:0xf bank_mask:0xf
	v_fmac_f32_dpp v13, v240, v85 row_newbcast:6 row_mask:0xf bank_mask:0xf
	v_fmac_f32_dpp v14, v240, v86 row_newbcast:6 row_mask:0xf bank_mask:0xf
	v_fmac_f32_dpp v15, v240, v87 row_newbcast:6 row_mask:0xf bank_mask:0xf
	global_load_dwordx4 v[80:83], v27, s[2:3]
	global_load_dwordx4 v[84:87], v27, s[2:3] offset:16
	s_waitcnt vmcnt(30)
	v_fmac_f32_dpp v8, v240, v88 row_newbcast:7 row_mask:0xf bank_mask:0xf
	v_fmac_f32_dpp v9, v240, v89 row_newbcast:7 row_mask:0xf bank_mask:0xf
	v_fmac_f32_dpp v10, v240, v90 row_newbcast:7 row_mask:0xf bank_mask:0xf
	v_fmac_f32_dpp v11, v240, v91 row_newbcast:7 row_mask:0xf bank_mask:0xf
	v_fmac_f32_dpp v12, v240, v92 row_newbcast:7 row_mask:0xf bank_mask:0xf
	v_fmac_f32_dpp v13, v240, v93 row_newbcast:7 row_mask:0xf bank_mask:0xf
	v_fmac_f32_dpp v14, v240, v94 row_newbcast:7 row_mask:0xf bank_mask:0xf
	v_fmac_f32_dpp v15, v240, v95 row_newbcast:7 row_mask:0xf bank_mask:0xf
	global_load_dwordx4 v[88:91], v27, s[2:3] offset:2048
	global_load_dwordx4 v[92:95], v27, s[2:3] offset:2064
	s_waitcnt vmcnt(30)
	v_fmac_f32_dpp v8, v240, v96 row_newbcast:8 row_mask:0xf bank_mask:0xf
	v_fmac_f32_dpp v9, v240, v97 row_newbcast:8 row_mask:0xf bank_mask:0xf
	v_fmac_f32_dpp v10, v240, v98 row_newbcast:8 row_mask:0xf bank_mask:0xf
	v_fmac_f32_dpp v11, v240, v99 row_newbcast:8 row_mask:0xf bank_mask:0xf
	v_fmac_f32_dpp v12, v240, v100 row_newbcast:8 row_mask:0xf bank_mask:0xf
	v_fmac_f32_dpp v13, v240, v101 row_newbcast:8 row_mask:0xf bank_mask:0xf
	v_fmac_f32_dpp v14, v240, v102 row_newbcast:8 row_mask:0xf bank_mask:0xf
	v_fmac_f32_dpp v15, v240, v103 row_newbcast:8 row_mask:0xf bank_mask:0xf
	global_load_dwordx4 v[96:99], v28, s[2:3]
	global_load_dwordx4 v[100:103], v28, s[2:3] offset:16
	s_waitcnt vmcnt(30)
	v_fmac_f32_dpp v8, v240, v104 row_newbcast:9 row_mask:0xf bank_mask:0xf
	v_fmac_f32_dpp v9, v240, v105 row_newbcast:9 row_mask:0xf bank_mask:0xf
	v_fmac_f32_dpp v10, v240, v106 row_newbcast:9 row_mask:0xf bank_mask:0xf
	v_fmac_f32_dpp v11, v240, v107 row_newbcast:9 row_mask:0xf bank_mask:0xf
	v_fmac_f32_dpp v12, v240, v108 row_newbcast:9 row_mask:0xf bank_mask:0xf
	v_fmac_f32_dpp v13, v240, v109 row_newbcast:9 row_mask:0xf bank_mask:0xf
	v_fmac_f32_dpp v14, v240, v110 row_newbcast:9 row_mask:0xf bank_mask:0xf
	v_fmac_f32_dpp v15, v240, v111 row_newbcast:9 row_mask:0xf bank_mask:0xf
	global_load_dwordx4 v[104:107], v28, s[2:3] offset:2048
	global_load_dwordx4 v[108:111], v28, s[2:3] offset:2064
	s_waitcnt vmcnt(30)
	v_fmac_f32_dpp v8, v240, v112 row_newbcast:10 row_mask:0xf bank_mask:0xf
	v_fmac_f32_dpp v9, v240, v113 row_newbcast:10 row_mask:0xf bank_mask:0xf
	v_fmac_f32_dpp v10, v240, v114 row_newbcast:10 row_mask:0xf bank_mask:0xf
	v_fmac_f32_dpp v11, v240, v115 row_newbcast:10 row_mask:0xf bank_mask:0xf
	v_fmac_f32_dpp v12, v240, v116 row_newbcast:10 row_mask:0xf bank_mask:0xf
	v_fmac_f32_dpp v13, v240, v117 row_newbcast:10 row_mask:0xf bank_mask:0xf
	v_fmac_f32_dpp v14, v240, v118 row_newbcast:10 row_mask:0xf bank_mask:0xf
	v_fmac_f32_dpp v15, v240, v119 row_newbcast:10 row_mask:0xf bank_mask:0xf
	global_load_dwordx4 v[112:115], v29, s[2:3]
	global_load_dwordx4 v[116:119], v29, s[2:3] offset:16
	s_waitcnt vmcnt(30)
	v_fmac_f32_dpp v8, v240, v120 row_newbcast:11 row_mask:0xf bank_mask:0xf
	v_fmac_f32_dpp v9, v240, v121 row_newbcast:11 row_mask:0xf bank_mask:0xf
	v_fmac_f32_dpp v10, v240, v122 row_newbcast:11 row_mask:0xf bank_mask:0xf
	v_fmac_f32_dpp v11, v240, v123 row_newbcast:11 row_mask:0xf bank_mask:0xf
	v_fmac_f32_dpp v12, v240, v124 row_newbcast:11 row_mask:0xf bank_mask:0xf
	v_fmac_f32_dpp v13, v240, v125 row_newbcast:11 row_mask:0xf bank_mask:0xf
	v_fmac_f32_dpp v14, v240, v126 row_newbcast:11 row_mask:0xf bank_mask:0xf
	v_fmac_f32_dpp v15, v240, v127 row_newbcast:11 row_mask:0xf bank_mask:0xf
	global_load_dwordx4 v[120:123], v29, s[2:3] offset:2048
	global_load_dwordx4 v[124:127], v29, s[2:3] offset:2064
	s_waitcnt vmcnt(30)
	v_fmac_f32_dpp v8, v240, v128 row_newbcast:12 row_mask:0xf bank_mask:0xf
	v_fmac_f32_dpp v9, v240, v129 row_newbcast:12 row_mask:0xf bank_mask:0xf
	v_fmac_f32_dpp v10, v240, v130 row_newbcast:12 row_mask:0xf bank_mask:0xf
	v_fmac_f32_dpp v11, v240, v131 row_newbcast:12 row_mask:0xf bank_mask:0xf
	v_fmac_f32_dpp v12, v240, v132 row_newbcast:12 row_mask:0xf bank_mask:0xf
	v_fmac_f32_dpp v13, v240, v133 row_newbcast:12 row_mask:0xf bank_mask:0xf
	v_fmac_f32_dpp v14, v240, v134 row_newbcast:12 row_mask:0xf bank_mask:0xf
	v_fmac_f32_dpp v15, v240, v135 row_newbcast:12 row_mask:0xf bank_mask:0xf
	global_load_dwordx4 v[128:131], v30, s[2:3]
	global_load_dwordx4 v[132:135], v30, s[2:3] offset:16
	s_waitcnt vmcnt(30)
	v_fmac_f32_dpp v8, v240, v136 row_newbcast:13 row_mask:0xf bank_mask:0xf
	v_fmac_f32_dpp v9, v240, v137 row_newbcast:13 row_mask:0xf bank_mask:0xf
	v_fmac_f32_dpp v10, v240, v138 row_newbcast:13 row_mask:0xf bank_mask:0xf
	v_fmac_f32_dpp v11, v240, v139 row_newbcast:13 row_mask:0xf bank_mask:0xf
	v_fmac_f32_dpp v12, v240, v140 row_newbcast:13 row_mask:0xf bank_mask:0xf
	v_fmac_f32_dpp v13, v240, v141 row_newbcast:13 row_mask:0xf bank_mask:0xf
	v_fmac_f32_dpp v14, v240, v142 row_newbcast:13 row_mask:0xf bank_mask:0xf
	v_fmac_f32_dpp v15, v240, v143 row_newbcast:13 row_mask:0xf bank_mask:0xf
	global_load_dwordx4 v[136:139], v30, s[2:3] offset:2048
	global_load_dwordx4 v[140:143], v30, s[2:3] offset:2064
	s_waitcnt vmcnt(30)
	v_fmac_f32_dpp v8, v240, v144 row_newbcast:14 row_mask:0xf bank_mask:0xf
	v_fmac_f32_dpp v9, v240, v145 row_newbcast:14 row_mask:0xf bank_mask:0xf
	v_fmac_f32_dpp v10, v240, v146 row_newbcast:14 row_mask:0xf bank_mask:0xf
	v_fmac_f32_dpp v11, v240, v147 row_newbcast:14 row_mask:0xf bank_mask:0xf
	v_fmac_f32_dpp v12, v240, v148 row_newbcast:14 row_mask:0xf bank_mask:0xf
	v_fmac_f32_dpp v13, v240, v149 row_newbcast:14 row_mask:0xf bank_mask:0xf
	v_fmac_f32_dpp v14, v240, v150 row_newbcast:14 row_mask:0xf bank_mask:0xf
	v_fmac_f32_dpp v15, v240, v151 row_newbcast:14 row_mask:0xf bank_mask:0xf
	global_load_dwordx4 v[144:147], v31, s[2:3]
	global_load_dwordx4 v[148:151], v31, s[2:3] offset:16
	s_waitcnt vmcnt(30)
	v_fmac_f32_dpp v8, v240, v152 row_newbcast:15 row_mask:0xf bank_mask:0xf
	v_fmac_f32_dpp v9, v240, v153 row_newbcast:15 row_mask:0xf bank_mask:0xf
	v_fmac_f32_dpp v10, v240, v154 row_newbcast:15 row_mask:0xf bank_mask:0xf
	v_fmac_f32_dpp v11, v240, v155 row_newbcast:15 row_mask:0xf bank_mask:0xf
	v_fmac_f32_dpp v12, v240, v156 row_newbcast:15 row_mask:0xf bank_mask:0xf
	v_fmac_f32_dpp v13, v240, v157 row_newbcast:15 row_mask:0xf bank_mask:0xf
	v_fmac_f32_dpp v14, v240, v158 row_newbcast:15 row_mask:0xf bank_mask:0xf
	v_fmac_f32_dpp v15, v240, v159 row_newbcast:15 row_mask:0xf bank_mask:0xf
	global_load_dwordx4 v[152:155], v31, s[2:3] offset:2048
	global_load_dwordx4 v[156:159], v31, s[2:3] offset:2064
	s_waitcnt vmcnt(30)
	v_mul_f32_e32 v160, v32, v0
	v_fmac_f32_e32 v160, v33, v1
	v_fmac_f32_e32 v160, v34, v2
	v_fmac_f32_e32 v160, v35, v3
	v_fmac_f32_e32 v160, v36, v4
	v_fmac_f32_e32 v160, v37, v5
	v_fmac_f32_e32 v160, v38, v6
	v_fmac_f32_e32 v160, v39, v7
	global_load_dwordx4 v[32:35], v24, s[4:5]
	global_load_dwordx4 v[36:39], v24, s[4:5] offset:16
	s_waitcnt vmcnt(30)
	v_mul_f32_e32 v161, v40, v0
	v_fmac_f32_e32 v161, v41, v1
	v_fmac_f32_e32 v161, v42, v2
	v_fmac_f32_e32 v161, v43, v3
	v_fmac_f32_e32 v161, v44, v4
	v_fmac_f32_e32 v161, v45, v5
	v_fmac_f32_e32 v161, v46, v6
	v_fmac_f32_e32 v161, v47, v7
	global_load_dwordx4 v[40:43], v24, s[4:5] offset:2048
	global_load_dwordx4 v[44:47], v24, s[4:5] offset:2064
	s_waitcnt vmcnt(30)
	v_mul_f32_e32 v162, v48, v0
	v_fmac_f32_e32 v162, v49, v1
	v_fmac_f32_e32 v162, v50, v2
	v_fmac_f32_e32 v162, v51, v3
	v_fmac_f32_e32 v162, v52, v4
	v_fmac_f32_e32 v162, v53, v5
	v_fmac_f32_e32 v162, v54, v6
	v_fmac_f32_e32 v162, v55, v7
	global_load_dwordx4 v[48:51], v25, s[4:5]
	global_load_dwordx4 v[52:55], v25, s[4:5] offset:16
	s_waitcnt vmcnt(30)
	v_mul_f32_e32 v163, v56, v0
	v_fmac_f32_e32 v163, v57, v1
	v_fmac_f32_e32 v163, v58, v2
	v_fmac_f32_e32 v163, v59, v3
	v_fmac_f32_e32 v163, v60, v4
	v_fmac_f32_e32 v163, v61, v5
	v_fmac_f32_e32 v163, v62, v6
	v_fmac_f32_e32 v163, v63, v7
	global_load_dwordx4 v[56:59], v25, s[4:5] offset:2048
	global_load_dwordx4 v[60:63], v25, s[4:5] offset:2064
	s_waitcnt vmcnt(30)
	v_mul_f32_e32 v164, v64, v0
	v_fmac_f32_e32 v164, v65, v1
	v_fmac_f32_e32 v164, v66, v2
	v_fmac_f32_e32 v164, v67, v3
	v_fmac_f32_e32 v164, v68, v4
	v_fmac_f32_e32 v164, v69, v5
	v_fmac_f32_e32 v164, v70, v6
	v_fmac_f32_e32 v164, v71, v7
	global_load_dwordx4 v[64:67], v26, s[4:5]
	global_load_dwordx4 v[68:71], v26, s[4:5] offset:16
	s_waitcnt vmcnt(30)
	v_mul_f32_e32 v165, v72, v0
	v_fmac_f32_e32 v165, v73, v1
	v_fmac_f32_e32 v165, v74, v2
	v_fmac_f32_e32 v165, v75, v3
	v_fmac_f32_e32 v165, v76, v4
	v_fmac_f32_e32 v165, v77, v5
	v_fmac_f32_e32 v165, v78, v6
	v_fmac_f32_e32 v165, v79, v7
	global_load_dwordx4 v[72:75], v26, s[4:5] offset:2048
	global_load_dwordx4 v[76:79], v26, s[4:5] offset:2064
	s_waitcnt vmcnt(30)
	v_mul_f32_e32 v166, v80, v0
	v_fmac_f32_e32 v166, v81, v1
	v_fmac_f32_e32 v166, v82, v2
	v_fmac_f32_e32 v166, v83, v3
	v_fmac_f32_e32 v166, v84, v4
	v_fmac_f32_e32 v166, v85, v5
	v_fmac_f32_e32 v166, v86, v6
	v_fmac_f32_e32 v166, v87, v7
	global_load_dwordx4 v[80:83], v27, s[4:5]
	global_load_dwordx4 v[84:87], v27, s[4:5] offset:16
	s_waitcnt vmcnt(30)
	v_mul_f32_e32 v167, v88, v0
	v_fmac_f32_e32 v167, v89, v1
	v_fmac_f32_e32 v167, v90, v2
	v_fmac_f32_e32 v167, v91, v3
	v_fmac_f32_e32 v167, v92, v4
	v_fmac_f32_e32 v167, v93, v5
	v_fmac_f32_e32 v167, v94, v6
	v_fmac_f32_e32 v167, v95, v7
	global_load_dwordx4 v[88:91], v27, s[4:5] offset:2048
	global_load_dwordx4 v[92:95], v27, s[4:5] offset:2064
	s_waitcnt vmcnt(30)
	v_mul_f32_e32 v168, v96, v0
	v_fmac_f32_e32 v168, v97, v1
	v_fmac_f32_e32 v168, v98, v2
	v_fmac_f32_e32 v168, v99, v3
	v_fmac_f32_e32 v168, v100, v4
	v_fmac_f32_e32 v168, v101, v5
	v_fmac_f32_e32 v168, v102, v6
	v_fmac_f32_e32 v168, v103, v7
	global_load_dwordx4 v[96:99], v28, s[4:5]
	global_load_dwordx4 v[100:103], v28, s[4:5] offset:16
	s_waitcnt vmcnt(30)
	v_mul_f32_e32 v169, v104, v0
	v_fmac_f32_e32 v169, v105, v1
	v_fmac_f32_e32 v169, v106, v2
	v_fmac_f32_e32 v169, v107, v3
	v_fmac_f32_e32 v169, v108, v4
	v_fmac_f32_e32 v169, v109, v5
	v_fmac_f32_e32 v169, v110, v6
	v_fmac_f32_e32 v169, v111, v7
	global_load_dwordx4 v[104:107], v28, s[4:5] offset:2048
	global_load_dwordx4 v[108:111], v28, s[4:5] offset:2064
	s_waitcnt vmcnt(30)
	v_mul_f32_e32 v170, v112, v0
	v_fmac_f32_e32 v170, v113, v1
	v_fmac_f32_e32 v170, v114, v2
	v_fmac_f32_e32 v170, v115, v3
	v_fmac_f32_e32 v170, v116, v4
	v_fmac_f32_e32 v170, v117, v5
	v_fmac_f32_e32 v170, v118, v6
	v_fmac_f32_e32 v170, v119, v7
	global_load_dwordx4 v[112:115], v29, s[4:5]
	global_load_dwordx4 v[116:119], v29, s[4:5] offset:16
	s_waitcnt vmcnt(30)
	v_mul_f32_e32 v171, v120, v0
	v_fmac_f32_e32 v171, v121, v1
	v_fmac_f32_e32 v171, v122, v2
	v_fmac_f32_e32 v171, v123, v3
	v_fmac_f32_e32 v171, v124, v4
	v_fmac_f32_e32 v171, v125, v5
	v_fmac_f32_e32 v171, v126, v6
	v_fmac_f32_e32 v171, v127, v7
	global_load_dwordx4 v[120:123], v29, s[4:5] offset:2048
	global_load_dwordx4 v[124:127], v29, s[4:5] offset:2064
	s_waitcnt vmcnt(30)
	v_mul_f32_e32 v172, v128, v0
	v_fmac_f32_e32 v172, v129, v1
	v_fmac_f32_e32 v172, v130, v2
	v_fmac_f32_e32 v172, v131, v3
	v_fmac_f32_e32 v172, v132, v4
	v_fmac_f32_e32 v172, v133, v5
	v_fmac_f32_e32 v172, v134, v6
	v_fmac_f32_e32 v172, v135, v7
	global_load_dwordx4 v[128:131], v30, s[4:5]
	global_load_dwordx4 v[132:135], v30, s[4:5] offset:16
	s_waitcnt vmcnt(30)
	v_mul_f32_e32 v173, v136, v0
	v_fmac_f32_e32 v173, v137, v1
	v_fmac_f32_e32 v173, v138, v2
	v_fmac_f32_e32 v173, v139, v3
	v_fmac_f32_e32 v173, v140, v4
	v_fmac_f32_e32 v173, v141, v5
	v_fmac_f32_e32 v173, v142, v6
	v_fmac_f32_e32 v173, v143, v7
	global_load_dwordx4 v[136:139], v30, s[4:5] offset:2048
	global_load_dwordx4 v[140:143], v30, s[4:5] offset:2064
	s_waitcnt vmcnt(30)
	v_mul_f32_e32 v174, v144, v0
	v_fmac_f32_e32 v174, v145, v1
	v_fmac_f32_e32 v174, v146, v2
	v_fmac_f32_e32 v174, v147, v3
	v_fmac_f32_e32 v174, v148, v4
	v_fmac_f32_e32 v174, v149, v5
	v_fmac_f32_e32 v174, v150, v6
	v_fmac_f32_e32 v174, v151, v7
	global_load_dwordx4 v[144:147], v31, s[4:5]
	global_load_dwordx4 v[148:151], v31, s[4:5] offset:16
	s_waitcnt vmcnt(30)
	v_mul_f32_e32 v175, v152, v0
	v_fmac_f32_e32 v175, v153, v1
	v_fmac_f32_e32 v175, v154, v2
	v_fmac_f32_e32 v175, v155, v3
	v_fmac_f32_e32 v175, v156, v4
	v_fmac_f32_e32 v175, v157, v5
	v_fmac_f32_e32 v175, v158, v6
	v_fmac_f32_e32 v175, v159, v7
	global_load_dwordx4 v[152:155], v31, s[4:5] offset:2048
	global_load_dwordx4 v[156:159], v31, s[4:5] offset:2064
	v_add_f32_dpp v160, v160, v160 row_ror:8 row_mask:0xf bank_mask:0x3
	v_add_f32_dpp v160, v168, v168 row_ror:8 row_mask:0xf bank_mask:0xc
	v_add_f32_dpp v161, v161, v161 row_ror:8 row_mask:0xf bank_mask:0x3
	v_add_f32_dpp v161, v169, v169 row_ror:8 row_mask:0xf bank_mask:0xc
	v_add_f32_dpp v162, v162, v162 row_ror:8 row_mask:0xf bank_mask:0x3
	v_add_f32_dpp v162, v170, v170 row_ror:8 row_mask:0xf bank_mask:0xc
	v_add_f32_dpp v163, v163, v163 row_ror:8 row_mask:0xf bank_mask:0x3
	v_add_f32_dpp v163, v171, v171 row_ror:8 row_mask:0xf bank_mask:0xc
	v_add_f32_dpp v164, v164, v164 row_ror:8 row_mask:0xf bank_mask:0x3
	v_add_f32_dpp v164, v172, v172 row_ror:8 row_mask:0xf bank_mask:0xc
	v_add_f32_dpp v165, v165, v165 row_ror:8 row_mask:0xf bank_mask:0x3
	v_add_f32_dpp v165, v173, v173 row_ror:8 row_mask:0xf bank_mask:0xc
	v_add_f32_dpp v166, v166, v166 row_ror:8 row_mask:0xf bank_mask:0x3
	v_add_f32_dpp v166, v174, v174 row_ror:8 row_mask:0xf bank_mask:0xc
	v_add_f32_dpp v167, v167, v167 row_ror:8 row_mask:0xf bank_mask:0x3
	v_add_f32_dpp v167, v175, v175 row_ror:8 row_mask:0xf bank_mask:0xc
	v_add_f32_dpp v160, v160, v160 row_shl:4 row_mask:0xf bank_mask:0x5
	v_add_f32_dpp v160, v164, v164 row_shr:4 row_mask:0xf bank_mask:0xa
	v_add_f32_dpp v161, v161, v161 row_shl:4 row_mask:0xf bank_mask:0x5
	v_add_f32_dpp v161, v165, v165 row_shr:4 row_mask:0xf bank_mask:0xa
	v_add_f32_dpp v162, v162, v162 row_shl:4 row_mask:0xf bank_mask:0x5
	v_add_f32_dpp v162, v166, v166 row_shr:4 row_mask:0xf bank_mask:0xa
	v_add_f32_dpp v163, v163, v163 row_shl:4 row_mask:0xf bank_mask:0x5
	v_add_f32_dpp v163, v167, v167 row_shr:4 row_mask:0xf bank_mask:0xa
	v_and_b32_e32 v176, 2, v18
	v_cmp_ne_u32_e32 vcc, 0, v176
	v_add_f32_dpp v230, v160, v160 quad_perm:[2,3,0,1] row_mask:0xf bank_mask:0xf
	v_add_f32_dpp v231, v162, v162 quad_perm:[2,3,0,1] row_mask:0xf bank_mask:0xf
	v_add_f32_dpp v232, v161, v161 quad_perm:[2,3,0,1] row_mask:0xf bank_mask:0xf
	v_add_f32_dpp v233, v163, v163 quad_perm:[2,3,0,1] row_mask:0xf bank_mask:0xf
	v_cndmask_b32_e32 v230, v230, v231, vcc
	v_cndmask_b32_e32 v232, v232, v233, vcc
	v_and_b32_e32 v176, 1, v18
	v_cmp_ne_u32_e32 vcc, 0, v176
	v_add_f32_dpp v231, v230, v230 quad_perm:[1,0,3,2] row_mask:0xf bank_mask:0xf
	v_add_f32_dpp v233, v232, v232 quad_perm:[1,0,3,2] row_mask:0xf bank_mask:0xf
	s_nop 1
	v_cndmask_b32_e32 v241, v231, v233, vcc
	s_nop 1
	v_max_f32_dpp v242, v241, v241 row_ror:8 row_mask:0xf bank_mask:0xf
	s_nop 1
	v_max_f32_dpp v242, v242, v242 row_ror:4 row_mask:0xf bank_mask:0xf
	s_nop 1
	v_max_f32_dpp v242, v242, v242 row_ror:2 row_mask:0xf bank_mask:0xf
	s_nop 1
	v_max_f32_dpp v242, v242, v242 row_ror:1 row_mask:0xf bank_mask:0xf
	ds_bpermute_b32 v234, v238, v242
	s_waitcnt lgkmcnt(0)
	v_max_f32_e32 v242, v242, v234
	ds_bpermute_b32 v234, v239, v242
	s_waitcnt lgkmcnt(0)
	v_max_f32_e32 v242, v242, v234
	v_max_f32_e32 v242, v16, v242
	v_sub_f32_e32 v243, v16, v242
	v_sub_f32_e32 v240, v241, v242
	v_mul_f32_e32 v243, 0x3fb8aa3b, v243
	v_mul_f32_e32 v240, 0x3fb8aa3b, v240
	v_exp_f32_e32 v243, v243
	v_exp_f32_e32 v240, v240
	v_mov_b32_e32 v16, v242
	s_nop 0
	s_nop 1
	v_add_f32_dpp v235, v240, v240 row_ror:8 row_mask:0xf bank_mask:0xf
	s_nop 1
	v_add_f32_dpp v235, v235, v235 row_ror:4 row_mask:0xf bank_mask:0xf
	s_nop 1
	v_add_f32_dpp v235, v235, v235 row_ror:2 row_mask:0xf bank_mask:0xf
	s_nop 1
	v_add_f32_dpp v235, v235, v235 row_ror:1 row_mask:0xf bank_mask:0xf
	ds_bpermute_b32 v234, v238, v235
	s_waitcnt lgkmcnt(0)
	v_add_f32_e32 v235, v235, v234
	ds_bpermute_b32 v234, v239, v235
	s_waitcnt lgkmcnt(0)
	v_add_f32_e32 v235, v235, v234
	v_fma_f32 v17, v17, v243, v235
	v_mul_f32_e32 v8, v8, v243
	v_mul_f32_e32 v9, v9, v243
	v_mul_f32_e32 v10, v10, v243
	v_mul_f32_e32 v11, v11, v243
	v_mul_f32_e32 v12, v12, v243
	v_mul_f32_e32 v13, v13, v243
	v_mul_f32_e32 v14, v14, v243
	v_mul_f32_e32 v15, v15, v243
	s_waitcnt vmcnt(30)
	v_fmac_f32_dpp v8, v240, v32 row_newbcast:0 row_mask:0xf bank_mask:0xf
	v_fmac_f32_dpp v9, v240, v33 row_newbcast:0 row_mask:0xf bank_mask:0xf
	v_fmac_f32_dpp v10, v240, v34 row_newbcast:0 row_mask:0xf bank_mask:0xf
	v_fmac_f32_dpp v11, v240, v35 row_newbcast:0 row_mask:0xf bank_mask:0xf
	v_fmac_f32_dpp v12, v240, v36 row_newbcast:0 row_mask:0xf bank_mask:0xf
	v_fmac_f32_dpp v13, v240, v37 row_newbcast:0 row_mask:0xf bank_mask:0xf
	v_fmac_f32_dpp v14, v240, v38 row_newbcast:0 row_mask:0xf bank_mask:0xf
	v_fmac_f32_dpp v15, v240, v39 row_newbcast:0 row_mask:0xf bank_mask:0xf
	s_waitcnt vmcnt(28)
	v_fmac_f32_dpp v8, v240, v40 row_newbcast:1 row_mask:0xf bank_mask:0xf
	v_fmac_f32_dpp v9, v240, v41 row_newbcast:1 row_mask:0xf bank_mask:0xf
	v_fmac_f32_dpp v10, v240, v42 row_newbcast:1 row_mask:0xf bank_mask:0xf
	v_fmac_f32_dpp v11, v240, v43 row_newbcast:1 row_mask:0xf bank_mask:0xf
	v_fmac_f32_dpp v12, v240, v44 row_newbcast:1 row_mask:0xf bank_mask:0xf
	v_fmac_f32_dpp v13, v240, v45 row_newbcast:1 row_mask:0xf bank_mask:0xf
	v_fmac_f32_dpp v14, v240, v46 row_newbcast:1 row_mask:0xf bank_mask:0xf
	v_fmac_f32_dpp v15, v240, v47 row_newbcast:1 row_mask:0xf bank_mask:0xf
	s_waitcnt vmcnt(26)
	v_fmac_f32_dpp v8, v240, v48 row_newbcast:2 row_mask:0xf bank_mask:0xf
	v_fmac_f32_dpp v9, v240, v49 row_newbcast:2 row_mask:0xf bank_mask:0xf
	v_fmac_f32_dpp v10, v240, v50 row_newbcast:2 row_mask:0xf bank_mask:0xf
	v_fmac_f32_dpp v11, v240, v51 row_newbcast:2 row_mask:0xf bank_mask:0xf
	v_fmac_f32_dpp v12, v240, v52 row_newbcast:2 row_mask:0xf bank_mask:0xf
	v_fmac_f32_dpp v13, v240, v53 row_newbcast:2 row_mask:0xf bank_mask:0xf
	v_fmac_f32_dpp v14, v240, v54 row_newbcast:2 row_mask:0xf bank_mask:0xf
	v_fmac_f32_dpp v15, v240, v55 row_newbcast:2 row_mask:0xf bank_mask:0xf
	s_waitcnt vmcnt(24)
	v_fmac_f32_dpp v8, v240, v56 row_newbcast:3 row_mask:0xf bank_mask:0xf
	v_fmac_f32_dpp v9, v240, v57 row_newbcast:3 row_mask:0xf bank_mask:0xf
	v_fmac_f32_dpp v10, v240, v58 row_newbcast:3 row_mask:0xf bank_mask:0xf
	v_fmac_f32_dpp v11, v240, v59 row_newbcast:3 row_mask:0xf bank_mask:0xf
	v_fmac_f32_dpp v12, v240, v60 row_newbcast:3 row_mask:0xf bank_mask:0xf
	v_fmac_f32_dpp v13, v240, v61 row_newbcast:3 row_mask:0xf bank_mask:0xf
	v_fmac_f32_dpp v14, v240, v62 row_newbcast:3 row_mask:0xf bank_mask:0xf
	v_fmac_f32_dpp v15, v240, v63 row_newbcast:3 row_mask:0xf bank_mask:0xf
	s_waitcnt vmcnt(22)
	v_fmac_f32_dpp v8, v240, v64 row_newbcast:4 row_mask:0xf bank_mask:0xf
	v_fmac_f32_dpp v9, v240, v65 row_newbcast:4 row_mask:0xf bank_mask:0xf
	v_fmac_f32_dpp v10, v240, v66 row_newbcast:4 row_mask:0xf bank_mask:0xf
	v_fmac_f32_dpp v11, v240, v67 row_newbcast:4 row_mask:0xf bank_mask:0xf
	v_fmac_f32_dpp v12, v240, v68 row_newbcast:4 row_mask:0xf bank_mask:0xf
	v_fmac_f32_dpp v13, v240, v69 row_newbcast:4 row_mask:0xf bank_mask:0xf
	v_fmac_f32_dpp v14, v240, v70 row_newbcast:4 row_mask:0xf bank_mask:0xf
	v_fmac_f32_dpp v15, v240, v71 row_newbcast:4 row_mask:0xf bank_mask:0xf
	s_waitcnt vmcnt(20)
	v_fmac_f32_dpp v8, v240, v72 row_newbcast:5 row_mask:0xf bank_mask:0xf
	v_fmac_f32_dpp v9, v240, v73 row_newbcast:5 row_mask:0xf bank_mask:0xf
	v_fmac_f32_dpp v10, v240, v74 row_newbcast:5 row_mask:0xf bank_mask:0xf
	v_fmac_f32_dpp v11, v240, v75 row_newbcast:5 row_mask:0xf bank_mask:0xf
	v_fmac_f32_dpp v12, v240, v76 row_newbcast:5 row_mask:0xf bank_mask:0xf
	v_fmac_f32_dpp v13, v240, v77 row_newbcast:5 row_mask:0xf bank_mask:0xf
	v_fmac_f32_dpp v14, v240, v78 row_newbcast:5 row_mask:0xf bank_mask:0xf
	v_fmac_f32_dpp v15, v240, v79 row_newbcast:5 row_mask:0xf bank_mask:0xf
	s_waitcnt vmcnt(18)
	v_fmac_f32_dpp v8, v240, v80 row_newbcast:6 row_mask:0xf bank_mask:0xf
	v_fmac_f32_dpp v9, v240, v81 row_newbcast:6 row_mask:0xf bank_mask:0xf
	v_fmac_f32_dpp v10, v240, v82 row_newbcast:6 row_mask:0xf bank_mask:0xf
	v_fmac_f32_dpp v11, v240, v83 row_newbcast:6 row_mask:0xf bank_mask:0xf
	v_fmac_f32_dpp v12, v240, v84 row_newbcast:6 row_mask:0xf bank_mask:0xf
	v_fmac_f32_dpp v13, v240, v85 row_newbcast:6 row_mask:0xf bank_mask:0xf
	v_fmac_f32_dpp v14, v240, v86 row_newbcast:6 row_mask:0xf bank_mask:0xf
	v_fmac_f32_dpp v15, v240, v87 row_newbcast:6 row_mask:0xf bank_mask:0xf
	s_waitcnt vmcnt(16)
	v_fmac_f32_dpp v8, v240, v88 row_newbcast:7 row_mask:0xf bank_mask:0xf
	v_fmac_f32_dpp v9, v240, v89 row_newbcast:7 row_mask:0xf bank_mask:0xf
	v_fmac_f32_dpp v10, v240, v90 row_newbcast:7 row_mask:0xf bank_mask:0xf
	v_fmac_f32_dpp v11, v240, v91 row_newbcast:7 row_mask:0xf bank_mask:0xf
	v_fmac_f32_dpp v12, v240, v92 row_newbcast:7 row_mask:0xf bank_mask:0xf
	v_fmac_f32_dpp v13, v240, v93 row_newbcast:7 row_mask:0xf bank_mask:0xf
	v_fmac_f32_dpp v14, v240, v94 row_newbcast:7 row_mask:0xf bank_mask:0xf
	v_fmac_f32_dpp v15, v240, v95 row_newbcast:7 row_mask:0xf bank_mask:0xf
	s_waitcnt vmcnt(14)
	v_fmac_f32_dpp v8, v240, v96 row_newbcast:8 row_mask:0xf bank_mask:0xf
	v_fmac_f32_dpp v9, v240, v97 row_newbcast:8 row_mask:0xf bank_mask:0xf
	v_fmac_f32_dpp v10, v240, v98 row_newbcast:8 row_mask:0xf bank_mask:0xf
	v_fmac_f32_dpp v11, v240, v99 row_newbcast:8 row_mask:0xf bank_mask:0xf
	v_fmac_f32_dpp v12, v240, v100 row_newbcast:8 row_mask:0xf bank_mask:0xf
	v_fmac_f32_dpp v13, v240, v101 row_newbcast:8 row_mask:0xf bank_mask:0xf
	v_fmac_f32_dpp v14, v240, v102 row_newbcast:8 row_mask:0xf bank_mask:0xf
	v_fmac_f32_dpp v15, v240, v103 row_newbcast:8 row_mask:0xf bank_mask:0xf
	s_waitcnt vmcnt(12)
	v_fmac_f32_dpp v8, v240, v104 row_newbcast:9 row_mask:0xf bank_mask:0xf
	v_fmac_f32_dpp v9, v240, v105 row_newbcast:9 row_mask:0xf bank_mask:0xf
	v_fmac_f32_dpp v10, v240, v106 row_newbcast:9 row_mask:0xf bank_mask:0xf
	v_fmac_f32_dpp v11, v240, v107 row_newbcast:9 row_mask:0xf bank_mask:0xf
	v_fmac_f32_dpp v12, v240, v108 row_newbcast:9 row_mask:0xf bank_mask:0xf
	v_fmac_f32_dpp v13, v240, v109 row_newbcast:9 row_mask:0xf bank_mask:0xf
	v_fmac_f32_dpp v14, v240, v110 row_newbcast:9 row_mask:0xf bank_mask:0xf
	v_fmac_f32_dpp v15, v240, v111 row_newbcast:9 row_mask:0xf bank_mask:0xf
	s_waitcnt vmcnt(10)
	v_fmac_f32_dpp v8, v240, v112 row_newbcast:10 row_mask:0xf bank_mask:0xf
	v_fmac_f32_dpp v9, v240, v113 row_newbcast:10 row_mask:0xf bank_mask:0xf
	v_fmac_f32_dpp v10, v240, v114 row_newbcast:10 row_mask:0xf bank_mask:0xf
	v_fmac_f32_dpp v11, v240, v115 row_newbcast:10 row_mask:0xf bank_mask:0xf
	v_fmac_f32_dpp v12, v240, v116 row_newbcast:10 row_mask:0xf bank_mask:0xf
	v_fmac_f32_dpp v13, v240, v117 row_newbcast:10 row_mask:0xf bank_mask:0xf
	v_fmac_f32_dpp v14, v240, v118 row_newbcast:10 row_mask:0xf bank_mask:0xf
	v_fmac_f32_dpp v15, v240, v119 row_newbcast:10 row_mask:0xf bank_mask:0xf
	s_waitcnt vmcnt(8)
	v_fmac_f32_dpp v8, v240, v120 row_newbcast:11 row_mask:0xf bank_mask:0xf
	v_fmac_f32_dpp v9, v240, v121 row_newbcast:11 row_mask:0xf bank_mask:0xf
	v_fmac_f32_dpp v10, v240, v122 row_newbcast:11 row_mask:0xf bank_mask:0xf
	v_fmac_f32_dpp v11, v240, v123 row_newbcast:11 row_mask:0xf bank_mask:0xf
	v_fmac_f32_dpp v12, v240, v124 row_newbcast:11 row_mask:0xf bank_mask:0xf
	v_fmac_f32_dpp v13, v240, v125 row_newbcast:11 row_mask:0xf bank_mask:0xf
	v_fmac_f32_dpp v14, v240, v126 row_newbcast:11 row_mask:0xf bank_mask:0xf
	v_fmac_f32_dpp v15, v240, v127 row_newbcast:11 row_mask:0xf bank_mask:0xf
	s_waitcnt vmcnt(6)
	v_fmac_f32_dpp v8, v240, v128 row_newbcast:12 row_mask:0xf bank_mask:0xf
	v_fmac_f32_dpp v9, v240, v129 row_newbcast:12 row_mask:0xf bank_mask:0xf
	v_fmac_f32_dpp v10, v240, v130 row_newbcast:12 row_mask:0xf bank_mask:0xf
	v_fmac_f32_dpp v11, v240, v131 row_newbcast:12 row_mask:0xf bank_mask:0xf
	v_fmac_f32_dpp v12, v240, v132 row_newbcast:12 row_mask:0xf bank_mask:0xf
	v_fmac_f32_dpp v13, v240, v133 row_newbcast:12 row_mask:0xf bank_mask:0xf
	v_fmac_f32_dpp v14, v240, v134 row_newbcast:12 row_mask:0xf bank_mask:0xf
	v_fmac_f32_dpp v15, v240, v135 row_newbcast:12 row_mask:0xf bank_mask:0xf
	s_waitcnt vmcnt(4)
	v_fmac_f32_dpp v8, v240, v136 row_newbcast:13 row_mask:0xf bank_mask:0xf
	v_fmac_f32_dpp v9, v240, v137 row_newbcast:13 row_mask:0xf bank_mask:0xf
	v_fmac_f32_dpp v10, v240, v138 row_newbcast:13 row_mask:0xf bank_mask:0xf
	v_fmac_f32_dpp v11, v240, v139 row_newbcast:13 row_mask:0xf bank_mask:0xf
	v_fmac_f32_dpp v12, v240, v140 row_newbcast:13 row_mask:0xf bank_mask:0xf
	v_fmac_f32_dpp v13, v240, v141 row_newbcast:13 row_mask:0xf bank_mask:0xf
	v_fmac_f32_dpp v14, v240, v142 row_newbcast:13 row_mask:0xf bank_mask:0xf
	v_fmac_f32_dpp v15, v240, v143 row_newbcast:13 row_mask:0xf bank_mask:0xf
	s_waitcnt vmcnt(2)
	v_fmac_f32_dpp v8, v240, v144 row_newbcast:14 row_mask:0xf bank_mask:0xf
	v_fmac_f32_dpp v9, v240, v145 row_newbcast:14 row_mask:0xf bank_mask:0xf
	v_fmac_f32_dpp v10, v240, v146 row_newbcast:14 row_mask:0xf bank_mask:0xf
	v_fmac_f32_dpp v11, v240, v147 row_newbcast:14 row_mask:0xf bank_mask:0xf
	v_fmac_f32_dpp v12, v240, v148 row_newbcast:14 row_mask:0xf bank_mask:0xf
	v_fmac_f32_dpp v13, v240, v149 row_newbcast:14 row_mask:0xf bank_mask:0xf
	v_fmac_f32_dpp v14, v240, v150 row_newbcast:14 row_mask:0xf bank_mask:0xf
	v_fmac_f32_dpp v15, v240, v151 row_newbcast:14 row_mask:0xf bank_mask:0xf
	s_waitcnt vmcnt(0)
	v_fmac_f32_dpp v8, v240, v152 row_newbcast:15 row_mask:0xf bank_mask:0xf
	v_fmac_f32_dpp v9, v240, v153 row_newbcast:15 row_mask:0xf bank_mask:0xf
	v_fmac_f32_dpp v10, v240, v154 row_newbcast:15 row_mask:0xf bank_mask:0xf
	v_fmac_f32_dpp v11, v240, v155 row_newbcast:15 row_mask:0xf bank_mask:0xf
	v_fmac_f32_dpp v12, v240, v156 row_newbcast:15 row_mask:0xf bank_mask:0xf
	v_fmac_f32_dpp v13, v240, v157 row_newbcast:15 row_mask:0xf bank_mask:0xf
	v_fmac_f32_dpp v14, v240, v158 row_newbcast:15 row_mask:0xf bank_mask:0xf
	v_fmac_f32_dpp v15, v240, v159 row_newbcast:15 row_mask:0xf bank_mask:0xf
	ds_bpermute_b32 v160, v238, v8
	ds_bpermute_b32 v161, v238, v9
	ds_bpermute_b32 v162, v238, v10
	ds_bpermute_b32 v163, v238, v11
	ds_bpermute_b32 v164, v238, v12
	ds_bpermute_b32 v165, v238, v13
	ds_bpermute_b32 v166, v238, v14
	ds_bpermute_b32 v167, v238, v15
	s_waitcnt lgkmcnt(0)
	v_add_f32_e32 v8, v8, v160
	v_add_f32_e32 v9, v9, v161
	v_add_f32_e32 v10, v10, v162
	v_add_f32_e32 v11, v11, v163
	v_add_f32_e32 v12, v12, v164
	v_add_f32_e32 v13, v13, v165
	v_add_f32_e32 v14, v14, v166
	v_add_f32_e32 v15, v15, v167
	ds_bpermute_b32 v160, v239, v8
	ds_bpermute_b32 v161, v239, v9
	ds_bpermute_b32 v162, v239, v10
	ds_bpermute_b32 v163, v239, v11
	ds_bpermute_b32 v164, v239, v12
	ds_bpermute_b32 v165, v239, v13
	ds_bpermute_b32 v166, v239, v14
	ds_bpermute_b32 v167, v239, v15
	s_waitcnt lgkmcnt(0)
	v_add_f32_e32 v8, v8, v160
	v_add_f32_e32 v9, v9, v161
	v_add_f32_e32 v10, v10, v162
	v_add_f32_e32 v11, v11, v163
	v_add_f32_e32 v12, v12, v164
	v_add_f32_e32 v13, v13, v165
	v_add_f32_e32 v14, v14, v166
	v_add_f32_e32 v15, v15, v167
	v_lshl_or_b32 v176, v20, 4, v18
	v_mul_u32_u24_e32 v176, 48, v176
	v_cmp_gt_u32_e32 vcc, 16, v18
	v_cmp_eq_u32_e64 s[6:7], 1, v21
	s_and_b64 s[6:7], s[6:7], vcc
	s_and_saveexec_b64 s[6:7], s[6:7]
	v_mov_b32_e32 v160, v16
	v_mov_b32_e32 v161, v17
	v_mov_b32_e32 v162, v8
	v_mov_b32_e32 v163, v9
	ds_write_b128 v176, v[160:163] offset:4096
	ds_write_b128 v176, v[10:13] offset:4112
	ds_write_b64 v176, v[14:15] offset:4128
	s_or_b64 exec, exec, s[6:7]
	s_waitcnt lgkmcnt(0)
	s_barrier
	v_cmp_gt_u32_e32 vcc, 16, v18
	v_cmp_eq_u32_e64 s[6:7], 0, v21
	s_and_b64 s[6:7], s[6:7], vcc
	s_and_saveexec_b64 s[6:7], s[6:7]
	s_cbranch_execz .Lsm0_mdone1
	global_load_dwordx4 v[172:175], v[244:245], off
	ds_read_b128 v[160:163], v176 offset:4096
	ds_read_b128 v[164:167], v176 offset:4112
	ds_read_b64 v[168:169], v176 offset:4128
	s_waitcnt lgkmcnt(0)
	v_max_f32_e32 v230, v16, v160
	v_sub_f32_e32 v231, v16, v230
	v_sub_f32_e32 v232, v160, v230
	v_mul_f32_e32 v231, 0x3fb8aa3b, v231
	v_mul_f32_e32 v232, 0x3fb8aa3b, v232
	v_exp_f32_e32 v231, v231
	v_exp_f32_e32 v232, v232
	s_nop 0
	v_mul_f32_e32 v233, v232, v161
	v_fmac_f32_e32 v233, v231, v17
	v_div_scale_f32 v234, s[8:9], v233, v233, 1.0
	v_rcp_f32_e32 v235, v234
	s_nop 0
	v_fma_f32 v236, -v234, v235, 1.0
	v_fmac_f32_e32 v235, v236, v235
	v_div_scale_f32 v236, vcc, 1.0, v233, 1.0
	v_mul_f32_e32 v237, v236, v235
	v_fma_f32 v176, -v234, v237, v236
	v_fmac_f32_e32 v237, v176, v235
	v_fma_f32 v234, -v234, v237, v236
	s_nop 0
	v_div_fmas_f32 v234, v234, v235, v237
	v_div_fixup_f32 v233, v234, v233, 1.0
	v_mul_f32_e32 v162, v232, v162
	v_fmac_f32_e32 v162, v231, v8
	v_mul_f32_e32 v162, v162, v233
	v_mul_f32_e32 v163, v232, v163
	v_fmac_f32_e32 v163, v231, v9
	v_mul_f32_e32 v163, v163, v233
	v_mul_f32_e32 v164, v232, v164
	v_fmac_f32_e32 v164, v231, v10
	v_mul_f32_e32 v164, v164, v233
	v_mul_f32_e32 v165, v232, v165
	v_fmac_f32_e32 v165, v231, v11
	v_mul_f32_e32 v165, v165, v233
	v_mul_f32_e32 v166, v232, v166
	v_fmac_f32_e32 v166, v231, v12
	v_mul_f32_e32 v166, v166, v233
	v_mul_f32_e32 v167, v232, v167
	v_fmac_f32_e32 v167, v231, v13
	v_mul_f32_e32 v167, v167, v233
	v_mul_f32_e32 v168, v232, v168
	v_fmac_f32_e32 v168, v231, v14
	v_mul_f32_e32 v168, v168, v233
	v_mul_f32_e32 v169, v232, v169
	v_fmac_f32_e32 v169, v231, v15
	v_mul_f32_e32 v169, v169, v233
	s_waitcnt vmcnt(0)
	v_lshlrev_b32_e32 v230, 16, v172
	v_and_b32_e32 v231, 0xffff0000, v172
	v_mul_f32_e32 v236, 0xbfb8aa3b, v230
	v_mul_f32_e32 v237, 0xbfb8aa3b, v231
	v_exp_f32_e32 v236, v236
	v_exp_f32_e32 v237, v237
	s_nop 0
	v_add_f32_e32 v236, 1.0, v236
	v_add_f32_e32 v237, 1.0, v237
	v_rcp_f32_e32 v236, v236
	v_rcp_f32_e32 v237, v237
	s_nop 0
	v_mul_f32_e32 v230, v230, v236
	v_mul_f32_e32 v231, v231, v237
	v_mul_f32_e32 v162, v162, v230
	v_mul_f32_e32 v163, v163, v231
	v_cvt_pk_bf16_f32 v172, v162, v163
	v_lshlrev_b32_e32 v230, 16, v173
	v_and_b32_e32 v231, 0xffff0000, v173
	v_mul_f32_e32 v236, 0xbfb8aa3b, v230
	v_mul_f32_e32 v237, 0xbfb8aa3b, v231
	v_exp_f32_e32 v236, v236
	v_exp_f32_e32 v237, v237
	s_nop 0
	v_add_f32_e32 v236, 1.0, v236
	v_add_f32_e32 v237, 1.0, v237
	v_rcp_f32_e32 v236, v236
	v_rcp_f32_e32 v237, v237
	s_nop 0
	v_mul_f32_e32 v230, v230, v236
	v_mul_f32_e32 v231, v231, v237
	v_mul_f32_e32 v164, v164, v230
	v_mul_f32_e32 v165, v165, v231
	v_cvt_pk_bf16_f32 v173, v164, v165
	v_lshlrev_b32_e32 v230, 16, v174
	v_and_b32_e32 v231, 0xffff0000, v174
	v_mul_f32_e32 v236, 0xbfb8aa3b, v230
	v_mul_f32_e32 v237, 0xbfb8aa3b, v231
	v_exp_f32_e32 v236, v236
	v_exp_f32_e32 v237, v237
	s_nop 0
	v_add_f32_e32 v236, 1.0, v236
	v_add_f32_e32 v237, 1.0, v237
	v_rcp_f32_e32 v236, v236
	v_rcp_f32_e32 v237, v237
	s_nop 0
	v_mul_f32_e32 v230, v230, v236
	v_mul_f32_e32 v231, v231, v237
	v_mul_f32_e32 v166, v166, v230
	v_mul_f32_e32 v167, v167, v231
	v_cvt_pk_bf16_f32 v174, v166, v167
	v_lshlrev_b32_e32 v230, 16, v175
	v_and_b32_e32 v231, 0xffff0000, v175
	v_mul_f32_e32 v236, 0xbfb8aa3b, v230
	v_mul_f32_e32 v237, 0xbfb8aa3b, v231
	v_exp_f32_e32 v236, v236
	v_exp_f32_e32 v237, v237
	s_nop 0
	v_add_f32_e32 v236, 1.0, v236
	v_add_f32_e32 v237, 1.0, v237
	v_rcp_f32_e32 v236, v236
	v_rcp_f32_e32 v237, v237
	s_nop 0
	v_mul_f32_e32 v230, v230, v236
	v_mul_f32_e32 v231, v231, v237
	v_mul_f32_e32 v168, v168, v230
	v_mul_f32_e32 v169, v169, v231
	v_cvt_pk_bf16_f32 v175, v168, v169
	global_store_dwordx4 v[246:247], v[172:175], off
.Lsm0_mdone1:
	s_or_b64 exec, exec, s[6:7]
	s_mov_b64 s[2:3], 0
	s_barrier
.LBB0_696:
	s_and_b64 vcc, exec, s[2:3]
	s_cbranch_vccz .LBB0_708
	v_and_b32_e32 v18, 63, v208
	v_lshrrev_b32_e32 v19, 6, v208
	v_and_b32_e32 v20, 3, v19
	v_lshrrev_b32_e32 v21, 2, v19
	v_and_b32_e32 v22, 15, v18
	v_lshrrev_b32_e32 v23, 4, v18
	v_lshlrev_b32_e32 v176, 2, v18
	v_xor_b32_e32 v238, 64, v176
	v_xor_b32_e32 v239, 0x80, v176
	s_add_i32 s2, s56, 0xfffff980
	s_lshr_b32 s6, s2, 3
	s_and_b32 s7, s56, 7
	v_readfirstlane_b32 s10, v20
	v_readfirstlane_b32 s11, v21
	s_lshl_b32 s8, s6, 2
	v_add_u32_e32 v230, s8, v20
	v_or_b32_e32 v230, 0x2000, v230
	v_mul_u32_u24_e32 v231, 0x5800, v230
	s_lshl_b32 s9, s7, 8
	v_and_b32_e32 v232, 1, v22
	v_lshlrev_b32_e32 v232, 5, v232
	v_lshlrev_b32_e32 v233, 4, v22
	v_cmp_gt_u32_e32 vcc, 4, v22
	s_nop 1
	v_cndmask_b32_e32 v232, v233, v232, vcc
	v_add3_u32 v232, v232, v231, s9
	v_add_u32_e32 v232, 0x3000, v232
	global_load_dwordx4 v[160:163], v232, s[0:1]
	global_load_dwordx4 v[164:167], v232, s[0:1] offset:16
	s_lshl_b32 s12, s6, 23
	s_lshl_b32 s13, s7, 9
	s_add_u32 s12, s12, s13
	s_add_u32 s16, s66, s12
	s_addc_u32 s17, s67, 0
	s_add_u32 s18, s68, s12
	s_addc_u32 s19, s69, 0
	s_lshl_b32 s12, s6, 14
	s_add_u32 s12, s12, s13
	s_add_u32 s20, s74, s12
	s_addc_u32 s21, s75, 0
	s_add_u32 s22, s90, s12
	s_addc_u32 s23, s91, 0
	s_mul_i32 s27, s11, 3
	v_mov_b32_e32 v16, v206
	v_mov_b32_e32 v17, 0
	v_mov_b32_e32 v8, 0
	v_mov_b32_e32 v9, 0
	v_mov_b32_e32 v10, 0
	v_mov_b32_e32 v11, 0
	v_mov_b32_e32 v12, 0
	v_mov_b32_e32 v13, 0
	v_mov_b32_e32 v14, 0
	v_mov_b32_e32 v15, 0
	s_lshl_b32 s24, s27, 6
	s_lshr_b32 s28, s24, 7
	s_and_b32 s24, s24, 64
	s_lshl_b32 s28, s28, 1
	s_add_u32 s28, s28, 12
	s_lshl_b32 s25, 1, s28
	s_add_u32 s24, s24, 64
	s_lshl_b32 s24, s24, s28
	s_add_u32 s26, s10, 0x800
	s_lshl_b32 s26, s26, 12
	s_sub_u32 s26, s26, s24
	s_add_u32 s2, s16, s26
	s_addc_u32 s3, s17, 0
	s_add_u32 s4, s18, s26
	s_addc_u32 s5, s19, 0
	v_lshlrev_b32_e32 v24, 4, v23
	v_sub_u32_e32 v24, 63, v24
	v_lshlrev_b32_e32 v24, s28, v24
	v_lshl_add_u32 v24, v22, 5, v24
	v_subrev_u32_e32 v25, s25, v24
	v_subrev_u32_e32 v26, s25, v25
	v_subrev_u32_e32 v27, s25, v26
	v_subrev_u32_e32 v28, s25, v27
	v_subrev_u32_e32 v29, s25, v28
	v_subrev_u32_e32 v30, s25, v29
	v_subrev_u32_e32 v31, s25, v30
	v_subrev_u32_e32 v244, s25, v31
	v_subrev_u32_e32 v245, s25, v244
	v_subrev_u32_e32 v246, s25, v245
	v_subrev_u32_e32 v247, s25, v246
	v_subrev_u32_e32 v248, s25, v247
	v_subrev_u32_e32 v249, s25, v248
	v_subrev_u32_e32 v250, s25, v249
	v_subrev_u32_e32 v251, s25, v250
	s_cmp_lg_u32 s11, 0
	s_cbranch_scc1 .Lsd_n1
	s_cmp_lt_u32 s10, 1
	s_cbranch_scc1 .Lsd_n1
	v_mov_b32_e32 v237, 0
	v_mov_b32_e32 v236, v24
	v_lshl_add_u64 v[230:231], s[2:3], 0, v[236:237]
	s_sub_u32 s29, s10, 1
	s_lshl_b32 s29, s29, 12
	v_lshlrev_b32_e32 v236, 5, v22
	v_add_u32_e32 v236, s29, v236
	v_lshl_add_u64 v[232:233], s[20:21], 0, v[236:237]
	v_cmp_eq_u32_e32 vcc, 0, v23
	s_nop 1
	v_cndmask_b32_e32 v230, v230, v232, vcc
	v_cndmask_b32_e32 v231, v231, v233, vcc
	global_load_dwordx4 v[32:35], v[230:231], off
	global_load_dwordx4 v[36:39], v[230:231], off offset:16
	s_branch .Lsd_d2
.Lsd_n1:
	global_load_dwordx4 v[32:35], v24, s[2:3]
	global_load_dwordx4 v[36:39], v24, s[2:3] offset:16
.Lsd_d2:
	s_cmp_lg_u32 s11, 0
	s_cbranch_scc1 .Lsd_n3
	s_cmp_lt_u32 s10, 2
	s_cbranch_scc1 .Lsd_n3
	v_mov_b32_e32 v237, 0
	v_mov_b32_e32 v236, v25
	v_lshl_add_u64 v[230:231], s[2:3], 0, v[236:237]
	s_sub_u32 s29, s10, 2
	s_lshl_b32 s29, s29, 12
	v_lshlrev_b32_e32 v236, 5, v22
	v_add_u32_e32 v236, s29, v236
	v_lshl_add_u64 v[232:233], s[20:21], 0, v[236:237]
	v_cmp_eq_u32_e32 vcc, 0, v23
	s_nop 1
	v_cndmask_b32_e32 v230, v230, v232, vcc
	v_cndmask_b32_e32 v231, v231, v233, vcc
	global_load_dwordx4 v[40:43], v[230:231], off
	global_load_dwordx4 v[44:47], v[230:231], off offset:16
	s_branch .Lsd_d4
.Lsd_n3:
	global_load_dwordx4 v[40:43], v25, s[2:3]
	global_load_dwordx4 v[44:47], v25, s[2:3] offset:16
.Lsd_d4:
	s_cmp_lg_u32 s11, 0
	s_cbranch_scc1 .Lsd_n5
	s_cmp_lt_u32 s10, 3
	s_cbranch_scc1 .Lsd_n5
	v_mov_b32_e32 v237, 0
	v_mov_b32_e32 v236, v26
	v_lshl_add_u64 v[230:231], s[2:3], 0, v[236:237]
	s_sub_u32 s29, s10, 3
	s_lshl_b32 s29, s29, 12
	v_lshlrev_b32_e32 v236, 5, v22
	v_add_u32_e32 v236, s29, v236
	v_lshl_add_u64 v[232:233], s[20:21], 0, v[236:237]
	v_cmp_eq_u32_e32 vcc, 0, v23
	s_nop 1
	v_cndmask_b32_e32 v230, v230, v232, vcc
	v_cndmask_b32_e32 v231, v231, v233, vcc
	global_load_dwordx4 v[48:51], v[230:231], off
	global_load_dwordx4 v[52:55], v[230:231], off offset:16
	s_branch .Lsd_d6
.Lsd_n5:
	global_load_dwordx4 v[48:51], v26, s[2:3]
	global_load_dwordx4 v[52:55], v26, s[2:3] offset:16
.Lsd_d6:
	global_load_dwordx4 v[56:59], v27, s[2:3]
	global_load_dwordx4 v[60:63], v27, s[2:3] offset:16
	global_load_dwordx4 v[64:67], v28, s[2:3]
	global_load_dwordx4 v[68:71], v28, s[2:3] offset:16
	global_load_dwordx4 v[72:75], v29, s[2:3]
	global_load_dwordx4 v[76:79], v29, s[2:3] offset:16
	global_load_dwordx4 v[80:83], v30, s[2:3]
	global_load_dwordx4 v[84:87], v30, s[2:3] offset:16
	global_load_dwordx4 v[88:91], v31, s[2:3]
	global_load_dwordx4 v[92:95], v31, s[2:3] offset:16
	global_load_dwordx4 v[96:99], v244, s[2:3]
	global_load_dwordx4 v[100:103], v244, s[2:3] offset:16
	global_load_dwordx4 v[104:107], v245, s[2:3]
	global_load_dwordx4 v[108:111], v245, s[2:3] offset:16
	global_load_dwordx4 v[112:115], v246, s[2:3]
	global_load_dwordx4 v[116:119], v246, s[2:3] offset:16
	global_load_dwordx4 v[120:123], v247, s[2:3]
	global_load_dwordx4 v[124:127], v247, s[2:3] offset:16
	global_load_dwordx4 v[128:131], v248, s[2:3]
	global_load_dwordx4 v[132:135], v248, s[2:3] offset:16
	global_load_dwordx4 v[136:139], v249, s[2:3]
	global_load_dwordx4 v[140:143], v249, s[2:3] offset:16
	global_load_dwordx4 v[144:147], v250, s[2:3]
	global_load_dwordx4 v[148:151], v250, s[2:3] offset:16
	global_load_dwordx4 v[152:155], v251, s[2:3]
	global_load_dwordx4 v[156:159], v251, s[2:3] offset:16
	s_waitcnt vmcnt(32)
	v_and_b32_e32 v176, 2, v22
	v_cmp_ne_u32_e32 vcc, 0, v176
	v_cmp_gt_u32_e64 s[30:31], 4, v22
	v_lshlrev_b32_e32 v236, 16, v160
	v_and_b32_e32 v237, 0xffff0000, v160
	v_cndmask_b32_e32 v236, v236, v237, vcc
	v_lshlrev_b32_e32 v237, 16, v160
	v_cndmask_b32_e64 v0, v237, v236, s[30:31]
	v_lshlrev_b32_e32 v236, 16, v161
	v_and_b32_e32 v237, 0xffff0000, v161
	v_cndmask_b32_e32 v236, v236, v237, vcc
	v_and_b32_e32 v237, 0xffff0000, v160
	v_cndmask_b32_e64 v1, v237, v236, s[30:31]
	v_lshlrev_b32_e32 v236, 16, v162
	v_and_b32_e32 v237, 0xffff0000, v162
	v_cndmask_b32_e32 v236, v236, v237, vcc
	v_lshlrev_b32_e32 v237, 16, v161
	v_cndmask_b32_e64 v2, v237, v236, s[30:31]
	v_lshlrev_b32_e32 v236, 16, v163
	v_and_b32_e32 v237, 0xffff0000, v163
	v_cndmask_b32_e32 v236, v236, v237, vcc
	v_and_b32_e32 v237, 0xffff0000, v161
	v_cndmask_b32_e64 v3, v237, v236, s[30:31]
	v_lshlrev_b32_e32 v236, 16, v164
	v_and_b32_e32 v237, 0xffff0000, v164
	v_cndmask_b32_e32 v236, v236, v237, vcc
	v_lshlrev_b32_e32 v237, 16, v162
	v_cndmask_b32_e64 v4, v237, v236, s[30:31]
	v_lshlrev_b32_e32 v236, 16, v165
	v_and_b32_e32 v237, 0xffff0000, v165
	v_cndmask_b32_e32 v236, v236, v237, vcc
	v_and_b32_e32 v237, 0xffff0000, v162
	v_cndmask_b32_e64 v5, v237, v236, s[30:31]
	v_lshlrev_b32_e32 v236, 16, v166
	v_and_b32_e32 v237, 0xffff0000, v166
	v_cndmask_b32_e32 v236, v236, v237, vcc
	v_lshlrev_b32_e32 v237, 16, v163
	v_cndmask_b32_e64 v6, v237, v236, s[30:31]
	v_lshlrev_b32_e32 v236, 16, v167
	v_and_b32_e32 v237, 0xffff0000, v167
	v_cndmask_b32_e32 v236, v236, v237, vcc
	v_and_b32_e32 v237, 0xffff0000, v163
	v_cndmask_b32_e64 v7, v237, v236, s[30:31]
	s_waitcnt vmcnt(30)
	v_mul_f32_e32 v160, v32, v0
	v_fmac_f32_e32 v160, v33, v1
	v_fmac_f32_e32 v160, v34, v2
	v_fmac_f32_e32 v160, v35, v3
	v_fmac_f32_e32 v160, v36, v4
	v_fmac_f32_e32 v160, v37, v5
	v_fmac_f32_e32 v160, v38, v6
	v_fmac_f32_e32 v160, v39, v7
	s_cmp_lg_u32 s11, 0
	s_cbranch_scc1 .Lsd_n7
	s_cmp_lt_u32 s10, 1
	s_cbranch_scc1 .Lsd_n7
	v_mov_b32_e32 v237, 0
	v_mov_b32_e32 v236, v24
	v_lshl_add_u64 v[230:231], s[4:5], 0, v[236:237]
	s_sub_u32 s29, s10, 1
	s_lshl_b32 s29, s29, 12
	v_lshlrev_b32_e32 v236, 5, v22
	v_add_u32_e32 v236, s29, v236
	v_lshl_add_u64 v[232:233], s[22:23], 0, v[236:237]
	v_cmp_eq_u32_e32 vcc, 0, v23
	s_nop 1
	v_cndmask_b32_e32 v230, v230, v232, vcc
	v_cndmask_b32_e32 v231, v231, v233, vcc
	global_load_dwordx4 v[32:35], v[230:231], off
	global_load_dwordx4 v[36:39], v[230:231], off offset:16
	s_branch .Lsd_d8
.Lsd_n7:
	global_load_dwordx4 v[32:35], v24, s[4:5]
	global_load_dwordx4 v[36:39], v24, s[4:5] offset:16
.Lsd_d8:
	s_waitcnt vmcnt(30)
	v_mul_f32_e32 v161, v40, v0
	v_fmac_f32_e32 v161, v41, v1
	v_fmac_f32_e32 v161, v42, v2
	v_fmac_f32_e32 v161, v43, v3
	v_fmac_f32_e32 v161, v44, v4
	v_fmac_f32_e32 v161, v45, v5
	v_fmac_f32_e32 v161, v46, v6
	v_fmac_f32_e32 v161, v47, v7
	s_cmp_lg_u32 s11, 0
	s_cbranch_scc1 .Lsd_n9
	s_cmp_lt_u32 s10, 2
	s_cbranch_scc1 .Lsd_n9
	v_mov_b32_e32 v237, 0
	v_mov_b32_e32 v236, v25
	v_lshl_add_u64 v[230:231], s[4:5], 0, v[236:237]
	s_sub_u32 s29, s10, 2
	s_lshl_b32 s29, s29, 12
	v_lshlrev_b32_e32 v236, 5, v22
	v_add_u32_e32 v236, s29, v236
	v_lshl_add_u64 v[232:233], s[22:23], 0, v[236:237]
	v_cmp_eq_u32_e32 vcc, 0, v23
	s_nop 1
	v_cndmask_b32_e32 v230, v230, v232, vcc
	v_cndmask_b32_e32 v231, v231, v233, vcc
	global_load_dwordx4 v[40:43], v[230:231], off
	global_load_dwordx4 v[44:47], v[230:231], off offset:16
	s_branch .Lsd_d10
.Lsd_n9:
	global_load_dwordx4 v[40:43], v25, s[4:5]
	global_load_dwordx4 v[44:47], v25, s[4:5] offset:16
.Lsd_d10:
	s_waitcnt vmcnt(30)
	v_mul_f32_e32 v162, v48, v0
	v_fmac_f32_e32 v162, v49, v1
	v_fmac_f32_e32 v162, v50, v2
	v_fmac_f32_e32 v162, v51, v3
	v_fmac_f32_e32 v162, v52, v4
	v_fmac_f32_e32 v162, v53, v5
	v_fmac_f32_e32 v162, v54, v6
	v_fmac_f32_e32 v162, v55, v7
	s_cmp_lg_u32 s11, 0
	s_cbranch_scc1 .Lsd_n11
	s_cmp_lt_u32 s10, 3
	s_cbranch_scc1 .Lsd_n11
	v_mov_b32_e32 v237, 0
	v_mov_b32_e32 v236, v26
	v_lshl_add_u64 v[230:231], s[4:5], 0, v[236:237]
	s_sub_u32 s29, s10, 3
	s_lshl_b32 s29, s29, 12
	v_lshlrev_b32_e32 v236, 5, v22
	v_add_u32_e32 v236, s29, v236
	v_lshl_add_u64 v[232:233], s[22:23], 0, v[236:237]
	v_cmp_eq_u32_e32 vcc, 0, v23
	s_nop 1
	v_cndmask_b32_e32 v230, v230, v232, vcc
	v_cndmask_b32_e32 v231, v231, v233, vcc
	global_load_dwordx4 v[48:51], v[230:231], off
	global_load_dwordx4 v[52:55], v[230:231], off offset:16
	s_branch .Lsd_d12
.Lsd_n11:
	global_load_dwordx4 v[48:51], v26, s[4:5]
	global_load_dwordx4 v[52:55], v26, s[4:5] offset:16
.Lsd_d12:
	s_waitcnt vmcnt(30)
	v_mul_f32_e32 v163, v56, v0
	v_fmac_f32_e32 v163, v57, v1
	v_fmac_f32_e32 v163, v58, v2
	v_fmac_f32_e32 v163, v59, v3
	v_fmac_f32_e32 v163, v60, v4
	v_fmac_f32_e32 v163, v61, v5
	v_fmac_f32_e32 v163, v62, v6
	v_fmac_f32_e32 v163, v63, v7
	global_load_dwordx4 v[56:59], v27, s[4:5]
	global_load_dwordx4 v[60:63], v27, s[4:5] offset:16
	s_waitcnt vmcnt(30)
	v_mul_f32_e32 v164, v64, v0
	v_fmac_f32_e32 v164, v65, v1
	v_fmac_f32_e32 v164, v66, v2
	v_fmac_f32_e32 v164, v67, v3
	v_fmac_f32_e32 v164, v68, v4
	v_fmac_f32_e32 v164, v69, v5
	v_fmac_f32_e32 v164, v70, v6
	v_fmac_f32_e32 v164, v71, v7
	global_load_dwordx4 v[64:67], v28, s[4:5]
	global_load_dwordx4 v[68:71], v28, s[4:5] offset:16
	s_waitcnt vmcnt(30)
	v_mul_f32_e32 v165, v72, v0
	v_fmac_f32_e32 v165, v73, v1
	v_fmac_f32_e32 v165, v74, v2
	v_fmac_f32_e32 v165, v75, v3
	v_fmac_f32_e32 v165, v76, v4
	v_fmac_f32_e32 v165, v77, v5
	v_fmac_f32_e32 v165, v78, v6
	v_fmac_f32_e32 v165, v79, v7
	global_load_dwordx4 v[72:75], v29, s[4:5]
	global_load_dwordx4 v[76:79], v29, s[4:5] offset:16
	s_waitcnt vmcnt(30)
	v_mul_f32_e32 v166, v80, v0
	v_fmac_f32_e32 v166, v81, v1
	v_fmac_f32_e32 v166, v82, v2
	v_fmac_f32_e32 v166, v83, v3
	v_fmac_f32_e32 v166, v84, v4
	v_fmac_f32_e32 v166, v85, v5
	v_fmac_f32_e32 v166, v86, v6
	v_fmac_f32_e32 v166, v87, v7
	global_load_dwordx4 v[80:83], v30, s[4:5]
	global_load_dwordx4 v[84:87], v30, s[4:5] offset:16
	s_waitcnt vmcnt(30)
	v_mul_f32_e32 v167, v88, v0
	v_fmac_f32_e32 v167, v89, v1
	v_fmac_f32_e32 v167, v90, v2
	v_fmac_f32_e32 v167, v91, v3
	v_fmac_f32_e32 v167, v92, v4
	v_fmac_f32_e32 v167, v93, v5
	v_fmac_f32_e32 v167, v94, v6
	v_fmac_f32_e32 v167, v95, v7
	global_load_dwordx4 v[88:91], v31, s[4:5]
	global_load_dwordx4 v[92:95], v31, s[4:5] offset:16
	s_waitcnt vmcnt(30)
	v_mul_f32_e32 v168, v96, v0
	v_fmac_f32_e32 v168, v97, v1
	v_fmac_f32_e32 v168, v98, v2
	v_fmac_f32_e32 v168, v99, v3
	v_fmac_f32_e32 v168, v100, v4
	v_fmac_f32_e32 v168, v101, v5
	v_fmac_f32_e32 v168, v102, v6
	v_fmac_f32_e32 v168, v103, v7
	global_load_dwordx4 v[96:99], v244, s[4:5]
	global_load_dwordx4 v[100:103], v244, s[4:5] offset:16
	s_waitcnt vmcnt(30)
	v_mul_f32_e32 v169, v104, v0
	v_fmac_f32_e32 v169, v105, v1
	v_fmac_f32_e32 v169, v106, v2
	v_fmac_f32_e32 v169, v107, v3
	v_fmac_f32_e32 v169, v108, v4
	v_fmac_f32_e32 v169, v109, v5
	v_fmac_f32_e32 v169, v110, v6
	v_fmac_f32_e32 v169, v111, v7
	global_load_dwordx4 v[104:107], v245, s[4:5]
	global_load_dwordx4 v[108:111], v245, s[4:5] offset:16
	s_waitcnt vmcnt(30)
	v_mul_f32_e32 v170, v112, v0
	v_fmac_f32_e32 v170, v113, v1
	v_fmac_f32_e32 v170, v114, v2
	v_fmac_f32_e32 v170, v115, v3
	v_fmac_f32_e32 v170, v116, v4
	v_fmac_f32_e32 v170, v117, v5
	v_fmac_f32_e32 v170, v118, v6
	v_fmac_f32_e32 v170, v119, v7
	global_load_dwordx4 v[112:115], v246, s[4:5]
	global_load_dwordx4 v[116:119], v246, s[4:5] offset:16
	s_waitcnt vmcnt(30)
	v_mul_f32_e32 v171, v120, v0
	v_fmac_f32_e32 v171, v121, v1
	v_fmac_f32_e32 v171, v122, v2
	v_fmac_f32_e32 v171, v123, v3
	v_fmac_f32_e32 v171, v124, v4
	v_fmac_f32_e32 v171, v125, v5
	v_fmac_f32_e32 v171, v126, v6
	v_fmac_f32_e32 v171, v127, v7
	global_load_dwordx4 v[120:123], v247, s[4:5]
	global_load_dwordx4 v[124:127], v247, s[4:5] offset:16
	s_waitcnt vmcnt(30)
	v_mul_f32_e32 v172, v128, v0
	v_fmac_f32_e32 v172, v129, v1
	v_fmac_f32_e32 v172, v130, v2
	v_fmac_f32_e32 v172, v131, v3
	v_fmac_f32_e32 v172, v132, v4
	v_fmac_f32_e32 v172, v133, v5
	v_fmac_f32_e32 v172, v134, v6
	v_fmac_f32_e32 v172, v135, v7
	global_load_dwordx4 v[128:131], v248, s[4:5]
	global_load_dwordx4 v[132:135], v248, s[4:5] offset:16
	s_waitcnt vmcnt(30)
	v_mul_f32_e32 v173, v136, v0
	v_fmac_f32_e32 v173, v137, v1
	v_fmac_f32_e32 v173, v138, v2
	v_fmac_f32_e32 v173, v139, v3
	v_fmac_f32_e32 v173, v140, v4
	v_fmac_f32_e32 v173, v141, v5
	v_fmac_f32_e32 v173, v142, v6
	v_fmac_f32_e32 v173, v143, v7
	global_load_dwordx4 v[136:139], v249, s[4:5]
	global_load_dwordx4 v[140:143], v249, s[4:5] offset:16
	s_waitcnt vmcnt(30)
	v_mul_f32_e32 v174, v144, v0
	v_fmac_f32_e32 v174, v145, v1
	v_fmac_f32_e32 v174, v146, v2
	v_fmac_f32_e32 v174, v147, v3
	v_fmac_f32_e32 v174, v148, v4
	v_fmac_f32_e32 v174, v149, v5
	v_fmac_f32_e32 v174, v150, v6
	v_fmac_f32_e32 v174, v151, v7
	global_load_dwordx4 v[144:147], v250, s[4:5]
	global_load_dwordx4 v[148:151], v250, s[4:5] offset:16
	s_waitcnt vmcnt(30)
	v_mul_f32_e32 v175, v152, v0
	v_fmac_f32_e32 v175, v153, v1
	v_fmac_f32_e32 v175, v154, v2
	v_fmac_f32_e32 v175, v155, v3
	v_fmac_f32_e32 v175, v156, v4
	v_fmac_f32_e32 v175, v157, v5
	v_fmac_f32_e32 v175, v158, v6
	v_fmac_f32_e32 v175, v159, v7
	global_load_dwordx4 v[152:155], v251, s[4:5]
	global_load_dwordx4 v[156:159], v251, s[4:5] offset:16
	v_add_f32_dpp v160, v160, v160 row_ror:8 row_mask:0xf bank_mask:0x3
	v_add_f32_dpp v160, v168, v168 row_ror:8 row_mask:0xf bank_mask:0xc
	v_add_f32_dpp v161, v161, v161 row_ror:8 row_mask:0xf bank_mask:0x3
	v_add_f32_dpp v161, v169, v169 row_ror:8 row_mask:0xf bank_mask:0xc
	v_add_f32_dpp v162, v162, v162 row_ror:8 row_mask:0xf bank_mask:0x3
	v_add_f32_dpp v162, v170, v170 row_ror:8 row_mask:0xf bank_mask:0xc
	v_add_f32_dpp v163, v163, v163 row_ror:8 row_mask:0xf bank_mask:0x3
	v_add_f32_dpp v163, v171, v171 row_ror:8 row_mask:0xf bank_mask:0xc
	v_add_f32_dpp v164, v164, v164 row_ror:8 row_mask:0xf bank_mask:0x3
	v_add_f32_dpp v164, v172, v172 row_ror:8 row_mask:0xf bank_mask:0xc
	v_add_f32_dpp v165, v165, v165 row_ror:8 row_mask:0xf bank_mask:0x3
	v_add_f32_dpp v165, v173, v173 row_ror:8 row_mask:0xf bank_mask:0xc
	v_add_f32_dpp v166, v166, v166 row_ror:8 row_mask:0xf bank_mask:0x3
	v_add_f32_dpp v166, v174, v174 row_ror:8 row_mask:0xf bank_mask:0xc
	v_add_f32_dpp v167, v167, v167 row_ror:8 row_mask:0xf bank_mask:0x3
	v_add_f32_dpp v167, v175, v175 row_ror:8 row_mask:0xf bank_mask:0xc
	v_add_f32_dpp v160, v160, v160 row_shl:4 row_mask:0xf bank_mask:0x5
	v_add_f32_dpp v160, v164, v164 row_shr:4 row_mask:0xf bank_mask:0xa
	v_add_f32_dpp v161, v161, v161 row_shl:4 row_mask:0xf bank_mask:0x5
	v_add_f32_dpp v161, v165, v165 row_shr:4 row_mask:0xf bank_mask:0xa
	v_add_f32_dpp v162, v162, v162 row_shl:4 row_mask:0xf bank_mask:0x5
	v_add_f32_dpp v162, v166, v166 row_shr:4 row_mask:0xf bank_mask:0xa
	v_add_f32_dpp v163, v163, v163 row_shl:4 row_mask:0xf bank_mask:0x5
	v_add_f32_dpp v163, v167, v167 row_shr:4 row_mask:0xf bank_mask:0xa
	v_and_b32_e32 v176, 2, v18
	v_cmp_ne_u32_e32 vcc, 0, v176
	v_add_f32_dpp v230, v160, v160 quad_perm:[2,3,0,1] row_mask:0xf bank_mask:0xf
	v_add_f32_dpp v231, v162, v162 quad_perm:[2,3,0,1] row_mask:0xf bank_mask:0xf
	v_add_f32_dpp v232, v161, v161 quad_perm:[2,3,0,1] row_mask:0xf bank_mask:0xf
	v_add_f32_dpp v233, v163, v163 quad_perm:[2,3,0,1] row_mask:0xf bank_mask:0xf
	v_cndmask_b32_e32 v230, v230, v231, vcc
	v_cndmask_b32_e32 v232, v232, v233, vcc
	v_and_b32_e32 v176, 1, v18
	v_cmp_ne_u32_e32 vcc, 0, v176
	v_add_f32_dpp v231, v230, v230 quad_perm:[1,0,3,2] row_mask:0xf bank_mask:0xf
	v_add_f32_dpp v233, v232, v232 quad_perm:[1,0,3,2] row_mask:0xf bank_mask:0xf
	s_nop 1
	v_cndmask_b32_e32 v241, v231, v233, vcc
	s_nop 1
	v_max_f32_dpp v242, v241, v241 row_ror:8 row_mask:0xf bank_mask:0xf
	s_nop 1
	v_max_f32_dpp v242, v242, v242 row_ror:4 row_mask:0xf bank_mask:0xf
	s_nop 1
	v_max_f32_dpp v242, v242, v242 row_ror:2 row_mask:0xf bank_mask:0xf
	s_nop 1
	v_max_f32_dpp v242, v242, v242 row_ror:1 row_mask:0xf bank_mask:0xf
	ds_bpermute_b32 v234, v238, v242
	s_waitcnt lgkmcnt(0)
	v_max_f32_e32 v242, v242, v234
	ds_bpermute_b32 v234, v239, v242
	s_waitcnt lgkmcnt(0)
	v_max_f32_e32 v242, v242, v234
	v_max_f32_e32 v242, v16, v242
	v_sub_f32_e32 v243, v16, v242
	v_sub_f32_e32 v240, v241, v242
	v_mul_f32_e32 v243, 0x3fb8aa3b, v243
	v_mul_f32_e32 v240, 0x3fb8aa3b, v240
	v_exp_f32_e32 v243, v243
	v_exp_f32_e32 v240, v240
	v_mov_b32_e32 v16, v242
	s_nop 0
	s_nop 1
	v_add_f32_dpp v235, v240, v240 row_ror:8 row_mask:0xf bank_mask:0xf
	s_nop 1
	v_add_f32_dpp v235, v235, v235 row_ror:4 row_mask:0xf bank_mask:0xf
	s_nop 1
	v_add_f32_dpp v235, v235, v235 row_ror:2 row_mask:0xf bank_mask:0xf
	s_nop 1
	v_add_f32_dpp v235, v235, v235 row_ror:1 row_mask:0xf bank_mask:0xf
	ds_bpermute_b32 v234, v238, v235
	s_waitcnt lgkmcnt(0)
	v_add_f32_e32 v235, v235, v234
	ds_bpermute_b32 v234, v239, v235
	s_waitcnt lgkmcnt(0)
	v_add_f32_e32 v235, v235, v234
	v_fma_f32 v17, v17, v243, v235
	v_mul_f32_e32 v8, v8, v243
	v_mul_f32_e32 v9, v9, v243
	v_mul_f32_e32 v10, v10, v243
	v_mul_f32_e32 v11, v11, v243
	v_mul_f32_e32 v12, v12, v243
	v_mul_f32_e32 v13, v13, v243
	v_mul_f32_e32 v14, v14, v243
	v_mul_f32_e32 v15, v15, v243
	s_add_u32 s27, s27, 1
	s_lshl_b32 s24, s27, 6
	s_lshr_b32 s28, s24, 7
	s_and_b32 s24, s24, 64
	s_lshl_b32 s28, s28, 1
	s_add_u32 s28, s28, 12
	s_lshl_b32 s25, 1, s28
	s_add_u32 s24, s24, 64
	s_lshl_b32 s24, s24, s28
	s_add_u32 s26, s10, 0x800
	s_lshl_b32 s26, s26, 12
	s_sub_u32 s26, s26, s24
	s_add_u32 s2, s16, s26
	s_addc_u32 s3, s17, 0
	s_add_u32 s4, s18, s26
	s_addc_u32 s5, s19, 0
	v_lshlrev_b32_e32 v24, 4, v23
	v_sub_u32_e32 v24, 63, v24
	v_lshlrev_b32_e32 v24, s28, v24
	v_lshl_add_u32 v24, v22, 5, v24
	v_subrev_u32_e32 v25, s25, v24
	v_subrev_u32_e32 v26, s25, v25
	v_subrev_u32_e32 v27, s25, v26
	v_subrev_u32_e32 v28, s25, v27
	v_subrev_u32_e32 v29, s25, v28
	v_subrev_u32_e32 v30, s25, v29
	v_subrev_u32_e32 v31, s25, v30
	v_subrev_u32_e32 v244, s25, v31
	v_subrev_u32_e32 v245, s25, v244
	v_subrev_u32_e32 v246, s25, v245
	v_subrev_u32_e32 v247, s25, v246
	v_subrev_u32_e32 v248, s25, v247
	v_subrev_u32_e32 v249, s25, v248
	v_subrev_u32_e32 v250, s25, v249
	v_subrev_u32_e32 v251, s25, v250
	s_waitcnt vmcnt(30)
	v_fmac_f32_dpp v8, v240, v32 row_newbcast:0 row_mask:0xf bank_mask:0xf
	v_fmac_f32_dpp v9, v240, v33 row_newbcast:0 row_mask:0xf bank_mask:0xf
	v_fmac_f32_dpp v10, v240, v34 row_newbcast:0 row_mask:0xf bank_mask:0xf
	v_fmac_f32_dpp v11, v240, v35 row_newbcast:0 row_mask:0xf bank_mask:0xf
	v_fmac_f32_dpp v12, v240, v36 row_newbcast:0 row_mask:0xf bank_mask:0xf
	v_fmac_f32_dpp v13, v240, v37 row_newbcast:0 row_mask:0xf bank_mask:0xf
	v_fmac_f32_dpp v14, v240, v38 row_newbcast:0 row_mask:0xf bank_mask:0xf
	v_fmac_f32_dpp v15, v240, v39 row_newbcast:0 row_mask:0xf bank_mask:0xf
	global_load_dwordx4 v[32:35], v24, s[2:3]
	global_load_dwordx4 v[36:39], v24, s[2:3] offset:16
	s_waitcnt vmcnt(30)
	v_fmac_f32_dpp v8, v240, v40 row_newbcast:1 row_mask:0xf bank_mask:0xf
	v_fmac_f32_dpp v9, v240, v41 row_newbcast:1 row_mask:0xf bank_mask:0xf
	v_fmac_f32_dpp v10, v240, v42 row_newbcast:1 row_mask:0xf bank_mask:0xf
	v_fmac_f32_dpp v11, v240, v43 row_newbcast:1 row_mask:0xf bank_mask:0xf
	v_fmac_f32_dpp v12, v240, v44 row_newbcast:1 row_mask:0xf bank_mask:0xf
	v_fmac_f32_dpp v13, v240, v45 row_newbcast:1 row_mask:0xf bank_mask:0xf
	v_fmac_f32_dpp v14, v240, v46 row_newbcast:1 row_mask:0xf bank_mask:0xf
	v_fmac_f32_dpp v15, v240, v47 row_newbcast:1 row_mask:0xf bank_mask:0xf
	global_load_dwordx4 v[40:43], v25, s[2:3]
	global_load_dwordx4 v[44:47], v25, s[2:3] offset:16
	s_waitcnt vmcnt(30)
	v_fmac_f32_dpp v8, v240, v48 row_newbcast:2 row_mask:0xf bank_mask:0xf
	v_fmac_f32_dpp v9, v240, v49 row_newbcast:2 row_mask:0xf bank_mask:0xf
	v_fmac_f32_dpp v10, v240, v50 row_newbcast:2 row_mask:0xf bank_mask:0xf
	v_fmac_f32_dpp v11, v240, v51 row_newbcast:2 row_mask:0xf bank_mask:0xf
	v_fmac_f32_dpp v12, v240, v52 row_newbcast:2 row_mask:0xf bank_mask:0xf
	v_fmac_f32_dpp v13, v240, v53 row_newbcast:2 row_mask:0xf bank_mask:0xf
	v_fmac_f32_dpp v14, v240, v54 row_newbcast:2 row_mask:0xf bank_mask:0xf
	v_fmac_f32_dpp v15, v240, v55 row_newbcast:2 row_mask:0xf bank_mask:0xf
	global_load_dwordx4 v[48:51], v26, s[2:3]
	global_load_dwordx4 v[52:55], v26, s[2:3] offset:16
	s_waitcnt vmcnt(30)
	v_fmac_f32_dpp v8, v240, v56 row_newbcast:3 row_mask:0xf bank_mask:0xf
	v_fmac_f32_dpp v9, v240, v57 row_newbcast:3 row_mask:0xf bank_mask:0xf
	v_fmac_f32_dpp v10, v240, v58 row_newbcast:3 row_mask:0xf bank_mask:0xf
	v_fmac_f32_dpp v11, v240, v59 row_newbcast:3 row_mask:0xf bank_mask:0xf
	v_fmac_f32_dpp v12, v240, v60 row_newbcast:3 row_mask:0xf bank_mask:0xf
	v_fmac_f32_dpp v13, v240, v61 row_newbcast:3 row_mask:0xf bank_mask:0xf
	v_fmac_f32_dpp v14, v240, v62 row_newbcast:3 row_mask:0xf bank_mask:0xf
	v_fmac_f32_dpp v15, v240, v63 row_newbcast:3 row_mask:0xf bank_mask:0xf
	global_load_dwordx4 v[56:59], v27, s[2:3]
	global_load_dwordx4 v[60:63], v27, s[2:3] offset:16
	s_waitcnt vmcnt(30)
	v_fmac_f32_dpp v8, v240, v64 row_newbcast:4 row_mask:0xf bank_mask:0xf
	v_fmac_f32_dpp v9, v240, v65 row_newbcast:4 row_mask:0xf bank_mask:0xf
	v_fmac_f32_dpp v10, v240, v66 row_newbcast:4 row_mask:0xf bank_mask:0xf
	v_fmac_f32_dpp v11, v240, v67 row_newbcast:4 row_mask:0xf bank_mask:0xf
	v_fmac_f32_dpp v12, v240, v68 row_newbcast:4 row_mask:0xf bank_mask:0xf
	v_fmac_f32_dpp v13, v240, v69 row_newbcast:4 row_mask:0xf bank_mask:0xf
	v_fmac_f32_dpp v14, v240, v70 row_newbcast:4 row_mask:0xf bank_mask:0xf
	v_fmac_f32_dpp v15, v240, v71 row_newbcast:4 row_mask:0xf bank_mask:0xf
	global_load_dwordx4 v[64:67], v28, s[2:3]
	global_load_dwordx4 v[68:71], v28, s[2:3] offset:16
	s_waitcnt vmcnt(30)
	v_fmac_f32_dpp v8, v240, v72 row_newbcast:5 row_mask:0xf bank_mask:0xf
	v_fmac_f32_dpp v9, v240, v73 row_newbcast:5 row_mask:0xf bank_mask:0xf
	v_fmac_f32_dpp v10, v240, v74 row_newbcast:5 row_mask:0xf bank_mask:0xf
	v_fmac_f32_dpp v11, v240, v75 row_newbcast:5 row_mask:0xf bank_mask:0xf
	v_fmac_f32_dpp v12, v240, v76 row_newbcast:5 row_mask:0xf bank_mask:0xf
	v_fmac_f32_dpp v13, v240, v77 row_newbcast:5 row_mask:0xf bank_mask:0xf
	v_fmac_f32_dpp v14, v240, v78 row_newbcast:5 row_mask:0xf bank_mask:0xf
	v_fmac_f32_dpp v15, v240, v79 row_newbcast:5 row_mask:0xf bank_mask:0xf
	global_load_dwordx4 v[72:75], v29, s[2:3]
	global_load_dwordx4 v[76:79], v29, s[2:3] offset:16
	s_waitcnt vmcnt(30)
	v_fmac_f32_dpp v8, v240, v80 row_newbcast:6 row_mask:0xf bank_mask:0xf
	v_fmac_f32_dpp v9, v240, v81 row_newbcast:6 row_mask:0xf bank_mask:0xf
	v_fmac_f32_dpp v10, v240, v82 row_newbcast:6 row_mask:0xf bank_mask:0xf
	v_fmac_f32_dpp v11, v240, v83 row_newbcast:6 row_mask:0xf bank_mask:0xf
	v_fmac_f32_dpp v12, v240, v84 row_newbcast:6 row_mask:0xf bank_mask:0xf
	v_fmac_f32_dpp v13, v240, v85 row_newbcast:6 row_mask:0xf bank_mask:0xf
	v_fmac_f32_dpp v14, v240, v86 row_newbcast:6 row_mask:0xf bank_mask:0xf
	v_fmac_f32_dpp v15, v240, v87 row_newbcast:6 row_mask:0xf bank_mask:0xf
	global_load_dwordx4 v[80:83], v30, s[2:3]
	global_load_dwordx4 v[84:87], v30, s[2:3] offset:16
	s_waitcnt vmcnt(30)
	v_fmac_f32_dpp v8, v240, v88 row_newbcast:7 row_mask:0xf bank_mask:0xf
	v_fmac_f32_dpp v9, v240, v89 row_newbcast:7 row_mask:0xf bank_mask:0xf
	v_fmac_f32_dpp v10, v240, v90 row_newbcast:7 row_mask:0xf bank_mask:0xf
	v_fmac_f32_dpp v11, v240, v91 row_newbcast:7 row_mask:0xf bank_mask:0xf
	v_fmac_f32_dpp v12, v240, v92 row_newbcast:7 row_mask:0xf bank_mask:0xf
	v_fmac_f32_dpp v13, v240, v93 row_newbcast:7 row_mask:0xf bank_mask:0xf
	v_fmac_f32_dpp v14, v240, v94 row_newbcast:7 row_mask:0xf bank_mask:0xf
	v_fmac_f32_dpp v15, v240, v95 row_newbcast:7 row_mask:0xf bank_mask:0xf
	global_load_dwordx4 v[88:91], v31, s[2:3]
	global_load_dwordx4 v[92:95], v31, s[2:3] offset:16
	s_waitcnt vmcnt(30)
	v_fmac_f32_dpp v8, v240, v96 row_newbcast:8 row_mask:0xf bank_mask:0xf
	v_fmac_f32_dpp v9, v240, v97 row_newbcast:8 row_mask:0xf bank_mask:0xf
	v_fmac_f32_dpp v10, v240, v98 row_newbcast:8 row_mask:0xf bank_mask:0xf
	v_fmac_f32_dpp v11, v240, v99 row_newbcast:8 row_mask:0xf bank_mask:0xf
	v_fmac_f32_dpp v12, v240, v100 row_newbcast:8 row_mask:0xf bank_mask:0xf
	v_fmac_f32_dpp v13, v240, v101 row_newbcast:8 row_mask:0xf bank_mask:0xf
	v_fmac_f32_dpp v14, v240, v102 row_newbcast:8 row_mask:0xf bank_mask:0xf
	v_fmac_f32_dpp v15, v240, v103 row_newbcast:8 row_mask:0xf bank_mask:0xf
	global_load_dwordx4 v[96:99], v244, s[2:3]
	global_load_dwordx4 v[100:103], v244, s[2:3] offset:16
	s_waitcnt vmcnt(30)
	v_fmac_f32_dpp v8, v240, v104 row_newbcast:9 row_mask:0xf bank_mask:0xf
	v_fmac_f32_dpp v9, v240, v105 row_newbcast:9 row_mask:0xf bank_mask:0xf
	v_fmac_f32_dpp v10, v240, v106 row_newbcast:9 row_mask:0xf bank_mask:0xf
	v_fmac_f32_dpp v11, v240, v107 row_newbcast:9 row_mask:0xf bank_mask:0xf
	v_fmac_f32_dpp v12, v240, v108 row_newbcast:9 row_mask:0xf bank_mask:0xf
	v_fmac_f32_dpp v13, v240, v109 row_newbcast:9 row_mask:0xf bank_mask:0xf
	v_fmac_f32_dpp v14, v240, v110 row_newbcast:9 row_mask:0xf bank_mask:0xf
	v_fmac_f32_dpp v15, v240, v111 row_newbcast:9 row_mask:0xf bank_mask:0xf
	global_load_dwordx4 v[104:107], v245, s[2:3]
	global_load_dwordx4 v[108:111], v245, s[2:3] offset:16
	s_waitcnt vmcnt(30)
	v_fmac_f32_dpp v8, v240, v112 row_newbcast:10 row_mask:0xf bank_mask:0xf
	v_fmac_f32_dpp v9, v240, v113 row_newbcast:10 row_mask:0xf bank_mask:0xf
	v_fmac_f32_dpp v10, v240, v114 row_newbcast:10 row_mask:0xf bank_mask:0xf
	v_fmac_f32_dpp v11, v240, v115 row_newbcast:10 row_mask:0xf bank_mask:0xf
	v_fmac_f32_dpp v12, v240, v116 row_newbcast:10 row_mask:0xf bank_mask:0xf
	v_fmac_f32_dpp v13, v240, v117 row_newbcast:10 row_mask:0xf bank_mask:0xf
	v_fmac_f32_dpp v14, v240, v118 row_newbcast:10 row_mask:0xf bank_mask:0xf
	v_fmac_f32_dpp v15, v240, v119 row_newbcast:10 row_mask:0xf bank_mask:0xf
	global_load_dwordx4 v[112:115], v246, s[2:3]
	global_load_dwordx4 v[116:119], v246, s[2:3] offset:16
	s_waitcnt vmcnt(30)
	v_fmac_f32_dpp v8, v240, v120 row_newbcast:11 row_mask:0xf bank_mask:0xf
	v_fmac_f32_dpp v9, v240, v121 row_newbcast:11 row_mask:0xf bank_mask:0xf
	v_fmac_f32_dpp v10, v240, v122 row_newbcast:11 row_mask:0xf bank_mask:0xf
	v_fmac_f32_dpp v11, v240, v123 row_newbcast:11 row_mask:0xf bank_mask:0xf
	v_fmac_f32_dpp v12, v240, v124 row_newbcast:11 row_mask:0xf bank_mask:0xf
	v_fmac_f32_dpp v13, v240, v125 row_newbcast:11 row_mask:0xf bank_mask:0xf
	v_fmac_f32_dpp v14, v240, v126 row_newbcast:11 row_mask:0xf bank_mask:0xf
	v_fmac_f32_dpp v15, v240, v127 row_newbcast:11 row_mask:0xf bank_mask:0xf
	global_load_dwordx4 v[120:123], v247, s[2:3]
	global_load_dwordx4 v[124:127], v247, s[2:3] offset:16
	s_waitcnt vmcnt(30)
	v_fmac_f32_dpp v8, v240, v128 row_newbcast:12 row_mask:0xf bank_mask:0xf
	v_fmac_f32_dpp v9, v240, v129 row_newbcast:12 row_mask:0xf bank_mask:0xf
	v_fmac_f32_dpp v10, v240, v130 row_newbcast:12 row_mask:0xf bank_mask:0xf
	v_fmac_f32_dpp v11, v240, v131 row_newbcast:12 row_mask:0xf bank_mask:0xf
	v_fmac_f32_dpp v12, v240, v132 row_newbcast:12 row_mask:0xf bank_mask:0xf
	v_fmac_f32_dpp v13, v240, v133 row_newbcast:12 row_mask:0xf bank_mask:0xf
	v_fmac_f32_dpp v14, v240, v134 row_newbcast:12 row_mask:0xf bank_mask:0xf
	v_fmac_f32_dpp v15, v240, v135 row_newbcast:12 row_mask:0xf bank_mask:0xf
	global_load_dwordx4 v[128:131], v248, s[2:3]
	global_load_dwordx4 v[132:135], v248, s[2:3] offset:16
	s_waitcnt vmcnt(30)
	v_fmac_f32_dpp v8, v240, v136 row_newbcast:13 row_mask:0xf bank_mask:0xf
	v_fmac_f32_dpp v9, v240, v137 row_newbcast:13 row_mask:0xf bank_mask:0xf
	v_fmac_f32_dpp v10, v240, v138 row_newbcast:13 row_mask:0xf bank_mask:0xf
	v_fmac_f32_dpp v11, v240, v139 row_newbcast:13 row_mask:0xf bank_mask:0xf
	v_fmac_f32_dpp v12, v240, v140 row_newbcast:13 row_mask:0xf bank_mask:0xf
	v_fmac_f32_dpp v13, v240, v141 row_newbcast:13 row_mask:0xf bank_mask:0xf
	v_fmac_f32_dpp v14, v240, v142 row_newbcast:13 row_mask:0xf bank_mask:0xf
	v_fmac_f32_dpp v15, v240, v143 row_newbcast:13 row_mask:0xf bank_mask:0xf
	global_load_dwordx4 v[136:139], v249, s[2:3]
	global_load_dwordx4 v[140:143], v249, s[2:3] offset:16
	s_waitcnt vmcnt(30)
	v_fmac_f32_dpp v8, v240, v144 row_newbcast:14 row_mask:0xf bank_mask:0xf
	v_fmac_f32_dpp v9, v240, v145 row_newbcast:14 row_mask:0xf bank_mask:0xf
	v_fmac_f32_dpp v10, v240, v146 row_newbcast:14 row_mask:0xf bank_mask:0xf
	v_fmac_f32_dpp v11, v240, v147 row_newbcast:14 row_mask:0xf bank_mask:0xf
	v_fmac_f32_dpp v12, v240, v148 row_newbcast:14 row_mask:0xf bank_mask:0xf
	v_fmac_f32_dpp v13, v240, v149 row_newbcast:14 row_mask:0xf bank_mask:0xf
	v_fmac_f32_dpp v14, v240, v150 row_newbcast:14 row_mask:0xf bank_mask:0xf
	v_fmac_f32_dpp v15, v240, v151 row_newbcast:14 row_mask:0xf bank_mask:0xf
	global_load_dwordx4 v[144:147], v250, s[2:3]
	global_load_dwordx4 v[148:151], v250, s[2:3] offset:16
	s_waitcnt vmcnt(30)
	v_fmac_f32_dpp v8, v240, v152 row_newbcast:15 row_mask:0xf bank_mask:0xf
	v_fmac_f32_dpp v9, v240, v153 row_newbcast:15 row_mask:0xf bank_mask:0xf
	v_fmac_f32_dpp v10, v240, v154 row_newbcast:15 row_mask:0xf bank_mask:0xf
	v_fmac_f32_dpp v11, v240, v155 row_newbcast:15 row_mask:0xf bank_mask:0xf
	v_fmac_f32_dpp v12, v240, v156 row_newbcast:15 row_mask:0xf bank_mask:0xf
	v_fmac_f32_dpp v13, v240, v157 row_newbcast:15 row_mask:0xf bank_mask:0xf
	v_fmac_f32_dpp v14, v240, v158 row_newbcast:15 row_mask:0xf bank_mask:0xf
	v_fmac_f32_dpp v15, v240, v159 row_newbcast:15 row_mask:0xf bank_mask:0xf
	global_load_dwordx4 v[152:155], v251, s[2:3]
	global_load_dwordx4 v[156:159], v251, s[2:3] offset:16
	s_waitcnt vmcnt(30)
	v_mul_f32_e32 v160, v32, v0
	v_fmac_f32_e32 v160, v33, v1
	v_fmac_f32_e32 v160, v34, v2
	v_fmac_f32_e32 v160, v35, v3
	v_fmac_f32_e32 v160, v36, v4
	v_fmac_f32_e32 v160, v37, v5
	v_fmac_f32_e32 v160, v38, v6
	v_fmac_f32_e32 v160, v39, v7
	global_load_dwordx4 v[32:35], v24, s[4:5]
	global_load_dwordx4 v[36:39], v24, s[4:5] offset:16
	s_waitcnt vmcnt(30)
	v_mul_f32_e32 v161, v40, v0
	v_fmac_f32_e32 v161, v41, v1
	v_fmac_f32_e32 v161, v42, v2
	v_fmac_f32_e32 v161, v43, v3
	v_fmac_f32_e32 v161, v44, v4
	v_fmac_f32_e32 v161, v45, v5
	v_fmac_f32_e32 v161, v46, v6
	v_fmac_f32_e32 v161, v47, v7
	global_load_dwordx4 v[40:43], v25, s[4:5]
	global_load_dwordx4 v[44:47], v25, s[4:5] offset:16
	s_waitcnt vmcnt(30)
	v_mul_f32_e32 v162, v48, v0
	v_fmac_f32_e32 v162, v49, v1
	v_fmac_f32_e32 v162, v50, v2
	v_fmac_f32_e32 v162, v51, v3
	v_fmac_f32_e32 v162, v52, v4
	v_fmac_f32_e32 v162, v53, v5
	v_fmac_f32_e32 v162, v54, v6
	v_fmac_f32_e32 v162, v55, v7
	global_load_dwordx4 v[48:51], v26, s[4:5]
	global_load_dwordx4 v[52:55], v26, s[4:5] offset:16
	s_waitcnt vmcnt(30)
	v_mul_f32_e32 v163, v56, v0
	v_fmac_f32_e32 v163, v57, v1
	v_fmac_f32_e32 v163, v58, v2
	v_fmac_f32_e32 v163, v59, v3
	v_fmac_f32_e32 v163, v60, v4
	v_fmac_f32_e32 v163, v61, v5
	v_fmac_f32_e32 v163, v62, v6
	v_fmac_f32_e32 v163, v63, v7
	global_load_dwordx4 v[56:59], v27, s[4:5]
	global_load_dwordx4 v[60:63], v27, s[4:5] offset:16
	s_waitcnt vmcnt(30)
	v_mul_f32_e32 v164, v64, v0
	v_fmac_f32_e32 v164, v65, v1
	v_fmac_f32_e32 v164, v66, v2
	v_fmac_f32_e32 v164, v67, v3
	v_fmac_f32_e32 v164, v68, v4
	v_fmac_f32_e32 v164, v69, v5
	v_fmac_f32_e32 v164, v70, v6
	v_fmac_f32_e32 v164, v71, v7
	global_load_dwordx4 v[64:67], v28, s[4:5]
	global_load_dwordx4 v[68:71], v28, s[4:5] offset:16
	s_waitcnt vmcnt(30)
	v_mul_f32_e32 v165, v72, v0
	v_fmac_f32_e32 v165, v73, v1
	v_fmac_f32_e32 v165, v74, v2
	v_fmac_f32_e32 v165, v75, v3
	v_fmac_f32_e32 v165, v76, v4
	v_fmac_f32_e32 v165, v77, v5
	v_fmac_f32_e32 v165, v78, v6
	v_fmac_f32_e32 v165, v79, v7
	global_load_dwordx4 v[72:75], v29, s[4:5]
	global_load_dwordx4 v[76:79], v29, s[4:5] offset:16
	s_waitcnt vmcnt(30)
	v_mul_f32_e32 v166, v80, v0
	v_fmac_f32_e32 v166, v81, v1
	v_fmac_f32_e32 v166, v82, v2
	v_fmac_f32_e32 v166, v83, v3
	v_fmac_f32_e32 v166, v84, v4
	v_fmac_f32_e32 v166, v85, v5
	v_fmac_f32_e32 v166, v86, v6
	v_fmac_f32_e32 v166, v87, v7
	global_load_dwordx4 v[80:83], v30, s[4:5]
	global_load_dwordx4 v[84:87], v30, s[4:5] offset:16
	s_waitcnt vmcnt(30)
	v_mul_f32_e32 v167, v88, v0
	v_fmac_f32_e32 v167, v89, v1
	v_fmac_f32_e32 v167, v90, v2
	v_fmac_f32_e32 v167, v91, v3
	v_fmac_f32_e32 v167, v92, v4
	v_fmac_f32_e32 v167, v93, v5
	v_fmac_f32_e32 v167, v94, v6
	v_fmac_f32_e32 v167, v95, v7
	global_load_dwordx4 v[88:91], v31, s[4:5]
	global_load_dwordx4 v[92:95], v31, s[4:5] offset:16
	s_waitcnt vmcnt(30)
	v_mul_f32_e32 v168, v96, v0
	v_fmac_f32_e32 v168, v97, v1
	v_fmac_f32_e32 v168, v98, v2
	v_fmac_f32_e32 v168, v99, v3
	v_fmac_f32_e32 v168, v100, v4
	v_fmac_f32_e32 v168, v101, v5
	v_fmac_f32_e32 v168, v102, v6
	v_fmac_f32_e32 v168, v103, v7
	global_load_dwordx4 v[96:99], v244, s[4:5]
	global_load_dwordx4 v[100:103], v244, s[4:5] offset:16
	s_waitcnt vmcnt(30)
	v_mul_f32_e32 v169, v104, v0
	v_fmac_f32_e32 v169, v105, v1
	v_fmac_f32_e32 v169, v106, v2
	v_fmac_f32_e32 v169, v107, v3
	v_fmac_f32_e32 v169, v108, v4
	v_fmac_f32_e32 v169, v109, v5
	v_fmac_f32_e32 v169, v110, v6
	v_fmac_f32_e32 v169, v111, v7
	global_load_dwordx4 v[104:107], v245, s[4:5]
	global_load_dwordx4 v[108:111], v245, s[4:5] offset:16
	s_waitcnt vmcnt(30)
	v_mul_f32_e32 v170, v112, v0
	v_fmac_f32_e32 v170, v113, v1
	v_fmac_f32_e32 v170, v114, v2
	v_fmac_f32_e32 v170, v115, v3
	v_fmac_f32_e32 v170, v116, v4
	v_fmac_f32_e32 v170, v117, v5
	v_fmac_f32_e32 v170, v118, v6
	v_fmac_f32_e32 v170, v119, v7
	global_load_dwordx4 v[112:115], v246, s[4:5]
	global_load_dwordx4 v[116:119], v246, s[4:5] offset:16
	s_waitcnt vmcnt(30)
	v_mul_f32_e32 v171, v120, v0
	v_fmac_f32_e32 v171, v121, v1
	v_fmac_f32_e32 v171, v122, v2
	v_fmac_f32_e32 v171, v123, v3
	v_fmac_f32_e32 v171, v124, v4
	v_fmac_f32_e32 v171, v125, v5
	v_fmac_f32_e32 v171, v126, v6
	v_fmac_f32_e32 v171, v127, v7
	global_load_dwordx4 v[120:123], v247, s[4:5]
	global_load_dwordx4 v[124:127], v247, s[4:5] offset:16
	s_waitcnt vmcnt(30)
	v_mul_f32_e32 v172, v128, v0
	v_fmac_f32_e32 v172, v129, v1
	v_fmac_f32_e32 v172, v130, v2
	v_fmac_f32_e32 v172, v131, v3
	v_fmac_f32_e32 v172, v132, v4
	v_fmac_f32_e32 v172, v133, v5
	v_fmac_f32_e32 v172, v134, v6
	v_fmac_f32_e32 v172, v135, v7
	global_load_dwordx4 v[128:131], v248, s[4:5]
	global_load_dwordx4 v[132:135], v248, s[4:5] offset:16
	s_waitcnt vmcnt(30)
	v_mul_f32_e32 v173, v136, v0
	v_fmac_f32_e32 v173, v137, v1
	v_fmac_f32_e32 v173, v138, v2
	v_fmac_f32_e32 v173, v139, v3
	v_fmac_f32_e32 v173, v140, v4
	v_fmac_f32_e32 v173, v141, v5
	v_fmac_f32_e32 v173, v142, v6
	v_fmac_f32_e32 v173, v143, v7
	global_load_dwordx4 v[136:139], v249, s[4:5]
	global_load_dwordx4 v[140:143], v249, s[4:5] offset:16
	s_waitcnt vmcnt(30)
	v_mul_f32_e32 v174, v144, v0
	v_fmac_f32_e32 v174, v145, v1
	v_fmac_f32_e32 v174, v146, v2
	v_fmac_f32_e32 v174, v147, v3
	v_fmac_f32_e32 v174, v148, v4
	v_fmac_f32_e32 v174, v149, v5
	v_fmac_f32_e32 v174, v150, v6
	v_fmac_f32_e32 v174, v151, v7
	global_load_dwordx4 v[144:147], v250, s[4:5]
	global_load_dwordx4 v[148:151], v250, s[4:5] offset:16
	s_waitcnt vmcnt(30)
	v_mul_f32_e32 v175, v152, v0
	v_fmac_f32_e32 v175, v153, v1
	v_fmac_f32_e32 v175, v154, v2
	v_fmac_f32_e32 v175, v155, v3
	v_fmac_f32_e32 v175, v156, v4
	v_fmac_f32_e32 v175, v157, v5
	v_fmac_f32_e32 v175, v158, v6
	v_fmac_f32_e32 v175, v159, v7
	global_load_dwordx4 v[152:155], v251, s[4:5]
	global_load_dwordx4 v[156:159], v251, s[4:5] offset:16
	v_add_f32_dpp v160, v160, v160 row_ror:8 row_mask:0xf bank_mask:0x3
	v_add_f32_dpp v160, v168, v168 row_ror:8 row_mask:0xf bank_mask:0xc
	v_add_f32_dpp v161, v161, v161 row_ror:8 row_mask:0xf bank_mask:0x3
	v_add_f32_dpp v161, v169, v169 row_ror:8 row_mask:0xf bank_mask:0xc
	v_add_f32_dpp v162, v162, v162 row_ror:8 row_mask:0xf bank_mask:0x3
	v_add_f32_dpp v162, v170, v170 row_ror:8 row_mask:0xf bank_mask:0xc
	v_add_f32_dpp v163, v163, v163 row_ror:8 row_mask:0xf bank_mask:0x3
	v_add_f32_dpp v163, v171, v171 row_ror:8 row_mask:0xf bank_mask:0xc
	v_add_f32_dpp v164, v164, v164 row_ror:8 row_mask:0xf bank_mask:0x3
	v_add_f32_dpp v164, v172, v172 row_ror:8 row_mask:0xf bank_mask:0xc
	v_add_f32_dpp v165, v165, v165 row_ror:8 row_mask:0xf bank_mask:0x3
	v_add_f32_dpp v165, v173, v173 row_ror:8 row_mask:0xf bank_mask:0xc
	v_add_f32_dpp v166, v166, v166 row_ror:8 row_mask:0xf bank_mask:0x3
	v_add_f32_dpp v166, v174, v174 row_ror:8 row_mask:0xf bank_mask:0xc
	v_add_f32_dpp v167, v167, v167 row_ror:8 row_mask:0xf bank_mask:0x3
	v_add_f32_dpp v167, v175, v175 row_ror:8 row_mask:0xf bank_mask:0xc
	v_add_f32_dpp v160, v160, v160 row_shl:4 row_mask:0xf bank_mask:0x5
	v_add_f32_dpp v160, v164, v164 row_shr:4 row_mask:0xf bank_mask:0xa
	v_add_f32_dpp v161, v161, v161 row_shl:4 row_mask:0xf bank_mask:0x5
	v_add_f32_dpp v161, v165, v165 row_shr:4 row_mask:0xf bank_mask:0xa
	v_add_f32_dpp v162, v162, v162 row_shl:4 row_mask:0xf bank_mask:0x5
	v_add_f32_dpp v162, v166, v166 row_shr:4 row_mask:0xf bank_mask:0xa
	v_add_f32_dpp v163, v163, v163 row_shl:4 row_mask:0xf bank_mask:0x5
	v_add_f32_dpp v163, v167, v167 row_shr:4 row_mask:0xf bank_mask:0xa
	v_and_b32_e32 v176, 2, v18
	v_cmp_ne_u32_e32 vcc, 0, v176
	v_add_f32_dpp v230, v160, v160 quad_perm:[2,3,0,1] row_mask:0xf bank_mask:0xf
	v_add_f32_dpp v231, v162, v162 quad_perm:[2,3,0,1] row_mask:0xf bank_mask:0xf
	v_add_f32_dpp v232, v161, v161 quad_perm:[2,3,0,1] row_mask:0xf bank_mask:0xf
	v_add_f32_dpp v233, v163, v163 quad_perm:[2,3,0,1] row_mask:0xf bank_mask:0xf
	v_cndmask_b32_e32 v230, v230, v231, vcc
	v_cndmask_b32_e32 v232, v232, v233, vcc
	v_and_b32_e32 v176, 1, v18
	v_cmp_ne_u32_e32 vcc, 0, v176
	v_add_f32_dpp v231, v230, v230 quad_perm:[1,0,3,2] row_mask:0xf bank_mask:0xf
	v_add_f32_dpp v233, v232, v232 quad_perm:[1,0,3,2] row_mask:0xf bank_mask:0xf
	s_nop 1
	v_cndmask_b32_e32 v241, v231, v233, vcc
	s_nop 1
	v_max_f32_dpp v242, v241, v241 row_ror:8 row_mask:0xf bank_mask:0xf
	s_nop 1
	v_max_f32_dpp v242, v242, v242 row_ror:4 row_mask:0xf bank_mask:0xf
	s_nop 1
	v_max_f32_dpp v242, v242, v242 row_ror:2 row_mask:0xf bank_mask:0xf
	s_nop 1
	v_max_f32_dpp v242, v242, v242 row_ror:1 row_mask:0xf bank_mask:0xf
	ds_bpermute_b32 v234, v238, v242
	s_waitcnt lgkmcnt(0)
	v_max_f32_e32 v242, v242, v234
	ds_bpermute_b32 v234, v239, v242
	s_waitcnt lgkmcnt(0)
	v_max_f32_e32 v242, v242, v234
	v_max_f32_e32 v242, v16, v242
	v_sub_f32_e32 v243, v16, v242
	v_sub_f32_e32 v240, v241, v242
	v_mul_f32_e32 v243, 0x3fb8aa3b, v243
	v_mul_f32_e32 v240, 0x3fb8aa3b, v240
	v_exp_f32_e32 v243, v243
	v_exp_f32_e32 v240, v240
	v_mov_b32_e32 v16, v242
	s_nop 0
	s_nop 1
	v_add_f32_dpp v235, v240, v240 row_ror:8 row_mask:0xf bank_mask:0xf
	s_nop 1
	v_add_f32_dpp v235, v235, v235 row_ror:4 row_mask:0xf bank_mask:0xf
	s_nop 1
	v_add_f32_dpp v235, v235, v235 row_ror:2 row_mask:0xf bank_mask:0xf
	s_nop 1
	v_add_f32_dpp v235, v235, v235 row_ror:1 row_mask:0xf bank_mask:0xf
	ds_bpermute_b32 v234, v238, v235
	s_waitcnt lgkmcnt(0)
	v_add_f32_e32 v235, v235, v234
	ds_bpermute_b32 v234, v239, v235
	s_waitcnt lgkmcnt(0)
	v_add_f32_e32 v235, v235, v234
	v_fma_f32 v17, v17, v243, v235
	v_mul_f32_e32 v8, v8, v243
	v_mul_f32_e32 v9, v9, v243
	v_mul_f32_e32 v10, v10, v243
	v_mul_f32_e32 v11, v11, v243
	v_mul_f32_e32 v12, v12, v243
	v_mul_f32_e32 v13, v13, v243
	v_mul_f32_e32 v14, v14, v243
	v_mul_f32_e32 v15, v15, v243
	s_add_u32 s27, s27, 1
	s_lshl_b32 s24, s27, 6
	s_lshr_b32 s28, s24, 7
	s_and_b32 s24, s24, 64
	s_lshl_b32 s28, s28, 1
	s_add_u32 s28, s28, 12
	s_lshl_b32 s25, 1, s28
	s_add_u32 s24, s24, 64
	s_lshl_b32 s24, s24, s28
	s_add_u32 s26, s10, 0x800
	s_lshl_b32 s26, s26, 12
	s_sub_u32 s26, s26, s24
	s_add_u32 s2, s16, s26
	s_addc_u32 s3, s17, 0
	s_add_u32 s4, s18, s26
	s_addc_u32 s5, s19, 0
	v_lshlrev_b32_e32 v24, 4, v23
	v_sub_u32_e32 v24, 63, v24
	v_lshlrev_b32_e32 v24, s28, v24
	v_lshl_add_u32 v24, v22, 5, v24
	v_subrev_u32_e32 v25, s25, v24
	v_subrev_u32_e32 v26, s25, v25
	v_subrev_u32_e32 v27, s25, v26
	v_subrev_u32_e32 v28, s25, v27
	v_subrev_u32_e32 v29, s25, v28
	v_subrev_u32_e32 v30, s25, v29
	v_subrev_u32_e32 v31, s25, v30
	v_subrev_u32_e32 v244, s25, v31
	v_subrev_u32_e32 v245, s25, v244
	v_subrev_u32_e32 v246, s25, v245
	v_subrev_u32_e32 v247, s25, v246
	v_subrev_u32_e32 v248, s25, v247
	v_subrev_u32_e32 v249, s25, v248
	v_subrev_u32_e32 v250, s25, v249
	v_subrev_u32_e32 v251, s25, v250
	s_waitcnt vmcnt(30)
	v_fmac_f32_dpp v8, v240, v32 row_newbcast:0 row_mask:0xf bank_mask:0xf
	v_fmac_f32_dpp v9, v240, v33 row_newbcast:0 row_mask:0xf bank_mask:0xf
	v_fmac_f32_dpp v10, v240, v34 row_newbcast:0 row_mask:0xf bank_mask:0xf
	v_fmac_f32_dpp v11, v240, v35 row_newbcast:0 row_mask:0xf bank_mask:0xf
	v_fmac_f32_dpp v12, v240, v36 row_newbcast:0 row_mask:0xf bank_mask:0xf
	v_fmac_f32_dpp v13, v240, v37 row_newbcast:0 row_mask:0xf bank_mask:0xf
	v_fmac_f32_dpp v14, v240, v38 row_newbcast:0 row_mask:0xf bank_mask:0xf
	v_fmac_f32_dpp v15, v240, v39 row_newbcast:0 row_mask:0xf bank_mask:0xf
	global_load_dwordx4 v[32:35], v24, s[2:3]
	global_load_dwordx4 v[36:39], v24, s[2:3] offset:16
	s_waitcnt vmcnt(30)
	v_fmac_f32_dpp v8, v240, v40 row_newbcast:1 row_mask:0xf bank_mask:0xf
	v_fmac_f32_dpp v9, v240, v41 row_newbcast:1 row_mask:0xf bank_mask:0xf
	v_fmac_f32_dpp v10, v240, v42 row_newbcast:1 row_mask:0xf bank_mask:0xf
	v_fmac_f32_dpp v11, v240, v43 row_newbcast:1 row_mask:0xf bank_mask:0xf
	v_fmac_f32_dpp v12, v240, v44 row_newbcast:1 row_mask:0xf bank_mask:0xf
	v_fmac_f32_dpp v13, v240, v45 row_newbcast:1 row_mask:0xf bank_mask:0xf
	v_fmac_f32_dpp v14, v240, v46 row_newbcast:1 row_mask:0xf bank_mask:0xf
	v_fmac_f32_dpp v15, v240, v47 row_newbcast:1 row_mask:0xf bank_mask:0xf
	global_load_dwordx4 v[40:43], v25, s[2:3]
	global_load_dwordx4 v[44:47], v25, s[2:3] offset:16
	s_waitcnt vmcnt(30)
	v_fmac_f32_dpp v8, v240, v48 row_newbcast:2 row_mask:0xf bank_mask:0xf
	v_fmac_f32_dpp v9, v240, v49 row_newbcast:2 row_mask:0xf bank_mask:0xf
	v_fmac_f32_dpp v10, v240, v50 row_newbcast:2 row_mask:0xf bank_mask:0xf
	v_fmac_f32_dpp v11, v240, v51 row_newbcast:2 row_mask:0xf bank_mask:0xf
	v_fmac_f32_dpp v12, v240, v52 row_newbcast:2 row_mask:0xf bank_mask:0xf
	v_fmac_f32_dpp v13, v240, v53 row_newbcast:2 row_mask:0xf bank_mask:0xf
	v_fmac_f32_dpp v14, v240, v54 row_newbcast:2 row_mask:0xf bank_mask:0xf
	v_fmac_f32_dpp v15, v240, v55 row_newbcast:2 row_mask:0xf bank_mask:0xf
	global_load_dwordx4 v[48:51], v26, s[2:3]
	global_load_dwordx4 v[52:55], v26, s[2:3] offset:16
	s_waitcnt vmcnt(30)
	v_fmac_f32_dpp v8, v240, v56 row_newbcast:3 row_mask:0xf bank_mask:0xf
	v_fmac_f32_dpp v9, v240, v57 row_newbcast:3 row_mask:0xf bank_mask:0xf
	v_fmac_f32_dpp v10, v240, v58 row_newbcast:3 row_mask:0xf bank_mask:0xf
	v_fmac_f32_dpp v11, v240, v59 row_newbcast:3 row_mask:0xf bank_mask:0xf
	v_fmac_f32_dpp v12, v240, v60 row_newbcast:3 row_mask:0xf bank_mask:0xf
	v_fmac_f32_dpp v13, v240, v61 row_newbcast:3 row_mask:0xf bank_mask:0xf
	v_fmac_f32_dpp v14, v240, v62 row_newbcast:3 row_mask:0xf bank_mask:0xf
	v_fmac_f32_dpp v15, v240, v63 row_newbcast:3 row_mask:0xf bank_mask:0xf
	global_load_dwordx4 v[56:59], v27, s[2:3]
	global_load_dwordx4 v[60:63], v27, s[2:3] offset:16
	s_waitcnt vmcnt(30)
	v_fmac_f32_dpp v8, v240, v64 row_newbcast:4 row_mask:0xf bank_mask:0xf
	v_fmac_f32_dpp v9, v240, v65 row_newbcast:4 row_mask:0xf bank_mask:0xf
	v_fmac_f32_dpp v10, v240, v66 row_newbcast:4 row_mask:0xf bank_mask:0xf
	v_fmac_f32_dpp v11, v240, v67 row_newbcast:4 row_mask:0xf bank_mask:0xf
	v_fmac_f32_dpp v12, v240, v68 row_newbcast:4 row_mask:0xf bank_mask:0xf
	v_fmac_f32_dpp v13, v240, v69 row_newbcast:4 row_mask:0xf bank_mask:0xf
	v_fmac_f32_dpp v14, v240, v70 row_newbcast:4 row_mask:0xf bank_mask:0xf
	v_fmac_f32_dpp v15, v240, v71 row_newbcast:4 row_mask:0xf bank_mask:0xf
	global_load_dwordx4 v[64:67], v28, s[2:3]
	global_load_dwordx4 v[68:71], v28, s[2:3] offset:16
	s_waitcnt vmcnt(30)
	v_fmac_f32_dpp v8, v240, v72 row_newbcast:5 row_mask:0xf bank_mask:0xf
	v_fmac_f32_dpp v9, v240, v73 row_newbcast:5 row_mask:0xf bank_mask:0xf
	v_fmac_f32_dpp v10, v240, v74 row_newbcast:5 row_mask:0xf bank_mask:0xf
	v_fmac_f32_dpp v11, v240, v75 row_newbcast:5 row_mask:0xf bank_mask:0xf
	v_fmac_f32_dpp v12, v240, v76 row_newbcast:5 row_mask:0xf bank_mask:0xf
	v_fmac_f32_dpp v13, v240, v77 row_newbcast:5 row_mask:0xf bank_mask:0xf
	v_fmac_f32_dpp v14, v240, v78 row_newbcast:5 row_mask:0xf bank_mask:0xf
	v_fmac_f32_dpp v15, v240, v79 row_newbcast:5 row_mask:0xf bank_mask:0xf
	global_load_dwordx4 v[72:75], v29, s[2:3]
	global_load_dwordx4 v[76:79], v29, s[2:3] offset:16
	s_waitcnt vmcnt(30)
	v_fmac_f32_dpp v8, v240, v80 row_newbcast:6 row_mask:0xf bank_mask:0xf
	v_fmac_f32_dpp v9, v240, v81 row_newbcast:6 row_mask:0xf bank_mask:0xf
	v_fmac_f32_dpp v10, v240, v82 row_newbcast:6 row_mask:0xf bank_mask:0xf
	v_fmac_f32_dpp v11, v240, v83 row_newbcast:6 row_mask:0xf bank_mask:0xf
	v_fmac_f32_dpp v12, v240, v84 row_newbcast:6 row_mask:0xf bank_mask:0xf
	v_fmac_f32_dpp v13, v240, v85 row_newbcast:6 row_mask:0xf bank_mask:0xf
	v_fmac_f32_dpp v14, v240, v86 row_newbcast:6 row_mask:0xf bank_mask:0xf
	v_fmac_f32_dpp v15, v240, v87 row_newbcast:6 row_mask:0xf bank_mask:0xf
	global_load_dwordx4 v[80:83], v30, s[2:3]
	global_load_dwordx4 v[84:87], v30, s[2:3] offset:16
	s_waitcnt vmcnt(30)
	v_fmac_f32_dpp v8, v240, v88 row_newbcast:7 row_mask:0xf bank_mask:0xf
	v_fmac_f32_dpp v9, v240, v89 row_newbcast:7 row_mask:0xf bank_mask:0xf
	v_fmac_f32_dpp v10, v240, v90 row_newbcast:7 row_mask:0xf bank_mask:0xf
	v_fmac_f32_dpp v11, v240, v91 row_newbcast:7 row_mask:0xf bank_mask:0xf
	v_fmac_f32_dpp v12, v240, v92 row_newbcast:7 row_mask:0xf bank_mask:0xf
	v_fmac_f32_dpp v13, v240, v93 row_newbcast:7 row_mask:0xf bank_mask:0xf
	v_fmac_f32_dpp v14, v240, v94 row_newbcast:7 row_mask:0xf bank_mask:0xf
	v_fmac_f32_dpp v15, v240, v95 row_newbcast:7 row_mask:0xf bank_mask:0xf
	global_load_dwordx4 v[88:91], v31, s[2:3]
	global_load_dwordx4 v[92:95], v31, s[2:3] offset:16
	s_waitcnt vmcnt(30)
	v_fmac_f32_dpp v8, v240, v96 row_newbcast:8 row_mask:0xf bank_mask:0xf
	v_fmac_f32_dpp v9, v240, v97 row_newbcast:8 row_mask:0xf bank_mask:0xf
	v_fmac_f32_dpp v10, v240, v98 row_newbcast:8 row_mask:0xf bank_mask:0xf
	v_fmac_f32_dpp v11, v240, v99 row_newbcast:8 row_mask:0xf bank_mask:0xf
	v_fmac_f32_dpp v12, v240, v100 row_newbcast:8 row_mask:0xf bank_mask:0xf
	v_fmac_f32_dpp v13, v240, v101 row_newbcast:8 row_mask:0xf bank_mask:0xf
	v_fmac_f32_dpp v14, v240, v102 row_newbcast:8 row_mask:0xf bank_mask:0xf
	v_fmac_f32_dpp v15, v240, v103 row_newbcast:8 row_mask:0xf bank_mask:0xf
	global_load_dwordx4 v[96:99], v244, s[2:3]
	global_load_dwordx4 v[100:103], v244, s[2:3] offset:16
	s_waitcnt vmcnt(30)
	v_fmac_f32_dpp v8, v240, v104 row_newbcast:9 row_mask:0xf bank_mask:0xf
	v_fmac_f32_dpp v9, v240, v105 row_newbcast:9 row_mask:0xf bank_mask:0xf
	v_fmac_f32_dpp v10, v240, v106 row_newbcast:9 row_mask:0xf bank_mask:0xf
	v_fmac_f32_dpp v11, v240, v107 row_newbcast:9 row_mask:0xf bank_mask:0xf
	v_fmac_f32_dpp v12, v240, v108 row_newbcast:9 row_mask:0xf bank_mask:0xf
	v_fmac_f32_dpp v13, v240, v109 row_newbcast:9 row_mask:0xf bank_mask:0xf
	v_fmac_f32_dpp v14, v240, v110 row_newbcast:9 row_mask:0xf bank_mask:0xf
	v_fmac_f32_dpp v15, v240, v111 row_newbcast:9 row_mask:0xf bank_mask:0xf
	global_load_dwordx4 v[104:107], v245, s[2:3]
	global_load_dwordx4 v[108:111], v245, s[2:3] offset:16
	s_waitcnt vmcnt(30)
	v_fmac_f32_dpp v8, v240, v112 row_newbcast:10 row_mask:0xf bank_mask:0xf
	v_fmac_f32_dpp v9, v240, v113 row_newbcast:10 row_mask:0xf bank_mask:0xf
	v_fmac_f32_dpp v10, v240, v114 row_newbcast:10 row_mask:0xf bank_mask:0xf
	v_fmac_f32_dpp v11, v240, v115 row_newbcast:10 row_mask:0xf bank_mask:0xf
	v_fmac_f32_dpp v12, v240, v116 row_newbcast:10 row_mask:0xf bank_mask:0xf
	v_fmac_f32_dpp v13, v240, v117 row_newbcast:10 row_mask:0xf bank_mask:0xf
	v_fmac_f32_dpp v14, v240, v118 row_newbcast:10 row_mask:0xf bank_mask:0xf
	v_fmac_f32_dpp v15, v240, v119 row_newbcast:10 row_mask:0xf bank_mask:0xf
	global_load_dwordx4 v[112:115], v246, s[2:3]
	global_load_dwordx4 v[116:119], v246, s[2:3] offset:16
	s_waitcnt vmcnt(30)
	v_fmac_f32_dpp v8, v240, v120 row_newbcast:11 row_mask:0xf bank_mask:0xf
	v_fmac_f32_dpp v9, v240, v121 row_newbcast:11 row_mask:0xf bank_mask:0xf
	v_fmac_f32_dpp v10, v240, v122 row_newbcast:11 row_mask:0xf bank_mask:0xf
	v_fmac_f32_dpp v11, v240, v123 row_newbcast:11 row_mask:0xf bank_mask:0xf
	v_fmac_f32_dpp v12, v240, v124 row_newbcast:11 row_mask:0xf bank_mask:0xf
	v_fmac_f32_dpp v13, v240, v125 row_newbcast:11 row_mask:0xf bank_mask:0xf
	v_fmac_f32_dpp v14, v240, v126 row_newbcast:11 row_mask:0xf bank_mask:0xf
	v_fmac_f32_dpp v15, v240, v127 row_newbcast:11 row_mask:0xf bank_mask:0xf
	global_load_dwordx4 v[120:123], v247, s[2:3]
	global_load_dwordx4 v[124:127], v247, s[2:3] offset:16
	s_waitcnt vmcnt(30)
	v_fmac_f32_dpp v8, v240, v128 row_newbcast:12 row_mask:0xf bank_mask:0xf
	v_fmac_f32_dpp v9, v240, v129 row_newbcast:12 row_mask:0xf bank_mask:0xf
	v_fmac_f32_dpp v10, v240, v130 row_newbcast:12 row_mask:0xf bank_mask:0xf
	v_fmac_f32_dpp v11, v240, v131 row_newbcast:12 row_mask:0xf bank_mask:0xf
	v_fmac_f32_dpp v12, v240, v132 row_newbcast:12 row_mask:0xf bank_mask:0xf
	v_fmac_f32_dpp v13, v240, v133 row_newbcast:12 row_mask:0xf bank_mask:0xf
	v_fmac_f32_dpp v14, v240, v134 row_newbcast:12 row_mask:0xf bank_mask:0xf
	v_fmac_f32_dpp v15, v240, v135 row_newbcast:12 row_mask:0xf bank_mask:0xf
	global_load_dwordx4 v[128:131], v248, s[2:3]
	global_load_dwordx4 v[132:135], v248, s[2:3] offset:16
	s_waitcnt vmcnt(30)
	v_fmac_f32_dpp v8, v240, v136 row_newbcast:13 row_mask:0xf bank_mask:0xf
	v_fmac_f32_dpp v9, v240, v137 row_newbcast:13 row_mask:0xf bank_mask:0xf
	v_fmac_f32_dpp v10, v240, v138 row_newbcast:13 row_mask:0xf bank_mask:0xf
	v_fmac_f32_dpp v11, v240, v139 row_newbcast:13 row_mask:0xf bank_mask:0xf
	v_fmac_f32_dpp v12, v240, v140 row_newbcast:13 row_mask:0xf bank_mask:0xf
	v_fmac_f32_dpp v13, v240, v141 row_newbcast:13 row_mask:0xf bank_mask:0xf
	v_fmac_f32_dpp v14, v240, v142 row_newbcast:13 row_mask:0xf bank_mask:0xf
	v_fmac_f32_dpp v15, v240, v143 row_newbcast:13 row_mask:0xf bank_mask:0xf
	global_load_dwordx4 v[136:139], v249, s[2:3]
	global_load_dwordx4 v[140:143], v249, s[2:3] offset:16
	s_waitcnt vmcnt(30)
	v_fmac_f32_dpp v8, v240, v144 row_newbcast:14 row_mask:0xf bank_mask:0xf
	v_fmac_f32_dpp v9, v240, v145 row_newbcast:14 row_mask:0xf bank_mask:0xf
	v_fmac_f32_dpp v10, v240, v146 row_newbcast:14 row_mask:0xf bank_mask:0xf
	v_fmac_f32_dpp v11, v240, v147 row_newbcast:14 row_mask:0xf bank_mask:0xf
	v_fmac_f32_dpp v12, v240, v148 row_newbcast:14 row_mask:0xf bank_mask:0xf
	v_fmac_f32_dpp v13, v240, v149 row_newbcast:14 row_mask:0xf bank_mask:0xf
	v_fmac_f32_dpp v14, v240, v150 row_newbcast:14 row_mask:0xf bank_mask:0xf
	v_fmac_f32_dpp v15, v240, v151 row_newbcast:14 row_mask:0xf bank_mask:0xf
	global_load_dwordx4 v[144:147], v250, s[2:3]
	global_load_dwordx4 v[148:151], v250, s[2:3] offset:16
	s_waitcnt vmcnt(30)
	v_fmac_f32_dpp v8, v240, v152 row_newbcast:15 row_mask:0xf bank_mask:0xf
	v_fmac_f32_dpp v9, v240, v153 row_newbcast:15 row_mask:0xf bank_mask:0xf
	v_fmac_f32_dpp v10, v240, v154 row_newbcast:15 row_mask:0xf bank_mask:0xf
	v_fmac_f32_dpp v11, v240, v155 row_newbcast:15 row_mask:0xf bank_mask:0xf
	v_fmac_f32_dpp v12, v240, v156 row_newbcast:15 row_mask:0xf bank_mask:0xf
	v_fmac_f32_dpp v13, v240, v157 row_newbcast:15 row_mask:0xf bank_mask:0xf
	v_fmac_f32_dpp v14, v240, v158 row_newbcast:15 row_mask:0xf bank_mask:0xf
	v_fmac_f32_dpp v15, v240, v159 row_newbcast:15 row_mask:0xf bank_mask:0xf
	global_load_dwordx4 v[152:155], v251, s[2:3]
	global_load_dwordx4 v[156:159], v251, s[2:3] offset:16
	s_waitcnt vmcnt(30)
	v_mul_f32_e32 v160, v32, v0
	v_fmac_f32_e32 v160, v33, v1
	v_fmac_f32_e32 v160, v34, v2
	v_fmac_f32_e32 v160, v35, v3
	v_fmac_f32_e32 v160, v36, v4
	v_fmac_f32_e32 v160, v37, v5
	v_fmac_f32_e32 v160, v38, v6
	v_fmac_f32_e32 v160, v39, v7
	global_load_dwordx4 v[32:35], v24, s[4:5]
	global_load_dwordx4 v[36:39], v24, s[4:5] offset:16
	s_waitcnt vmcnt(30)
	v_mul_f32_e32 v161, v40, v0
	v_fmac_f32_e32 v161, v41, v1
	v_fmac_f32_e32 v161, v42, v2
	v_fmac_f32_e32 v161, v43, v3
	v_fmac_f32_e32 v161, v44, v4
	v_fmac_f32_e32 v161, v45, v5
	v_fmac_f32_e32 v161, v46, v6
	v_fmac_f32_e32 v161, v47, v7
	global_load_dwordx4 v[40:43], v25, s[4:5]
	global_load_dwordx4 v[44:47], v25, s[4:5] offset:16
	s_waitcnt vmcnt(30)
	v_mul_f32_e32 v162, v48, v0
	v_fmac_f32_e32 v162, v49, v1
	v_fmac_f32_e32 v162, v50, v2
	v_fmac_f32_e32 v162, v51, v3
	v_fmac_f32_e32 v162, v52, v4
	v_fmac_f32_e32 v162, v53, v5
	v_fmac_f32_e32 v162, v54, v6
	v_fmac_f32_e32 v162, v55, v7
	global_load_dwordx4 v[48:51], v26, s[4:5]
	global_load_dwordx4 v[52:55], v26, s[4:5] offset:16
	s_waitcnt vmcnt(30)
	v_mul_f32_e32 v163, v56, v0
	v_fmac_f32_e32 v163, v57, v1
	v_fmac_f32_e32 v163, v58, v2
	v_fmac_f32_e32 v163, v59, v3
	v_fmac_f32_e32 v163, v60, v4
	v_fmac_f32_e32 v163, v61, v5
	v_fmac_f32_e32 v163, v62, v6
	v_fmac_f32_e32 v163, v63, v7
	global_load_dwordx4 v[56:59], v27, s[4:5]
	global_load_dwordx4 v[60:63], v27, s[4:5] offset:16
	s_waitcnt vmcnt(30)
	v_mul_f32_e32 v164, v64, v0
	v_fmac_f32_e32 v164, v65, v1
	v_fmac_f32_e32 v164, v66, v2
	v_fmac_f32_e32 v164, v67, v3
	v_fmac_f32_e32 v164, v68, v4
	v_fmac_f32_e32 v164, v69, v5
	v_fmac_f32_e32 v164, v70, v6
	v_fmac_f32_e32 v164, v71, v7
	global_load_dwordx4 v[64:67], v28, s[4:5]
	global_load_dwordx4 v[68:71], v28, s[4:5] offset:16
	s_waitcnt vmcnt(30)
	v_mul_f32_e32 v165, v72, v0
	v_fmac_f32_e32 v165, v73, v1
	v_fmac_f32_e32 v165, v74, v2
	v_fmac_f32_e32 v165, v75, v3
	v_fmac_f32_e32 v165, v76, v4
	v_fmac_f32_e32 v165, v77, v5
	v_fmac_f32_e32 v165, v78, v6
	v_fmac_f32_e32 v165, v79, v7
	global_load_dwordx4 v[72:75], v29, s[4:5]
	global_load_dwordx4 v[76:79], v29, s[4:5] offset:16
	s_waitcnt vmcnt(30)
	v_mul_f32_e32 v166, v80, v0
	v_fmac_f32_e32 v166, v81, v1
	v_fmac_f32_e32 v166, v82, v2
	v_fmac_f32_e32 v166, v83, v3
	v_fmac_f32_e32 v166, v84, v4
	v_fmac_f32_e32 v166, v85, v5
	v_fmac_f32_e32 v166, v86, v6
	v_fmac_f32_e32 v166, v87, v7
	global_load_dwordx4 v[80:83], v30, s[4:5]
	global_load_dwordx4 v[84:87], v30, s[4:5] offset:16
	s_waitcnt vmcnt(30)
	v_mul_f32_e32 v167, v88, v0
	v_fmac_f32_e32 v167, v89, v1
	v_fmac_f32_e32 v167, v90, v2
	v_fmac_f32_e32 v167, v91, v3
	v_fmac_f32_e32 v167, v92, v4
	v_fmac_f32_e32 v167, v93, v5
	v_fmac_f32_e32 v167, v94, v6
	v_fmac_f32_e32 v167, v95, v7
	global_load_dwordx4 v[88:91], v31, s[4:5]
	global_load_dwordx4 v[92:95], v31, s[4:5] offset:16
	s_waitcnt vmcnt(30)
	v_mul_f32_e32 v168, v96, v0
	v_fmac_f32_e32 v168, v97, v1
	v_fmac_f32_e32 v168, v98, v2
	v_fmac_f32_e32 v168, v99, v3
	v_fmac_f32_e32 v168, v100, v4
	v_fmac_f32_e32 v168, v101, v5
	v_fmac_f32_e32 v168, v102, v6
	v_fmac_f32_e32 v168, v103, v7
	global_load_dwordx4 v[96:99], v244, s[4:5]
	global_load_dwordx4 v[100:103], v244, s[4:5] offset:16
	s_waitcnt vmcnt(30)
	v_mul_f32_e32 v169, v104, v0
	v_fmac_f32_e32 v169, v105, v1
	v_fmac_f32_e32 v169, v106, v2
	v_fmac_f32_e32 v169, v107, v3
	v_fmac_f32_e32 v169, v108, v4
	v_fmac_f32_e32 v169, v109, v5
	v_fmac_f32_e32 v169, v110, v6
	v_fmac_f32_e32 v169, v111, v7
	global_load_dwordx4 v[104:107], v245, s[4:5]
	global_load_dwordx4 v[108:111], v245, s[4:5] offset:16
	s_waitcnt vmcnt(30)
	v_mul_f32_e32 v170, v112, v0
	v_fmac_f32_e32 v170, v113, v1
	v_fmac_f32_e32 v170, v114, v2
	v_fmac_f32_e32 v170, v115, v3
	v_fmac_f32_e32 v170, v116, v4
	v_fmac_f32_e32 v170, v117, v5
	v_fmac_f32_e32 v170, v118, v6
	v_fmac_f32_e32 v170, v119, v7
	global_load_dwordx4 v[112:115], v246, s[4:5]
	global_load_dwordx4 v[116:119], v246, s[4:5] offset:16
	s_waitcnt vmcnt(30)
	v_mul_f32_e32 v171, v120, v0
	v_fmac_f32_e32 v171, v121, v1
	v_fmac_f32_e32 v171, v122, v2
	v_fmac_f32_e32 v171, v123, v3
	v_fmac_f32_e32 v171, v124, v4
	v_fmac_f32_e32 v171, v125, v5
	v_fmac_f32_e32 v171, v126, v6
	v_fmac_f32_e32 v171, v127, v7
	global_load_dwordx4 v[120:123], v247, s[4:5]
	global_load_dwordx4 v[124:127], v247, s[4:5] offset:16
	s_waitcnt vmcnt(30)
	v_mul_f32_e32 v172, v128, v0
	v_fmac_f32_e32 v172, v129, v1
	v_fmac_f32_e32 v172, v130, v2
	v_fmac_f32_e32 v172, v131, v3
	v_fmac_f32_e32 v172, v132, v4
	v_fmac_f32_e32 v172, v133, v5
	v_fmac_f32_e32 v172, v134, v6
	v_fmac_f32_e32 v172, v135, v7
	global_load_dwordx4 v[128:131], v248, s[4:5]
	global_load_dwordx4 v[132:135], v248, s[4:5] offset:16
	s_waitcnt vmcnt(30)
	v_mul_f32_e32 v173, v136, v0
	v_fmac_f32_e32 v173, v137, v1
	v_fmac_f32_e32 v173, v138, v2
	v_fmac_f32_e32 v173, v139, v3
	v_fmac_f32_e32 v173, v140, v4
	v_fmac_f32_e32 v173, v141, v5
	v_fmac_f32_e32 v173, v142, v6
	v_fmac_f32_e32 v173, v143, v7
	global_load_dwordx4 v[136:139], v249, s[4:5]
	global_load_dwordx4 v[140:143], v249, s[4:5] offset:16
	s_waitcnt vmcnt(30)
	v_mul_f32_e32 v174, v144, v0
	v_fmac_f32_e32 v174, v145, v1
	v_fmac_f32_e32 v174, v146, v2
	v_fmac_f32_e32 v174, v147, v3
	v_fmac_f32_e32 v174, v148, v4
	v_fmac_f32_e32 v174, v149, v5
	v_fmac_f32_e32 v174, v150, v6
	v_fmac_f32_e32 v174, v151, v7
	global_load_dwordx4 v[144:147], v250, s[4:5]
	global_load_dwordx4 v[148:151], v250, s[4:5] offset:16
	s_waitcnt vmcnt(30)
	v_mul_f32_e32 v175, v152, v0
	v_fmac_f32_e32 v175, v153, v1
	v_fmac_f32_e32 v175, v154, v2
	v_fmac_f32_e32 v175, v155, v3
	v_fmac_f32_e32 v175, v156, v4
	v_fmac_f32_e32 v175, v157, v5
	v_fmac_f32_e32 v175, v158, v6
	v_fmac_f32_e32 v175, v159, v7
	global_load_dwordx4 v[152:155], v251, s[4:5]
	global_load_dwordx4 v[156:159], v251, s[4:5] offset:16
	v_add_f32_dpp v160, v160, v160 row_ror:8 row_mask:0xf bank_mask:0x3
	v_add_f32_dpp v160, v168, v168 row_ror:8 row_mask:0xf bank_mask:0xc
	v_add_f32_dpp v161, v161, v161 row_ror:8 row_mask:0xf bank_mask:0x3
	v_add_f32_dpp v161, v169, v169 row_ror:8 row_mask:0xf bank_mask:0xc
	v_add_f32_dpp v162, v162, v162 row_ror:8 row_mask:0xf bank_mask:0x3
	v_add_f32_dpp v162, v170, v170 row_ror:8 row_mask:0xf bank_mask:0xc
	v_add_f32_dpp v163, v163, v163 row_ror:8 row_mask:0xf bank_mask:0x3
	v_add_f32_dpp v163, v171, v171 row_ror:8 row_mask:0xf bank_mask:0xc
	v_add_f32_dpp v164, v164, v164 row_ror:8 row_mask:0xf bank_mask:0x3
	v_add_f32_dpp v164, v172, v172 row_ror:8 row_mask:0xf bank_mask:0xc
	v_add_f32_dpp v165, v165, v165 row_ror:8 row_mask:0xf bank_mask:0x3
	v_add_f32_dpp v165, v173, v173 row_ror:8 row_mask:0xf bank_mask:0xc
	v_add_f32_dpp v166, v166, v166 row_ror:8 row_mask:0xf bank_mask:0x3
	v_add_f32_dpp v166, v174, v174 row_ror:8 row_mask:0xf bank_mask:0xc
	v_add_f32_dpp v167, v167, v167 row_ror:8 row_mask:0xf bank_mask:0x3
	v_add_f32_dpp v167, v175, v175 row_ror:8 row_mask:0xf bank_mask:0xc
	v_add_f32_dpp v160, v160, v160 row_shl:4 row_mask:0xf bank_mask:0x5
	v_add_f32_dpp v160, v164, v164 row_shr:4 row_mask:0xf bank_mask:0xa
	v_add_f32_dpp v161, v161, v161 row_shl:4 row_mask:0xf bank_mask:0x5
	v_add_f32_dpp v161, v165, v165 row_shr:4 row_mask:0xf bank_mask:0xa
	v_add_f32_dpp v162, v162, v162 row_shl:4 row_mask:0xf bank_mask:0x5
	v_add_f32_dpp v162, v166, v166 row_shr:4 row_mask:0xf bank_mask:0xa
	v_add_f32_dpp v163, v163, v163 row_shl:4 row_mask:0xf bank_mask:0x5
	v_add_f32_dpp v163, v167, v167 row_shr:4 row_mask:0xf bank_mask:0xa
	v_and_b32_e32 v176, 2, v18
	v_cmp_ne_u32_e32 vcc, 0, v176
	v_add_f32_dpp v230, v160, v160 quad_perm:[2,3,0,1] row_mask:0xf bank_mask:0xf
	v_add_f32_dpp v231, v162, v162 quad_perm:[2,3,0,1] row_mask:0xf bank_mask:0xf
	v_add_f32_dpp v232, v161, v161 quad_perm:[2,3,0,1] row_mask:0xf bank_mask:0xf
	v_add_f32_dpp v233, v163, v163 quad_perm:[2,3,0,1] row_mask:0xf bank_mask:0xf
	v_cndmask_b32_e32 v230, v230, v231, vcc
	v_cndmask_b32_e32 v232, v232, v233, vcc
	v_and_b32_e32 v176, 1, v18
	v_cmp_ne_u32_e32 vcc, 0, v176
	v_add_f32_dpp v231, v230, v230 quad_perm:[1,0,3,2] row_mask:0xf bank_mask:0xf
	v_add_f32_dpp v233, v232, v232 quad_perm:[1,0,3,2] row_mask:0xf bank_mask:0xf
	s_nop 1
	v_cndmask_b32_e32 v241, v231, v233, vcc
	s_nop 1
	v_max_f32_dpp v242, v241, v241 row_ror:8 row_mask:0xf bank_mask:0xf
	s_nop 1
	v_max_f32_dpp v242, v242, v242 row_ror:4 row_mask:0xf bank_mask:0xf
	s_nop 1
	v_max_f32_dpp v242, v242, v242 row_ror:2 row_mask:0xf bank_mask:0xf
	s_nop 1
	v_max_f32_dpp v242, v242, v242 row_ror:1 row_mask:0xf bank_mask:0xf
	ds_bpermute_b32 v234, v238, v242
	s_waitcnt lgkmcnt(0)
	v_max_f32_e32 v242, v242, v234
	ds_bpermute_b32 v234, v239, v242
	s_waitcnt lgkmcnt(0)
	v_max_f32_e32 v242, v242, v234
	v_max_f32_e32 v242, v16, v242
	v_sub_f32_e32 v243, v16, v242
	v_sub_f32_e32 v240, v241, v242
	v_mul_f32_e32 v243, 0x3fb8aa3b, v243
	v_mul_f32_e32 v240, 0x3fb8aa3b, v240
	v_exp_f32_e32 v243, v243
	v_exp_f32_e32 v240, v240
	v_mov_b32_e32 v16, v242
	s_nop 0
	s_nop 1
	v_add_f32_dpp v235, v240, v240 row_ror:8 row_mask:0xf bank_mask:0xf
	s_nop 1
	v_add_f32_dpp v235, v235, v235 row_ror:4 row_mask:0xf bank_mask:0xf
	s_nop 1
	v_add_f32_dpp v235, v235, v235 row_ror:2 row_mask:0xf bank_mask:0xf
	s_nop 1
	v_add_f32_dpp v235, v235, v235 row_ror:1 row_mask:0xf bank_mask:0xf
	ds_bpermute_b32 v234, v238, v235
	s_waitcnt lgkmcnt(0)
	v_add_f32_e32 v235, v235, v234
	ds_bpermute_b32 v234, v239, v235
	s_waitcnt lgkmcnt(0)
	v_add_f32_e32 v235, v235, v234
	v_fma_f32 v17, v17, v243, v235
	v_mul_f32_e32 v8, v8, v243
	v_mul_f32_e32 v9, v9, v243
	v_mul_f32_e32 v10, v10, v243
	v_mul_f32_e32 v11, v11, v243
	v_mul_f32_e32 v12, v12, v243
	v_mul_f32_e32 v13, v13, v243
	v_mul_f32_e32 v14, v14, v243
	v_mul_f32_e32 v15, v15, v243
	s_waitcnt vmcnt(30)
	v_fmac_f32_dpp v8, v240, v32 row_newbcast:0 row_mask:0xf bank_mask:0xf
	v_fmac_f32_dpp v9, v240, v33 row_newbcast:0 row_mask:0xf bank_mask:0xf
	v_fmac_f32_dpp v10, v240, v34 row_newbcast:0 row_mask:0xf bank_mask:0xf
	v_fmac_f32_dpp v11, v240, v35 row_newbcast:0 row_mask:0xf bank_mask:0xf
	v_fmac_f32_dpp v12, v240, v36 row_newbcast:0 row_mask:0xf bank_mask:0xf
	v_fmac_f32_dpp v13, v240, v37 row_newbcast:0 row_mask:0xf bank_mask:0xf
	v_fmac_f32_dpp v14, v240, v38 row_newbcast:0 row_mask:0xf bank_mask:0xf
	v_fmac_f32_dpp v15, v240, v39 row_newbcast:0 row_mask:0xf bank_mask:0xf
	s_waitcnt vmcnt(28)
	v_fmac_f32_dpp v8, v240, v40 row_newbcast:1 row_mask:0xf bank_mask:0xf
	v_fmac_f32_dpp v9, v240, v41 row_newbcast:1 row_mask:0xf bank_mask:0xf
	v_fmac_f32_dpp v10, v240, v42 row_newbcast:1 row_mask:0xf bank_mask:0xf
	v_fmac_f32_dpp v11, v240, v43 row_newbcast:1 row_mask:0xf bank_mask:0xf
	v_fmac_f32_dpp v12, v240, v44 row_newbcast:1 row_mask:0xf bank_mask:0xf
	v_fmac_f32_dpp v13, v240, v45 row_newbcast:1 row_mask:0xf bank_mask:0xf
	v_fmac_f32_dpp v14, v240, v46 row_newbcast:1 row_mask:0xf bank_mask:0xf
	v_fmac_f32_dpp v15, v240, v47 row_newbcast:1 row_mask:0xf bank_mask:0xf
	s_waitcnt vmcnt(26)
	v_fmac_f32_dpp v8, v240, v48 row_newbcast:2 row_mask:0xf bank_mask:0xf
	v_fmac_f32_dpp v9, v240, v49 row_newbcast:2 row_mask:0xf bank_mask:0xf
	v_fmac_f32_dpp v10, v240, v50 row_newbcast:2 row_mask:0xf bank_mask:0xf
	v_fmac_f32_dpp v11, v240, v51 row_newbcast:2 row_mask:0xf bank_mask:0xf
	v_fmac_f32_dpp v12, v240, v52 row_newbcast:2 row_mask:0xf bank_mask:0xf
	v_fmac_f32_dpp v13, v240, v53 row_newbcast:2 row_mask:0xf bank_mask:0xf
	v_fmac_f32_dpp v14, v240, v54 row_newbcast:2 row_mask:0xf bank_mask:0xf
	v_fmac_f32_dpp v15, v240, v55 row_newbcast:2 row_mask:0xf bank_mask:0xf
	s_waitcnt vmcnt(24)
	v_fmac_f32_dpp v8, v240, v56 row_newbcast:3 row_mask:0xf bank_mask:0xf
	v_fmac_f32_dpp v9, v240, v57 row_newbcast:3 row_mask:0xf bank_mask:0xf
	v_fmac_f32_dpp v10, v240, v58 row_newbcast:3 row_mask:0xf bank_mask:0xf
	v_fmac_f32_dpp v11, v240, v59 row_newbcast:3 row_mask:0xf bank_mask:0xf
	v_fmac_f32_dpp v12, v240, v60 row_newbcast:3 row_mask:0xf bank_mask:0xf
	v_fmac_f32_dpp v13, v240, v61 row_newbcast:3 row_mask:0xf bank_mask:0xf
	v_fmac_f32_dpp v14, v240, v62 row_newbcast:3 row_mask:0xf bank_mask:0xf
	v_fmac_f32_dpp v15, v240, v63 row_newbcast:3 row_mask:0xf bank_mask:0xf
	s_waitcnt vmcnt(22)
	v_fmac_f32_dpp v8, v240, v64 row_newbcast:4 row_mask:0xf bank_mask:0xf
	v_fmac_f32_dpp v9, v240, v65 row_newbcast:4 row_mask:0xf bank_mask:0xf
	v_fmac_f32_dpp v10, v240, v66 row_newbcast:4 row_mask:0xf bank_mask:0xf
	v_fmac_f32_dpp v11, v240, v67 row_newbcast:4 row_mask:0xf bank_mask:0xf
	v_fmac_f32_dpp v12, v240, v68 row_newbcast:4 row_mask:0xf bank_mask:0xf
	v_fmac_f32_dpp v13, v240, v69 row_newbcast:4 row_mask:0xf bank_mask:0xf
	v_fmac_f32_dpp v14, v240, v70 row_newbcast:4 row_mask:0xf bank_mask:0xf
	v_fmac_f32_dpp v15, v240, v71 row_newbcast:4 row_mask:0xf bank_mask:0xf
	s_waitcnt vmcnt(20)
	v_fmac_f32_dpp v8, v240, v72 row_newbcast:5 row_mask:0xf bank_mask:0xf
	v_fmac_f32_dpp v9, v240, v73 row_newbcast:5 row_mask:0xf bank_mask:0xf
	v_fmac_f32_dpp v10, v240, v74 row_newbcast:5 row_mask:0xf bank_mask:0xf
	v_fmac_f32_dpp v11, v240, v75 row_newbcast:5 row_mask:0xf bank_mask:0xf
	v_fmac_f32_dpp v12, v240, v76 row_newbcast:5 row_mask:0xf bank_mask:0xf
	v_fmac_f32_dpp v13, v240, v77 row_newbcast:5 row_mask:0xf bank_mask:0xf
	v_fmac_f32_dpp v14, v240, v78 row_newbcast:5 row_mask:0xf bank_mask:0xf
	v_fmac_f32_dpp v15, v240, v79 row_newbcast:5 row_mask:0xf bank_mask:0xf
	s_waitcnt vmcnt(18)
	v_fmac_f32_dpp v8, v240, v80 row_newbcast:6 row_mask:0xf bank_mask:0xf
	v_fmac_f32_dpp v9, v240, v81 row_newbcast:6 row_mask:0xf bank_mask:0xf
	v_fmac_f32_dpp v10, v240, v82 row_newbcast:6 row_mask:0xf bank_mask:0xf
	v_fmac_f32_dpp v11, v240, v83 row_newbcast:6 row_mask:0xf bank_mask:0xf
	v_fmac_f32_dpp v12, v240, v84 row_newbcast:6 row_mask:0xf bank_mask:0xf
	v_fmac_f32_dpp v13, v240, v85 row_newbcast:6 row_mask:0xf bank_mask:0xf
	v_fmac_f32_dpp v14, v240, v86 row_newbcast:6 row_mask:0xf bank_mask:0xf
	v_fmac_f32_dpp v15, v240, v87 row_newbcast:6 row_mask:0xf bank_mask:0xf
	s_waitcnt vmcnt(16)
	v_fmac_f32_dpp v8, v240, v88 row_newbcast:7 row_mask:0xf bank_mask:0xf
	v_fmac_f32_dpp v9, v240, v89 row_newbcast:7 row_mask:0xf bank_mask:0xf
	v_fmac_f32_dpp v10, v240, v90 row_newbcast:7 row_mask:0xf bank_mask:0xf
	v_fmac_f32_dpp v11, v240, v91 row_newbcast:7 row_mask:0xf bank_mask:0xf
	v_fmac_f32_dpp v12, v240, v92 row_newbcast:7 row_mask:0xf bank_mask:0xf
	v_fmac_f32_dpp v13, v240, v93 row_newbcast:7 row_mask:0xf bank_mask:0xf
	v_fmac_f32_dpp v14, v240, v94 row_newbcast:7 row_mask:0xf bank_mask:0xf
	v_fmac_f32_dpp v15, v240, v95 row_newbcast:7 row_mask:0xf bank_mask:0xf
	s_waitcnt vmcnt(14)
	v_fmac_f32_dpp v8, v240, v96 row_newbcast:8 row_mask:0xf bank_mask:0xf
	v_fmac_f32_dpp v9, v240, v97 row_newbcast:8 row_mask:0xf bank_mask:0xf
	v_fmac_f32_dpp v10, v240, v98 row_newbcast:8 row_mask:0xf bank_mask:0xf
	v_fmac_f32_dpp v11, v240, v99 row_newbcast:8 row_mask:0xf bank_mask:0xf
	v_fmac_f32_dpp v12, v240, v100 row_newbcast:8 row_mask:0xf bank_mask:0xf
	v_fmac_f32_dpp v13, v240, v101 row_newbcast:8 row_mask:0xf bank_mask:0xf
	v_fmac_f32_dpp v14, v240, v102 row_newbcast:8 row_mask:0xf bank_mask:0xf
	v_fmac_f32_dpp v15, v240, v103 row_newbcast:8 row_mask:0xf bank_mask:0xf
	s_waitcnt vmcnt(12)
	v_fmac_f32_dpp v8, v240, v104 row_newbcast:9 row_mask:0xf bank_mask:0xf
	v_fmac_f32_dpp v9, v240, v105 row_newbcast:9 row_mask:0xf bank_mask:0xf
	v_fmac_f32_dpp v10, v240, v106 row_newbcast:9 row_mask:0xf bank_mask:0xf
	v_fmac_f32_dpp v11, v240, v107 row_newbcast:9 row_mask:0xf bank_mask:0xf
	v_fmac_f32_dpp v12, v240, v108 row_newbcast:9 row_mask:0xf bank_mask:0xf
	v_fmac_f32_dpp v13, v240, v109 row_newbcast:9 row_mask:0xf bank_mask:0xf
	v_fmac_f32_dpp v14, v240, v110 row_newbcast:9 row_mask:0xf bank_mask:0xf
	v_fmac_f32_dpp v15, v240, v111 row_newbcast:9 row_mask:0xf bank_mask:0xf
	s_waitcnt vmcnt(10)
	v_fmac_f32_dpp v8, v240, v112 row_newbcast:10 row_mask:0xf bank_mask:0xf
	v_fmac_f32_dpp v9, v240, v113 row_newbcast:10 row_mask:0xf bank_mask:0xf
	v_fmac_f32_dpp v10, v240, v114 row_newbcast:10 row_mask:0xf bank_mask:0xf
	v_fmac_f32_dpp v11, v240, v115 row_newbcast:10 row_mask:0xf bank_mask:0xf
	v_fmac_f32_dpp v12, v240, v116 row_newbcast:10 row_mask:0xf bank_mask:0xf
	v_fmac_f32_dpp v13, v240, v117 row_newbcast:10 row_mask:0xf bank_mask:0xf
	v_fmac_f32_dpp v14, v240, v118 row_newbcast:10 row_mask:0xf bank_mask:0xf
	v_fmac_f32_dpp v15, v240, v119 row_newbcast:10 row_mask:0xf bank_mask:0xf
	s_waitcnt vmcnt(8)
	v_fmac_f32_dpp v8, v240, v120 row_newbcast:11 row_mask:0xf bank_mask:0xf
	v_fmac_f32_dpp v9, v240, v121 row_newbcast:11 row_mask:0xf bank_mask:0xf
	v_fmac_f32_dpp v10, v240, v122 row_newbcast:11 row_mask:0xf bank_mask:0xf
	v_fmac_f32_dpp v11, v240, v123 row_newbcast:11 row_mask:0xf bank_mask:0xf
	v_fmac_f32_dpp v12, v240, v124 row_newbcast:11 row_mask:0xf bank_mask:0xf
	v_fmac_f32_dpp v13, v240, v125 row_newbcast:11 row_mask:0xf bank_mask:0xf
	v_fmac_f32_dpp v14, v240, v126 row_newbcast:11 row_mask:0xf bank_mask:0xf
	v_fmac_f32_dpp v15, v240, v127 row_newbcast:11 row_mask:0xf bank_mask:0xf
	s_waitcnt vmcnt(6)
	v_fmac_f32_dpp v8, v240, v128 row_newbcast:12 row_mask:0xf bank_mask:0xf
	v_fmac_f32_dpp v9, v240, v129 row_newbcast:12 row_mask:0xf bank_mask:0xf
	v_fmac_f32_dpp v10, v240, v130 row_newbcast:12 row_mask:0xf bank_mask:0xf
	v_fmac_f32_dpp v11, v240, v131 row_newbcast:12 row_mask:0xf bank_mask:0xf
	v_fmac_f32_dpp v12, v240, v132 row_newbcast:12 row_mask:0xf bank_mask:0xf
	v_fmac_f32_dpp v13, v240, v133 row_newbcast:12 row_mask:0xf bank_mask:0xf
	v_fmac_f32_dpp v14, v240, v134 row_newbcast:12 row_mask:0xf bank_mask:0xf
	v_fmac_f32_dpp v15, v240, v135 row_newbcast:12 row_mask:0xf bank_mask:0xf
	s_waitcnt vmcnt(4)
	v_fmac_f32_dpp v8, v240, v136 row_newbcast:13 row_mask:0xf bank_mask:0xf
	v_fmac_f32_dpp v9, v240, v137 row_newbcast:13 row_mask:0xf bank_mask:0xf
	v_fmac_f32_dpp v10, v240, v138 row_newbcast:13 row_mask:0xf bank_mask:0xf
	v_fmac_f32_dpp v11, v240, v139 row_newbcast:13 row_mask:0xf bank_mask:0xf
	v_fmac_f32_dpp v12, v240, v140 row_newbcast:13 row_mask:0xf bank_mask:0xf
	v_fmac_f32_dpp v13, v240, v141 row_newbcast:13 row_mask:0xf bank_mask:0xf
	v_fmac_f32_dpp v14, v240, v142 row_newbcast:13 row_mask:0xf bank_mask:0xf
	v_fmac_f32_dpp v15, v240, v143 row_newbcast:13 row_mask:0xf bank_mask:0xf
	s_waitcnt vmcnt(2)
	v_fmac_f32_dpp v8, v240, v144 row_newbcast:14 row_mask:0xf bank_mask:0xf
	v_fmac_f32_dpp v9, v240, v145 row_newbcast:14 row_mask:0xf bank_mask:0xf
	v_fmac_f32_dpp v10, v240, v146 row_newbcast:14 row_mask:0xf bank_mask:0xf
	v_fmac_f32_dpp v11, v240, v147 row_newbcast:14 row_mask:0xf bank_mask:0xf
	v_fmac_f32_dpp v12, v240, v148 row_newbcast:14 row_mask:0xf bank_mask:0xf
	v_fmac_f32_dpp v13, v240, v149 row_newbcast:14 row_mask:0xf bank_mask:0xf
	v_fmac_f32_dpp v14, v240, v150 row_newbcast:14 row_mask:0xf bank_mask:0xf
	v_fmac_f32_dpp v15, v240, v151 row_newbcast:14 row_mask:0xf bank_mask:0xf
	s_waitcnt vmcnt(0)
	v_fmac_f32_dpp v8, v240, v152 row_newbcast:15 row_mask:0xf bank_mask:0xf
	v_fmac_f32_dpp v9, v240, v153 row_newbcast:15 row_mask:0xf bank_mask:0xf
	v_fmac_f32_dpp v10, v240, v154 row_newbcast:15 row_mask:0xf bank_mask:0xf
	v_fmac_f32_dpp v11, v240, v155 row_newbcast:15 row_mask:0xf bank_mask:0xf
	v_fmac_f32_dpp v12, v240, v156 row_newbcast:15 row_mask:0xf bank_mask:0xf
	v_fmac_f32_dpp v13, v240, v157 row_newbcast:15 row_mask:0xf bank_mask:0xf
	v_fmac_f32_dpp v14, v240, v158 row_newbcast:15 row_mask:0xf bank_mask:0xf
	v_fmac_f32_dpp v15, v240, v159 row_newbcast:15 row_mask:0xf bank_mask:0xf
	s_lshl_b32 s29, s10, 12
	v_lshlrev_b32_e32 v236, 5, v22
	v_add_u32_e32 v236, s29, v236
	global_load_dwordx4 v[32:35], v236, s[20:21]
	global_load_dwordx4 v[36:39], v236, s[20:21] offset:16
	global_load_dwordx4 v[40:43], v236, s[22:23]
	global_load_dwordx4 v[44:47], v236, s[22:23] offset:16
	ds_bpermute_b32 v160, v238, v8
	ds_bpermute_b32 v161, v238, v9
	ds_bpermute_b32 v162, v238, v10
	ds_bpermute_b32 v163, v238, v11
	ds_bpermute_b32 v164, v238, v12
	ds_bpermute_b32 v165, v238, v13
	ds_bpermute_b32 v166, v238, v14
	ds_bpermute_b32 v167, v238, v15
	s_waitcnt lgkmcnt(0)
	v_add_f32_e32 v8, v8, v160
	v_add_f32_e32 v9, v9, v161
	v_add_f32_e32 v10, v10, v162
	v_add_f32_e32 v11, v11, v163
	v_add_f32_e32 v12, v12, v164
	v_add_f32_e32 v13, v13, v165
	v_add_f32_e32 v14, v14, v166
	v_add_f32_e32 v15, v15, v167
	ds_bpermute_b32 v160, v239, v8
	ds_bpermute_b32 v161, v239, v9
	ds_bpermute_b32 v162, v239, v10
	ds_bpermute_b32 v163, v239, v11
	ds_bpermute_b32 v164, v239, v12
	ds_bpermute_b32 v165, v239, v13
	ds_bpermute_b32 v166, v239, v14
	ds_bpermute_b32 v167, v239, v15
	s_waitcnt lgkmcnt(0)
	v_add_f32_e32 v8, v8, v160
	v_add_f32_e32 v9, v9, v161
	v_add_f32_e32 v10, v10, v162
	v_add_f32_e32 v11, v11, v163
	v_add_f32_e32 v12, v12, v164
	v_add_f32_e32 v13, v13, v165
	v_add_f32_e32 v14, v14, v166
	v_add_f32_e32 v15, v15, v167
	s_waitcnt vmcnt(0)
	s_cmp_lg_u32 s11, 0
	s_cbranch_scc1 .Lsd_noself13
	v_mul_f32_e32 v241, v32, v0
	v_fmac_f32_e32 v241, v33, v1
	v_fmac_f32_e32 v241, v34, v2
	v_fmac_f32_e32 v241, v35, v3
	v_fmac_f32_e32 v241, v36, v4
	v_fmac_f32_e32 v241, v37, v5
	v_fmac_f32_e32 v241, v38, v6
	v_fmac_f32_e32 v241, v39, v7
	s_nop 1
	v_add_f32_dpp v241, v241, v241 row_ror:8 row_mask:0xf bank_mask:0xf
	s_nop 1
	v_add_f32_dpp v241, v241, v241 row_ror:4 row_mask:0xf bank_mask:0xf
	s_nop 1
	v_add_f32_dpp v241, v241, v241 row_ror:2 row_mask:0xf bank_mask:0xf
	s_nop 1
	v_add_f32_dpp v241, v241, v241 row_ror:1 row_mask:0xf bank_mask:0xf
	v_max_f32_e32 v242, v16, v241
	v_sub_f32_e32 v243, v16, v242
	v_sub_f32_e32 v240, v241, v242
	v_mul_f32_e32 v243, 0x3fb8aa3b, v243
	v_mul_f32_e32 v240, 0x3fb8aa3b, v240
	v_exp_f32_e32 v243, v243
	v_exp_f32_e32 v240, v240
	v_mov_b32_e32 v16, v242
	v_mul_f32_e32 v240, 0x40400000, v240
	v_fma_f32 v17, v17, v243, v240
	v_mul_f32_e32 v8, v8, v243
	v_fmac_f32_e32 v8, v240, v40
	v_mul_f32_e32 v9, v9, v243
	v_fmac_f32_e32 v9, v240, v41
	v_mul_f32_e32 v10, v10, v243
	v_fmac_f32_e32 v10, v240, v42
	v_mul_f32_e32 v11, v11, v243
	v_fmac_f32_e32 v11, v240, v43
	v_mul_f32_e32 v12, v12, v243
	v_fmac_f32_e32 v12, v240, v44
	v_mul_f32_e32 v13, v13, v243
	v_fmac_f32_e32 v13, v240, v45
	v_mul_f32_e32 v14, v14, v243
	v_fmac_f32_e32 v14, v240, v46
	v_mul_f32_e32 v15, v15, v243
	v_fmac_f32_e32 v15, v240, v47
.Lsd_noself13:
	v_add_u32_e32 v230, s8, v20
	v_or_b32_e32 v230, 0x2000, v230
	v_mul_u32_u24_e32 v231, 0x5800, v230
	v_lshl_add_u32 v232, v22, 4, v231
	v_add_u32_e32 v232, s9, v232
	v_add_u32_e32 v232, 0x4800, v232
	v_mov_b32_e32 v233, 0
	v_lshl_add_u64 v[244:245], s[0:1], 0, v[232:233]
	v_mul_u32_u24_e32 v231, 0x1c00, v230
	v_lshl_add_u32 v232, v22, 4, v231
	v_add_u32_e32 v232, s9, v232
	v_add_u32_e32 v232, 0x1d301000, v232
	v_lshl_add_u64 v[246:247], s[96:97], 0, v[232:233]
	v_lshl_or_b32 v176, v20, 4, v18
	v_mul_u32_u24_e32 v176, 48, v176
	v_cmp_gt_u32_e32 vcc, 16, v18
	v_cmp_eq_u32_e64 s[6:7], 1, v21
	s_and_b64 s[6:7], s[6:7], vcc
	s_and_saveexec_b64 s[6:7], s[6:7]
	v_mov_b32_e32 v160, v16
	v_mov_b32_e32 v161, v17
	v_mov_b32_e32 v162, v8
	v_mov_b32_e32 v163, v9
	ds_write_b128 v176, v[160:163] offset:4096
	ds_write_b128 v176, v[10:13] offset:4112
	ds_write_b64 v176, v[14:15] offset:4128
	s_or_b64 exec, exec, s[6:7]
	s_waitcnt lgkmcnt(0)
	s_barrier
	v_cmp_gt_u32_e32 vcc, 16, v18
	v_cmp_eq_u32_e64 s[6:7], 0, v21
	s_and_b64 s[6:7], s[6:7], vcc
	s_and_saveexec_b64 s[6:7], s[6:7]
	s_cbranch_execz .Lsd_mdone14
	global_load_dwordx4 v[172:175], v[244:245], off
	ds_read_b128 v[160:163], v176 offset:4096
	ds_read_b128 v[164:167], v176 offset:4112
	ds_read_b64 v[168:169], v176 offset:4128
	s_waitcnt lgkmcnt(0)
	v_max_f32_e32 v230, v16, v160
	v_sub_f32_e32 v231, v16, v230
	v_sub_f32_e32 v232, v160, v230
	v_mul_f32_e32 v231, 0x3fb8aa3b, v231
	v_mul_f32_e32 v232, 0x3fb8aa3b, v232
	v_exp_f32_e32 v231, v231
	v_exp_f32_e32 v232, v232
	s_nop 0
	v_mul_f32_e32 v233, v232, v161
	v_fmac_f32_e32 v233, v231, v17
	v_div_scale_f32 v234, s[8:9], v233, v233, 1.0
	v_rcp_f32_e32 v235, v234
	s_nop 0
	v_fma_f32 v236, -v234, v235, 1.0
	v_fmac_f32_e32 v235, v236, v235
	v_div_scale_f32 v236, vcc, 1.0, v233, 1.0
	v_mul_f32_e32 v237, v236, v235
	v_fma_f32 v176, -v234, v237, v236
	v_fmac_f32_e32 v237, v176, v235
	v_fma_f32 v234, -v234, v237, v236
	s_nop 0
	v_div_fmas_f32 v234, v234, v235, v237
	v_div_fixup_f32 v233, v234, v233, 1.0
	v_mul_f32_e32 v162, v232, v162
	v_fmac_f32_e32 v162, v231, v8
	v_mul_f32_e32 v162, v162, v233
	v_mul_f32_e32 v163, v232, v163
	v_fmac_f32_e32 v163, v231, v9
	v_mul_f32_e32 v163, v163, v233
	v_mul_f32_e32 v164, v232, v164
	v_fmac_f32_e32 v164, v231, v10
	v_mul_f32_e32 v164, v164, v233
	v_mul_f32_e32 v165, v232, v165
	v_fmac_f32_e32 v165, v231, v11
	v_mul_f32_e32 v165, v165, v233
	v_mul_f32_e32 v166, v232, v166
	v_fmac_f32_e32 v166, v231, v12
	v_mul_f32_e32 v166, v166, v233
	v_mul_f32_e32 v167, v232, v167
	v_fmac_f32_e32 v167, v231, v13
	v_mul_f32_e32 v167, v167, v233
	v_mul_f32_e32 v168, v232, v168
	v_fmac_f32_e32 v168, v231, v14
	v_mul_f32_e32 v168, v168, v233
	v_mul_f32_e32 v169, v232, v169
	v_fmac_f32_e32 v169, v231, v15
	v_mul_f32_e32 v169, v169, v233
	s_waitcnt vmcnt(0)
	v_lshlrev_b32_e32 v230, 16, v172
	v_and_b32_e32 v231, 0xffff0000, v172
	v_mul_f32_e32 v236, 0xbfb8aa3b, v230
	v_mul_f32_e32 v237, 0xbfb8aa3b, v231
	v_exp_f32_e32 v236, v236
	v_exp_f32_e32 v237, v237
	s_nop 0
	v_add_f32_e32 v236, 1.0, v236
	v_add_f32_e32 v237, 1.0, v237
	v_rcp_f32_e32 v236, v236
	v_rcp_f32_e32 v237, v237
	s_nop 0
	v_mul_f32_e32 v230, v230, v236
	v_mul_f32_e32 v231, v231, v237
	v_mul_f32_e32 v162, v162, v230
	v_mul_f32_e32 v163, v163, v231
	v_cvt_pk_bf16_f32 v172, v162, v163
	v_lshlrev_b32_e32 v230, 16, v173
	v_and_b32_e32 v231, 0xffff0000, v173
	v_mul_f32_e32 v236, 0xbfb8aa3b, v230
	v_mul_f32_e32 v237, 0xbfb8aa3b, v231
	v_exp_f32_e32 v236, v236
	v_exp_f32_e32 v237, v237
	s_nop 0
	v_add_f32_e32 v236, 1.0, v236
	v_add_f32_e32 v237, 1.0, v237
	v_rcp_f32_e32 v236, v236
	v_rcp_f32_e32 v237, v237
	s_nop 0
	v_mul_f32_e32 v230, v230, v236
	v_mul_f32_e32 v231, v231, v237
	v_mul_f32_e32 v164, v164, v230
	v_mul_f32_e32 v165, v165, v231
	v_cvt_pk_bf16_f32 v173, v164, v165
	v_lshlrev_b32_e32 v230, 16, v174
	v_and_b32_e32 v231, 0xffff0000, v174
	v_mul_f32_e32 v236, 0xbfb8aa3b, v230
	v_mul_f32_e32 v237, 0xbfb8aa3b, v231
	v_exp_f32_e32 v236, v236
	v_exp_f32_e32 v237, v237
	s_nop 0
	v_add_f32_e32 v236, 1.0, v236
	v_add_f32_e32 v237, 1.0, v237
	v_rcp_f32_e32 v236, v236
	v_rcp_f32_e32 v237, v237
	s_nop 0
	v_mul_f32_e32 v230, v230, v236
	v_mul_f32_e32 v231, v231, v237
	v_mul_f32_e32 v166, v166, v230
	v_mul_f32_e32 v167, v167, v231
	v_cvt_pk_bf16_f32 v174, v166, v167
	v_lshlrev_b32_e32 v230, 16, v175
	v_and_b32_e32 v231, 0xffff0000, v175
	v_mul_f32_e32 v236, 0xbfb8aa3b, v230
	v_mul_f32_e32 v237, 0xbfb8aa3b, v231
	v_exp_f32_e32 v236, v236
	v_exp_f32_e32 v237, v237
	s_nop 0
	v_add_f32_e32 v236, 1.0, v236
	v_add_f32_e32 v237, 1.0, v237
	v_rcp_f32_e32 v236, v236
	v_rcp_f32_e32 v237, v237
	s_nop 0
	v_mul_f32_e32 v230, v230, v236
	v_mul_f32_e32 v231, v231, v237
	v_mul_f32_e32 v168, v168, v230
	v_mul_f32_e32 v169, v169, v231
	v_cvt_pk_bf16_f32 v175, v168, v169
	global_store_dwordx4 v[246:247], v[172:175], off
.Lsd_mdone14:
	s_or_b64 exec, exec, s[6:7]
	s_barrier
